# v_full6 + GEMM phases: one static priority raise for the wave half wr==0 for the whole phase, the K-loops' per-segment s_setprio flips deleted
# speedup vs baseline: 1.0071x; 1.0071x over previous
.LBB0_284:
	s_or_b64 exec, exec, s[0:1]
	s_waitcnt lgkmcnt(0)
	s_barrier
	s_cselect_b32 s5, 1, 0
	v_readfirstlane_b32 s6, v180
	s_nop 1
	s_bitcmp1_b32 s6, 8
	s_cbranch_scc1 .Lmy_prio_0
	s_setprio 1
.Lmy_prio_0:
	s_cmp_lg_u32 s5, 0

.LBB0_292:
	s_add_i32 s9, 0, 0x10000
	v_add_u32_e32 v143, s9, v142
	s_add_i32 s12, 0, 0x14000
	ds_read_b128 v[148:151], v143
	ds_read_b128 v[164:167], v143 offset:1024
	ds_read_b128 v[168:171], v143 offset:2048
	ds_read_b128 v[172:175], v143 offset:3072
	v_add_u32_e32 v143, s12, v142
	ds_read_b128 v[176:179], v143
	ds_read_b128 v[192:195], v143 offset:1024
	ds_read_b128 v[196:199], v143 offset:2048
	ds_read_b128 v[200:203], v143 offset:3072
	v_lshl_add_u64 v[144:145], s[78:79], 0, v[138:139]
	s_add_i32 s8, s30, 0xc000
	v_lshl_add_u64 v[152:153], v[144:145], 0, s[50:51]
	s_mov_b32 m0, s8
	ds_read_b128 v[204:207], v112
	ds_read_b128 v[208:211], v112 offset:1024
	ds_read_b128 v[212:215], v112 offset:2048
	ds_read_b128 v[216:219], v112 offset:3072
	ds_read_b128 v[220:223], v112 offset:4096
	ds_read_b128 v[224:227], v112 offset:5120
	ds_read_b128 v[228:231], v112 offset:6144
	ds_read_b128 v[232:235], v112 offset:7168
	global_load_lds_dwordx4 v[152:153], off
	v_lshl_add_u64 v[152:153], s[78:79], 0, v[140:141]
	s_add_i32 s7, s30, 0xe000
	v_lshl_add_u64 v[154:155], v[152:153], 0, s[50:51]
	s_mov_b32 m0, s7
	s_nop 0
	global_load_lds_dwordx4 v[154:155], off
	s_waitcnt vmcnt(8)
	s_waitcnt lgkmcnt(0)
	s_barrier
	s_waitcnt lgkmcnt(0)
	v_mfma_f32_16x16x32_bf16 v[126:129], v[148:151], v[204:207], v[126:129]
	v_mfma_f32_16x16x32_bf16 v[122:125], v[168:171], v[204:207], v[122:125]
	v_mfma_f32_16x16x32_bf16 v[118:121], v[148:151], v[212:215], v[118:121]
	v_mfma_f32_16x16x32_bf16 v[114:117], v[168:171], v[212:215], v[114:117]
	v_mfma_f32_16x16x32_bf16 v[108:111], v[148:151], v[220:223], v[108:111]
	v_mfma_f32_16x16x32_bf16 v[104:107], v[168:171], v[220:223], v[104:107]
	v_mfma_f32_16x16x32_bf16 v[100:103], v[148:151], v[228:231], v[100:103]
	v_mfma_f32_16x16x32_bf16 v[96:99], v[168:171], v[228:231], v[96:99]
	v_mfma_f32_16x16x32_bf16 v[126:129], v[164:167], v[208:211], v[126:129]
	v_mfma_f32_16x16x32_bf16 v[122:125], v[172:175], v[208:211], v[122:125]
	v_mfma_f32_16x16x32_bf16 v[118:121], v[164:167], v[216:219], v[118:121]
	v_mfma_f32_16x16x32_bf16 v[114:117], v[172:175], v[216:219], v[114:117]
	v_mfma_f32_16x16x32_bf16 v[108:111], v[164:167], v[224:227], v[108:111]
	v_mfma_f32_16x16x32_bf16 v[104:107], v[172:175], v[224:227], v[104:107]
	v_mfma_f32_16x16x32_bf16 v[100:103], v[164:167], v[232:235], v[100:103]
	v_mfma_f32_16x16x32_bf16 v[96:99], v[172:175], v[232:235], v[96:99]
	v_mfma_f32_16x16x32_bf16 v[92:95], v[176:179], v[204:207], v[92:95]
	v_mfma_f32_16x16x32_bf16 v[88:91], v[196:199], v[204:207], v[88:91]
	v_mfma_f32_16x16x32_bf16 v[84:87], v[176:179], v[212:215], v[84:87]
	v_mfma_f32_16x16x32_bf16 v[80:83], v[196:199], v[212:215], v[80:83]
	v_mfma_f32_16x16x32_bf16 v[68:71], v[176:179], v[220:223], v[68:71]
	v_mfma_f32_16x16x32_bf16 v[60:63], v[196:199], v[220:223], v[60:63]
	v_mfma_f32_16x16x32_bf16 v[56:59], v[176:179], v[228:231], v[56:59]
	v_mfma_f32_16x16x32_bf16 v[52:55], v[196:199], v[228:231], v[52:55]
	v_mfma_f32_16x16x32_bf16 v[92:95], v[192:195], v[208:211], v[92:95]
	v_mfma_f32_16x16x32_bf16 v[88:91], v[200:203], v[208:211], v[88:91]
	v_mfma_f32_16x16x32_bf16 v[84:87], v[192:195], v[216:219], v[84:87]
	v_mfma_f32_16x16x32_bf16 v[80:83], v[200:203], v[216:219], v[80:83]
	v_mfma_f32_16x16x32_bf16 v[68:71], v[192:195], v[224:227], v[68:71]
	v_mfma_f32_16x16x32_bf16 v[60:63], v[200:203], v[224:227], v[60:63]
	v_mfma_f32_16x16x32_bf16 v[56:59], v[192:195], v[232:235], v[56:59]
	v_mfma_f32_16x16x32_bf16 v[52:55], v[200:203], v[232:235], v[52:55]
	s_barrier
	v_lshl_add_u64 v[154:155], s[78:79], 0, v[134:135]
	s_add_i32 s9, s9, s1
	v_lshl_add_u64 v[236:237], v[154:155], 0, s[52:53]
	s_mov_b32 m0, s9
	ds_read_b128 v[204:207], v112 offset:16384
	ds_read_b128 v[208:211], v112 offset:17408
	ds_read_b128 v[212:215], v112 offset:18432
	ds_read_b128 v[216:219], v112 offset:19456
	ds_read_b128 v[220:223], v112 offset:20480
	ds_read_b128 v[224:227], v112 offset:21504
	ds_read_b128 v[228:231], v112 offset:22528
	ds_read_b128 v[232:235], v112 offset:23552
	global_load_lds_dwordx4 v[236:237], off
	v_lshl_add_u64 v[236:237], s[78:79], 0, v[136:137]
	v_lshl_add_u64 v[238:239], v[236:237], 0, s[52:53]
	s_add_i32 m0, s9, 0x2000
	s_add_i32 s9, s12, s1
	global_load_lds_dwordx4 v[238:239], off
	v_lshl_add_u64 v[238:239], v[154:155], 0, s[54:55]
	s_mov_b32 m0, s9
	s_nop 0
	global_load_lds_dwordx4 v[238:239], off
	v_lshl_add_u64 v[238:239], v[236:237], 0, s[54:55]
	s_add_i32 m0, s9, 0x2000
	s_nop 0
	global_load_lds_dwordx4 v[238:239], off
	v_lshl_add_u64 v[238:239], v[144:145], 0, s[70:71]
	s_mov_b32 m0, s30
	s_nop 0
	global_load_lds_dwordx4 v[238:239], off
	v_lshl_add_u64 v[238:239], v[152:153], 0, s[70:71]
	s_mov_b32 m0, s31
	s_nop 0
	global_load_lds_dwordx4 v[238:239], off
	s_waitcnt vmcnt(8)
	s_waitcnt lgkmcnt(0)
	s_barrier
	s_waitcnt lgkmcnt(0)
	v_mfma_f32_16x16x32_bf16 v[48:51], v[148:151], v[204:207], v[48:51]
	v_mfma_f32_16x16x32_bf16 v[44:47], v[168:171], v[204:207], v[44:47]
	v_mfma_f32_16x16x32_bf16 v[40:43], v[148:151], v[212:215], v[40:43]
	v_mfma_f32_16x16x32_bf16 v[36:39], v[168:171], v[212:215], v[36:39]
	v_mfma_f32_16x16x32_bf16 v[32:35], v[148:151], v[220:223], v[32:35]
	v_mfma_f32_16x16x32_bf16 v[28:31], v[168:171], v[220:223], v[28:31]
	v_mfma_f32_16x16x32_bf16 v[24:27], v[148:151], v[228:231], v[24:27]
	v_mfma_f32_16x16x32_bf16 v[20:23], v[168:171], v[228:231], v[20:23]
	v_mfma_f32_16x16x32_bf16 v[48:51], v[164:167], v[208:211], v[48:51]
	v_mfma_f32_16x16x32_bf16 v[44:47], v[172:175], v[208:211], v[44:47]
	v_mfma_f32_16x16x32_bf16 v[40:43], v[164:167], v[216:219], v[40:43]
	v_mfma_f32_16x16x32_bf16 v[36:39], v[172:175], v[216:219], v[36:39]
	v_mfma_f32_16x16x32_bf16 v[32:35], v[164:167], v[224:227], v[32:35]
	v_mfma_f32_16x16x32_bf16 v[28:31], v[172:175], v[224:227], v[28:31]
	v_mfma_f32_16x16x32_bf16 v[24:27], v[164:167], v[232:235], v[24:27]
	v_mfma_f32_16x16x32_bf16 v[20:23], v[172:175], v[232:235], v[20:23]
	v_mfma_f32_16x16x32_bf16 v[16:19], v[176:179], v[204:207], v[16:19]
	v_mfma_f32_16x16x32_bf16 v[12:15], v[196:199], v[204:207], v[12:15]
	v_mfma_f32_16x16x32_bf16 v[8:11], v[176:179], v[212:215], v[8:11]
	v_mfma_f32_16x16x32_bf16 v[4:7], v[196:199], v[212:215], v[4:7]
	v_mfma_f32_16x16x32_bf16 v[0:3], v[176:179], v[220:223], v[0:3]
	v_mfma_f32_16x16x32_bf16 v[64:67], v[196:199], v[220:223], v[64:67]
	v_mfma_f32_16x16x32_bf16 v[72:75], v[176:179], v[228:231], v[72:75]
	v_mfma_f32_16x16x32_bf16 v[76:79], v[196:199], v[228:231], v[76:79]
	v_mfma_f32_16x16x32_bf16 v[16:19], v[192:195], v[208:211], v[16:19]
	v_mfma_f32_16x16x32_bf16 v[12:15], v[200:203], v[208:211], v[12:15]
	v_mfma_f32_16x16x32_bf16 v[8:11], v[192:195], v[216:219], v[8:11]
	v_mfma_f32_16x16x32_bf16 v[4:7], v[200:203], v[216:219], v[4:7]
	v_mfma_f32_16x16x32_bf16 v[0:3], v[192:195], v[224:227], v[0:3]
	v_mfma_f32_16x16x32_bf16 v[64:67], v[200:203], v[224:227], v[64:67]
	v_mfma_f32_16x16x32_bf16 v[72:75], v[192:195], v[232:235], v[72:75]
	v_mfma_f32_16x16x32_bf16 v[76:79], v[200:203], v[232:235], v[76:79]
	s_barrier
	s_add_i32 s9, 0, 0x18000
	v_add_u32_e32 v143, s9, v142
	s_add_i32 s12, 0, 0x1c000
	ds_read_b128 v[148:151], v143
	ds_read_b128 v[164:167], v143 offset:1024
	ds_read_b128 v[168:171], v143 offset:2048
	ds_read_b128 v[172:175], v143 offset:3072
	v_add_u32_e32 v143, s12, v142
	ds_read_b128 v[176:179], v143
	ds_read_b128 v[192:195], v143 offset:1024
	ds_read_b128 v[196:199], v143 offset:2048
	ds_read_b128 v[200:203], v143 offset:3072
	s_mov_b32 m0, s33
	v_lshl_add_u64 v[238:239], v[144:145], 0, s[56:57]
	ds_read_b128 v[204:207], v112 offset:32768
	ds_read_b128 v[208:211], v112 offset:33792
	ds_read_b128 v[212:215], v112 offset:34816
	ds_read_b128 v[216:219], v112 offset:35840
	ds_read_b128 v[220:223], v112 offset:36864
	ds_read_b128 v[224:227], v112 offset:37888
	ds_read_b128 v[228:231], v112 offset:38912
	ds_read_b128 v[232:235], v112 offset:39936
	global_load_lds_dwordx4 v[238:239], off
	v_lshl_add_u64 v[238:239], v[152:153], 0, s[56:57]
	s_mov_b32 m0, s46
	s_nop 0
	global_load_lds_dwordx4 v[238:239], off
	s_waitcnt vmcnt(8)
	s_waitcnt lgkmcnt(0)
	s_barrier
	s_waitcnt lgkmcnt(0)
	v_mfma_f32_16x16x32_bf16 v[126:129], v[148:151], v[204:207], v[126:129]
	v_mfma_f32_16x16x32_bf16 v[122:125], v[168:171], v[204:207], v[122:125]
	v_mfma_f32_16x16x32_bf16 v[118:121], v[148:151], v[212:215], v[118:121]
	v_mfma_f32_16x16x32_bf16 v[114:117], v[168:171], v[212:215], v[114:117]
	v_mfma_f32_16x16x32_bf16 v[108:111], v[148:151], v[220:223], v[108:111]
	v_mfma_f32_16x16x32_bf16 v[104:107], v[168:171], v[220:223], v[104:107]
	v_mfma_f32_16x16x32_bf16 v[100:103], v[148:151], v[228:231], v[100:103]
	v_mfma_f32_16x16x32_bf16 v[96:99], v[168:171], v[228:231], v[96:99]
	v_mfma_f32_16x16x32_bf16 v[126:129], v[164:167], v[208:211], v[126:129]
	v_mfma_f32_16x16x32_bf16 v[122:125], v[172:175], v[208:211], v[122:125]
	v_mfma_f32_16x16x32_bf16 v[118:121], v[164:167], v[216:219], v[118:121]
	v_mfma_f32_16x16x32_bf16 v[114:117], v[172:175], v[216:219], v[114:117]
	v_mfma_f32_16x16x32_bf16 v[108:111], v[164:167], v[224:227], v[108:111]
	v_mfma_f32_16x16x32_bf16 v[104:107], v[172:175], v[224:227], v[104:107]
	v_mfma_f32_16x16x32_bf16 v[100:103], v[164:167], v[232:235], v[100:103]
	v_mfma_f32_16x16x32_bf16 v[96:99], v[172:175], v[232:235], v[96:99]
	v_mfma_f32_16x16x32_bf16 v[92:95], v[176:179], v[204:207], v[92:95]
	v_mfma_f32_16x16x32_bf16 v[88:91], v[196:199], v[204:207], v[88:91]
	v_mfma_f32_16x16x32_bf16 v[84:87], v[176:179], v[212:215], v[84:87]
	v_mfma_f32_16x16x32_bf16 v[80:83], v[196:199], v[212:215], v[80:83]
	v_mfma_f32_16x16x32_bf16 v[68:71], v[176:179], v[220:223], v[68:71]
	v_mfma_f32_16x16x32_bf16 v[60:63], v[196:199], v[220:223], v[60:63]
	v_mfma_f32_16x16x32_bf16 v[56:59], v[176:179], v[228:231], v[56:59]
	v_mfma_f32_16x16x32_bf16 v[52:55], v[196:199], v[228:231], v[52:55]
	v_mfma_f32_16x16x32_bf16 v[92:95], v[192:195], v[208:211], v[92:95]
	v_mfma_f32_16x16x32_bf16 v[88:91], v[200:203], v[208:211], v[88:91]
	v_mfma_f32_16x16x32_bf16 v[84:87], v[192:195], v[216:219], v[84:87]
	v_mfma_f32_16x16x32_bf16 v[80:83], v[200:203], v[216:219], v[80:83]
	v_mfma_f32_16x16x32_bf16 v[68:71], v[192:195], v[224:227], v[68:71]
	v_mfma_f32_16x16x32_bf16 v[60:63], v[200:203], v[224:227], v[60:63]
	v_mfma_f32_16x16x32_bf16 v[56:59], v[192:195], v[232:235], v[56:59]
	v_mfma_f32_16x16x32_bf16 v[52:55], v[200:203], v[232:235], v[52:55]
	s_barrier
	s_add_i32 s9, s9, s1
	v_lshl_add_u64 v[238:239], v[154:155], 0, s[58:59]
	s_mov_b32 m0, s9
	ds_read_b128 v[204:207], v112 offset:49152
	ds_read_b128 v[208:211], v112 offset:50176
	ds_read_b128 v[212:215], v112 offset:51200
	ds_read_b128 v[216:219], v112 offset:52224
	ds_read_b128 v[220:223], v112 offset:53248
	ds_read_b128 v[224:227], v112 offset:54272
	ds_read_b128 v[228:231], v112 offset:55296
	ds_read_b128 v[232:235], v112 offset:56320
	global_load_lds_dwordx4 v[238:239], off
	v_lshl_add_u64 v[238:239], v[236:237], 0, s[58:59]
	s_add_i32 m0, s9, 0x2000
	s_add_i32 s9, s12, s1
	global_load_lds_dwordx4 v[238:239], off
	v_lshl_add_u64 v[154:155], v[154:155], 0, s[60:61]
	s_mov_b32 m0, s9
	v_lshl_add_u64 v[144:145], v[144:145], 0, s[44:45]
	global_load_lds_dwordx4 v[154:155], off
	v_lshl_add_u64 v[154:155], v[236:237], 0, s[60:61]
	s_add_i32 m0, s9, 0x2000
	s_nop 0
	global_load_lds_dwordx4 v[154:155], off
	s_mov_b32 m0, s47
	s_nop 0
	global_load_lds_dwordx4 v[144:145], off
	v_lshl_add_u64 v[144:145], v[152:153], 0, s[44:45]
	s_mov_b32 m0, s48
	s_nop 0
	global_load_lds_dwordx4 v[144:145], off
	s_waitcnt vmcnt(8)
	s_waitcnt lgkmcnt(0)
	s_barrier
	s_waitcnt lgkmcnt(0)
	v_mfma_f32_16x16x32_bf16 v[48:51], v[148:151], v[204:207], v[48:51]
	v_mfma_f32_16x16x32_bf16 v[44:47], v[168:171], v[204:207], v[44:47]
	v_mfma_f32_16x16x32_bf16 v[40:43], v[148:151], v[212:215], v[40:43]
	v_mfma_f32_16x16x32_bf16 v[36:39], v[168:171], v[212:215], v[36:39]
	v_mfma_f32_16x16x32_bf16 v[32:35], v[148:151], v[220:223], v[32:35]
	v_mfma_f32_16x16x32_bf16 v[28:31], v[168:171], v[220:223], v[28:31]
	v_mfma_f32_16x16x32_bf16 v[24:27], v[148:151], v[228:231], v[24:27]
	v_mfma_f32_16x16x32_bf16 v[20:23], v[168:171], v[228:231], v[20:23]
	v_mfma_f32_16x16x32_bf16 v[48:51], v[164:167], v[208:211], v[48:51]
	v_mfma_f32_16x16x32_bf16 v[44:47], v[172:175], v[208:211], v[44:47]
	v_mfma_f32_16x16x32_bf16 v[40:43], v[164:167], v[216:219], v[40:43]
	v_mfma_f32_16x16x32_bf16 v[36:39], v[172:175], v[216:219], v[36:39]
	v_mfma_f32_16x16x32_bf16 v[32:35], v[164:167], v[224:227], v[32:35]
	v_mfma_f32_16x16x32_bf16 v[28:31], v[172:175], v[224:227], v[28:31]
	v_mfma_f32_16x16x32_bf16 v[24:27], v[164:167], v[232:235], v[24:27]
	v_mfma_f32_16x16x32_bf16 v[20:23], v[172:175], v[232:235], v[20:23]
	v_mfma_f32_16x16x32_bf16 v[16:19], v[176:179], v[204:207], v[16:19]
	v_mfma_f32_16x16x32_bf16 v[12:15], v[196:199], v[204:207], v[12:15]
	v_mfma_f32_16x16x32_bf16 v[8:11], v[176:179], v[212:215], v[8:11]
	v_mfma_f32_16x16x32_bf16 v[4:7], v[196:199], v[212:215], v[4:7]
	v_mfma_f32_16x16x32_bf16 v[0:3], v[176:179], v[220:223], v[0:3]
	v_mfma_f32_16x16x32_bf16 v[64:67], v[196:199], v[220:223], v[64:67]
	v_mfma_f32_16x16x32_bf16 v[72:75], v[176:179], v[228:231], v[72:75]
	v_mfma_f32_16x16x32_bf16 v[76:79], v[196:199], v[228:231], v[76:79]
	v_mfma_f32_16x16x32_bf16 v[16:19], v[192:195], v[208:211], v[16:19]
	v_mfma_f32_16x16x32_bf16 v[12:15], v[200:203], v[208:211], v[12:15]
	v_mfma_f32_16x16x32_bf16 v[8:11], v[192:195], v[216:219], v[8:11]
	v_mfma_f32_16x16x32_bf16 v[4:7], v[200:203], v[216:219], v[4:7]
	v_mfma_f32_16x16x32_bf16 v[0:3], v[192:195], v[224:227], v[0:3]
	v_mfma_f32_16x16x32_bf16 v[64:67], v[200:203], v[224:227], v[64:67]
	v_mfma_f32_16x16x32_bf16 v[72:75], v[192:195], v[232:235], v[72:75]
	v_mfma_f32_16x16x32_bf16 v[76:79], v[200:203], v[232:235], v[76:79]
	s_barrier
	s_add_i32 s6, s6, 2
	v_lshl_add_u64 v[134:135], v[134:135], 0, s[34:35]
	v_lshl_add_u64 v[136:137], v[136:137], 0, s[34:35]
	v_lshl_add_u64 v[138:139], v[138:139], 0, s[34:35]
	s_cmp_gt_u32 s6, 3
	v_lshl_add_u64 v[140:141], v[140:141], 0, s[34:35]
	s_cbranch_scc0 .LBB0_292
	v_add_u32_e32 v148, 0, v142
	v_add_u32_e32 v149, 0x10000, v148
	ds_read_b128 v[134:137], v149
	ds_read_b128 v[138:141], v149 offset:1024
	ds_read_b128 v[142:145], v149 offset:2048
	ds_read_b128 v[164:167], v149 offset:3072
	v_add_u32_e32 v149, 0x14000, v148
	ds_read_b128 v[168:171], v149
	ds_read_b128 v[172:175], v149 offset:1024
	ds_read_b128 v[176:179], v149 offset:2048
	ds_read_b128 v[192:195], v149 offset:3072
	s_add_u32 s4, s4, 0x400380
	s_addc_u32 s5, s5, 0
	s_mov_b32 m0, s8
	v_lshl_add_u64 v[130:131], s[4:5], 0, v[130:131]
	ds_read_b128 v[196:199], v112
	ds_read_b128 v[200:203], v112 offset:1024
	ds_read_b128 v[204:207], v112 offset:2048
	ds_read_b128 v[208:211], v112 offset:3072
	ds_read_b128 v[212:215], v112 offset:4096
	ds_read_b128 v[216:219], v112 offset:5120
	ds_read_b128 v[220:223], v112 offset:6144
	ds_read_b128 v[224:227], v112 offset:7168
	global_load_lds_dwordx4 v[130:131], off
	v_lshl_add_u64 v[130:131], s[4:5], 0, v[132:133]
	s_mov_b32 m0, s7
	s_nop 0
	global_load_lds_dwordx4 v[130:131], off
	s_waitcnt vmcnt(8)
	s_waitcnt lgkmcnt(0)
	s_barrier
	s_waitcnt lgkmcnt(0)
	v_mfma_f32_16x16x32_bf16 v[126:129], v[134:137], v[196:199], v[126:129]
	v_mfma_f32_16x16x32_bf16 v[122:125], v[142:145], v[196:199], v[122:125]
	v_mfma_f32_16x16x32_bf16 v[118:121], v[134:137], v[204:207], v[118:121]
	v_mfma_f32_16x16x32_bf16 v[114:117], v[142:145], v[204:207], v[114:117]
	v_mfma_f32_16x16x32_bf16 v[108:111], v[134:137], v[212:215], v[108:111]
	v_mfma_f32_16x16x32_bf16 v[104:107], v[142:145], v[212:215], v[104:107]
	v_mfma_f32_16x16x32_bf16 v[100:103], v[134:137], v[220:223], v[100:103]
	v_mfma_f32_16x16x32_bf16 v[96:99], v[142:145], v[220:223], v[96:99]
	v_mfma_f32_16x16x32_bf16 v[126:129], v[138:141], v[200:203], v[126:129]
	v_mfma_f32_16x16x32_bf16 v[122:125], v[164:167], v[200:203], v[122:125]
	v_mfma_f32_16x16x32_bf16 v[118:121], v[138:141], v[208:211], v[118:121]
	v_mfma_f32_16x16x32_bf16 v[114:117], v[164:167], v[208:211], v[114:117]
	v_mfma_f32_16x16x32_bf16 v[108:111], v[138:141], v[216:219], v[108:111]
	v_mfma_f32_16x16x32_bf16 v[104:107], v[164:167], v[216:219], v[104:107]
	v_mfma_f32_16x16x32_bf16 v[100:103], v[138:141], v[224:227], v[100:103]
	v_mfma_f32_16x16x32_bf16 v[96:99], v[164:167], v[224:227], v[96:99]
	v_mfma_f32_16x16x32_bf16 v[92:95], v[168:171], v[196:199], v[92:95]
	v_mfma_f32_16x16x32_bf16 v[88:91], v[176:179], v[196:199], v[88:91]
	v_mfma_f32_16x16x32_bf16 v[84:87], v[168:171], v[204:207], v[84:87]
	v_mfma_f32_16x16x32_bf16 v[80:83], v[176:179], v[204:207], v[80:83]
	v_mfma_f32_16x16x32_bf16 v[56:59], v[168:171], v[220:223], v[56:59]
	v_mfma_f32_16x16x32_bf16 v[52:55], v[176:179], v[220:223], v[52:55]
	v_mfma_f32_16x16x32_bf16 v[92:95], v[172:175], v[200:203], v[92:95]
	v_mfma_f32_16x16x32_bf16 v[88:91], v[192:195], v[200:203], v[88:91]
	v_mfma_f32_16x16x32_bf16 v[84:87], v[172:175], v[208:211], v[84:87]
	v_mfma_f32_16x16x32_bf16 v[80:83], v[192:195], v[208:211], v[80:83]
	v_mfma_f32_16x16x32_bf16 v[68:71], v[168:171], v[212:215], v[68:71]
	v_mfma_f32_16x16x32_bf16 v[60:63], v[176:179], v[212:215], v[60:63]
	v_mfma_f32_16x16x32_bf16 v[56:59], v[172:175], v[224:227], v[56:59]
	v_mfma_f32_16x16x32_bf16 v[52:55], v[192:195], v[224:227], v[52:55]
	v_mfma_f32_16x16x32_bf16 v[130:133], v[172:175], v[216:219], v[68:71]
	v_mfma_f32_16x16x32_bf16 v[196:199], v[192:195], v[216:219], v[60:63]
	s_barrier
	s_nop 1
	ds_read_b128 v[60:63], v112 offset:16384
	ds_read_b128 v[68:71], v112 offset:17408
	ds_read_b128 v[200:203], v112 offset:18432
	ds_read_b128 v[204:207], v112 offset:19456
	ds_read_b128 v[208:211], v112 offset:20480
	ds_read_b128 v[212:215], v112 offset:21504
	ds_read_b128 v[216:219], v112 offset:22528
	ds_read_b128 v[220:223], v112 offset:23552
	s_waitcnt vmcnt(2)
	s_waitcnt lgkmcnt(0)
	s_barrier
	s_waitcnt lgkmcnt(0)
	v_mfma_f32_16x16x32_bf16 v[48:51], v[134:137], v[60:63], v[48:51]
	v_mfma_f32_16x16x32_bf16 v[28:31], v[142:145], v[208:211], v[28:31]
	v_mfma_f32_16x16x32_bf16 v[48:51], v[138:141], v[68:71], v[48:51]
	v_mfma_f32_16x16x32_bf16 v[44:47], v[142:145], v[60:63], v[44:47]
	v_mfma_f32_16x16x32_bf16 v[40:43], v[134:137], v[200:203], v[40:43]
	v_mfma_f32_16x16x32_bf16 v[36:39], v[142:145], v[200:203], v[36:39]
	v_mfma_f32_16x16x32_bf16 v[32:35], v[134:137], v[208:211], v[32:35]
	v_mfma_f32_16x16x32_bf16 v[28:31], v[164:167], v[212:215], v[28:31]
	v_mfma_f32_16x16x32_bf16 v[24:27], v[134:137], v[216:219], v[24:27]
	v_mfma_f32_16x16x32_bf16 v[20:23], v[142:145], v[216:219], v[20:23]
	v_mfma_f32_16x16x32_bf16 v[224:227], v[164:167], v[68:71], v[44:47]
	v_mfma_f32_16x16x32_bf16 v[228:231], v[138:141], v[204:207], v[40:43]
	v_mfma_f32_16x16x32_bf16 v[232:235], v[164:167], v[204:207], v[36:39]
	v_mfma_f32_16x16x32_bf16 v[236:239], v[138:141], v[212:215], v[32:35]
	v_mfma_f32_16x16x32_bf16 v[134:137], v[138:141], v[220:223], v[24:27]
	v_mfma_f32_16x16x32_bf16 v[138:141], v[164:167], v[220:223], v[20:23]
	v_mfma_f32_16x16x32_bf16 v[8:11], v[168:171], v[200:203], v[8:11]
	v_mfma_f32_16x16x32_bf16 v[4:7], v[176:179], v[200:203], v[4:7]
	v_mfma_f32_16x16x32_bf16 v[0:3], v[168:171], v[208:211], v[0:3]
	v_mfma_f32_16x16x32_bf16 v[240:243], v[172:175], v[204:207], v[8:11]
	v_mfma_f32_16x16x32_bf16 v[200:203], v[192:195], v[204:207], v[4:7]
	v_mfma_f32_16x16x32_bf16 v[204:207], v[172:175], v[212:215], v[0:3]
	v_mfma_f32_16x16x32_bf16 v[0:3], v[176:179], v[208:211], v[64:67]
	v_mfma_f32_16x16x32_bf16 v[64:67], v[192:195], v[212:215], v[0:3]
	v_mfma_f32_16x16x32_bf16 v[0:3], v[168:171], v[216:219], v[72:75]
	v_mfma_f32_16x16x32_bf16 v[16:19], v[168:171], v[60:63], v[16:19]
	v_mfma_f32_16x16x32_bf16 v[12:15], v[176:179], v[60:63], v[12:15]
	v_mfma_f32_16x16x32_bf16 v[168:171], v[172:175], v[220:223], v[0:3]
	v_mfma_f32_16x16x32_bf16 v[0:3], v[176:179], v[216:219], v[76:79]
	v_mfma_f32_16x16x32_bf16 v[142:145], v[172:175], v[68:71], v[16:19]
	v_mfma_f32_16x16x32_bf16 v[164:167], v[192:195], v[68:71], v[12:15]
	v_mfma_f32_16x16x32_bf16 v[172:175], v[192:195], v[220:223], v[0:3]
	s_barrier
	s_nop 2
	v_add_u32_e32 v0, 0x18000, v148
	ds_read_b128 v[8:11], v0
	ds_read_b128 v[12:15], v0 offset:1024
	ds_read_b128 v[176:179], v0 offset:2048
	ds_read_b128 v[192:195], v0 offset:3072
	v_add_u32_e32 v0, 0x1c000, v148
	ds_read_b128 v[208:211], v0
	ds_read_b128 v[212:215], v0 offset:1024
	ds_read_b128 v[216:219], v0 offset:2048
	ds_read_b128 v[220:223], v0 offset:3072
	ds_read_b128 v[24:27], v112 offset:32768
	ds_read_b128 v[40:43], v112 offset:33792
	ds_read_b128 v[44:47], v112 offset:34816
	ds_read_b128 v[72:75], v112 offset:35840
	ds_read_b128 v[76:79], v112 offset:36864
	ds_read_b128 v[244:247], v112 offset:37888
	ds_read_b128 v[248:251], v112 offset:38912
	ds_read_b128 v[148:151], v112 offset:39936
	s_waitcnt vmcnt(0)
	s_waitcnt lgkmcnt(0)
	s_barrier
	s_waitcnt lgkmcnt(0)
	v_mfma_f32_16x16x32_bf16 v[0:3], v[8:11], v[24:27], v[126:129]
	v_mfma_f32_16x16x32_bf16 v[60:63], v[12:15], v[40:43], v[0:3]
	v_mfma_f32_16x16x32_bf16 v[0:3], v[176:179], v[24:27], v[122:125]
	v_mfma_f32_16x16x32_bf16 v[68:71], v[192:195], v[40:43], v[0:3]
	v_mfma_f32_16x16x32_bf16 v[0:3], v[8:11], v[44:47], v[118:121]
	v_mfma_f32_16x16x32_bf16 v[32:35], v[12:15], v[72:75], v[0:3]
	v_mfma_f32_16x16x32_bf16 v[0:3], v[176:179], v[44:47], v[114:117]
	v_mfma_f32_16x16x32_bf16 v[36:39], v[192:195], v[72:75], v[0:3]
	v_mfma_f32_16x16x32_bf16 v[0:3], v[8:11], v[76:79], v[108:111]
	v_mfma_f32_16x16x32_bf16 v[16:19], v[12:15], v[244:247], v[0:3]
	v_mfma_f32_16x16x32_bf16 v[0:3], v[176:179], v[76:79], v[104:107]
	v_mfma_f32_16x16x32_bf16 v[20:23], v[192:195], v[244:247], v[0:3]
	v_mfma_f32_16x16x32_bf16 v[0:3], v[8:11], v[248:251], v[100:103]
	v_mfma_f32_16x16x32_bf16 v[4:7], v[176:179], v[248:251], v[96:99]
	v_mfma_f32_16x16x32_bf16 v[0:3], v[12:15], v[148:151], v[0:3]
	v_mfma_f32_16x16x32_bf16 v[4:7], v[192:195], v[148:151], v[4:7]
	v_mfma_f32_16x16x32_bf16 v[92:95], v[208:211], v[24:27], v[92:95]
	v_mfma_f32_16x16x32_bf16 v[24:27], v[216:219], v[24:27], v[88:91]
	v_mfma_f32_16x16x32_bf16 v[118:121], v[220:223], v[40:43], v[24:27]
	v_mfma_f32_16x16x32_bf16 v[24:27], v[208:211], v[44:47], v[84:87]
	v_mfma_f32_16x16x32_bf16 v[96:99], v[212:215], v[72:75], v[24:27]
	v_mfma_f32_16x16x32_bf16 v[24:27], v[216:219], v[44:47], v[80:83]
	v_mfma_f32_16x16x32_bf16 v[100:103], v[220:223], v[72:75], v[24:27]
	v_mfma_f32_16x16x32_bf16 v[24:27], v[208:211], v[76:79], v[130:133]
	v_mfma_f32_16x16x32_bf16 v[72:75], v[212:215], v[244:247], v[24:27]
	v_mfma_f32_16x16x32_bf16 v[24:27], v[216:219], v[76:79], v[196:199]
	v_mfma_f32_16x16x32_bf16 v[76:79], v[220:223], v[244:247], v[24:27]
	v_mfma_f32_16x16x32_bf16 v[24:27], v[208:211], v[248:251], v[56:59]
	v_mfma_f32_16x16x32_bf16 v[114:117], v[212:215], v[40:43], v[92:95]
	v_mfma_f32_16x16x32_bf16 v[40:43], v[212:215], v[148:151], v[24:27]
	v_mfma_f32_16x16x32_bf16 v[24:27], v[216:219], v[248:251], v[52:55]
	v_mfma_f32_16x16x32_bf16 v[44:47], v[220:223], v[148:151], v[24:27]
	s_barrier
	ds_read_b128 v[56:59], v112 offset:49152
	ds_read_b128 v[88:91], v112 offset:50176
	ds_read_b128 v[92:95], v112 offset:51200
	ds_read_b128 v[108:111], v112 offset:52224
	ds_read_b128 v[130:133], v112 offset:53248
	ds_read_b128 v[148:151], v112 offset:54272
	ds_read_b128 v[196:199], v112 offset:55296
	ds_read_b128 v[244:247], v112 offset:56320
	s_waitcnt lgkmcnt(0)
	s_barrier
	s_waitcnt lgkmcnt(0)
	v_mfma_f32_16x16x32_bf16 v[24:27], v[8:11], v[56:59], v[48:51]
	v_mfma_f32_16x16x32_bf16 v[80:83], v[12:15], v[88:91], v[24:27]
	v_mfma_f32_16x16x32_bf16 v[24:27], v[176:179], v[56:59], v[224:227]
	v_mfma_f32_16x16x32_bf16 v[84:87], v[192:195], v[88:91], v[24:27]
	v_mfma_f32_16x16x32_bf16 v[24:27], v[8:11], v[92:95], v[228:231]
	v_mfma_f32_16x16x32_bf16 v[48:51], v[12:15], v[108:111], v[24:27]
	v_mfma_f32_16x16x32_bf16 v[24:27], v[176:179], v[92:95], v[232:235]
	v_mfma_f32_16x16x32_bf16 v[52:55], v[192:195], v[108:111], v[24:27]
	v_mfma_f32_16x16x32_bf16 v[24:27], v[8:11], v[130:133], v[236:239]
	v_mfma_f32_16x16x32_bf16 v[8:11], v[8:11], v[196:199], v[134:137]
	v_mfma_f32_16x16x32_bf16 v[24:27], v[12:15], v[148:151], v[24:27]
	v_mfma_f32_16x16x32_bf16 v[28:31], v[176:179], v[130:133], v[28:31]
	v_mfma_f32_16x16x32_bf16 v[8:11], v[12:15], v[244:247], v[8:11]
	v_mfma_f32_16x16x32_bf16 v[12:15], v[176:179], v[196:199], v[138:141]
	v_mfma_f32_16x16x32_bf16 v[28:31], v[192:195], v[148:151], v[28:31]
	v_mfma_f32_16x16x32_bf16 v[12:15], v[192:195], v[244:247], v[12:15]
	v_mfma_f32_16x16x32_bf16 v[104:107], v[208:211], v[56:59], v[142:145]
	v_mfma_f32_16x16x32_bf16 v[56:59], v[216:219], v[56:59], v[164:167]
	v_mfma_f32_16x16x32_bf16 v[126:129], v[220:223], v[88:91], v[56:59]
	v_mfma_f32_16x16x32_bf16 v[56:59], v[208:211], v[92:95], v[240:243]
	v_mfma_f32_16x16x32_bf16 v[122:125], v[212:215], v[88:91], v[104:107]
	v_mfma_f32_16x16x32_bf16 v[104:107], v[212:215], v[108:111], v[56:59]
	v_mfma_f32_16x16x32_bf16 v[56:59], v[216:219], v[92:95], v[200:203]
	v_mfma_f32_16x16x32_bf16 v[108:111], v[220:223], v[108:111], v[56:59]
	v_mfma_f32_16x16x32_bf16 v[56:59], v[208:211], v[130:133], v[204:207]
	v_mfma_f32_16x16x32_bf16 v[88:91], v[212:215], v[148:151], v[56:59]
	v_mfma_f32_16x16x32_bf16 v[56:59], v[216:219], v[130:133], v[64:67]
	v_mfma_f32_16x16x32_bf16 v[92:95], v[220:223], v[148:151], v[56:59]
	v_mfma_f32_16x16x32_bf16 v[56:59], v[208:211], v[196:199], v[168:171]
	v_mfma_f32_16x16x32_bf16 v[64:67], v[216:219], v[196:199], v[172:175]
	v_mfma_f32_16x16x32_bf16 v[56:59], v[212:215], v[244:247], v[56:59]
	v_mfma_f32_16x16x32_bf16 v[64:67], v[220:223], v[244:247], v[64:67]
	s_barrier
	s_waitcnt vmcnt(0)
	s_cmpk_lt_u32 s3, 0x100
	s_cbranch_scc0 .LBB0_286
	s_barrier
	s_branch .LBB0_286
.LBB0_295:
	s_setprio 0
	s_getreg_b32 s2, hwreg(HW_REG_XCC_ID, 0, 4)
	s_waitcnt vmcnt(0)
	s_waitcnt vmcnt(0)
	s_barrier
	s_mov_b64 s[0:1], exec
	v_readlane_b32 s4, v253, 14
	v_readlane_b32 s5, v253, 15
	s_and_b64 s[4:5], s[0:1], s[4:5]
	s_mov_b64 s[52:53], 0x40000
	s_mov_b64 exec, s[4:5]
	s_cbranch_execz .LBB0_347
	v_readlane_b32 s3, v252, 5
	s_waitcnt vmcnt(0) expcnt(0) lgkmcnt(0)
	s_and_b32 s8, s2, 15
	v_mov_b32_e32 v0, s3
	ds_read_b32 v2, v0
	v_readlane_b32 s3, v252, 6
	s_waitcnt lgkmcnt(0)
	v_cmp_ne_u32_e32 vcc, 0, v2
	v_mov_b32_e32 v0, s3
	ds_read_b32 v0, v0
	s_cbranch_vccnz .LBB0_311
	s_mov_b32 s9, 1
	s_branch .LBB0_299

.LBB0_435:
	s_or_b64 exec, exec, s[0:1]
	v_readlane_b32 s2, v252, 20
	s_mul_hi_u32 s0, s2, 0xc00000
	s_mul_i32 s1, s2, 0xc00000
	v_readlane_b32 s2, v254, 57
	s_add_u32 s1, s2, s1
	v_readlane_b32 s3, v252, 21
	v_writelane_b32 v252, s1, 26
	v_readlane_b32 s1, v254, 58
	s_addc_u32 s0, s1, s0
	v_writelane_b32 v252, s0, 27
	s_mov_b32 s0, s92
	s_waitcnt lgkmcnt(0)
	s_barrier
	s_cselect_b32 s5, 1, 0
	v_readfirstlane_b32 s6, v180
	s_nop 1
	s_bitcmp1_b32 s6, 8
	s_cbranch_scc1 .Lmy_prio_1
	s_setprio 1
.Lmy_prio_1:
	s_cmp_lg_u32 s5, 0
	s_mov_b32 s48, 0
	s_waitcnt vmcnt(0)
	s_branch .LBB0_438

.LBB0_444:
	s_or_b32 s4, s5, s51
	s_add_i32 s61, 0, 0x10000
	s_add_i32 s53, 0, 0x14000
	s_ashr_i32 s6, s4, 31
	s_add_u32 s38, s42, s4
	s_addc_u32 s39, s43, s6
	s_add_i32 s33, s74, 0xc000
	s_add_i32 s69, s74, 0xe000
	s_add_i32 s10, s5, 0x100
	s_add_u32 s12, s0, s5
	s_addc_u32 s13, s1, 0
	s_add_i32 s59, s61, s31
	s_add_i32 s58, s53, s31
	s_add_i32 s60, s59, 0x2000
	s_add_i32 s66, s58, 0x2000
	s_add_i32 s4, s55, s5
	s_and_b64 s[6:7], s[2:3], exec
	s_cselect_b32 s4, s94, s4
	s_cselect_b32 s67, s43, s41
	s_cselect_b32 vcc_lo, s42, s40
	s_ashr_i32 s6, s4, 31
	s_add_u32 s8, vcc_lo, s4
	s_addc_u32 s9, s67, s6
	s_add_i32 s25, 0, 0x18000
	s_add_i32 s93, 0, 0x1c000
	s_add_i32 s92, s25, s31
	s_add_i32 s75, s93, s31
	s_add_i32 s4, s5, 0x180
	s_add_i32 s52, s92, 0x2000
	s_add_i32 s24, s75, 0x2000
	s_add_i32 s5, s95, s5
	s_and_b64 s[6:7], s[2:3], exec
	s_cselect_b32 s5, s68, s5
	v_cndmask_b32_e64 v148, 0, 1, s[2:3]
	s_ashr_i32 s7, s5, 31
	v_add_u32_e32 v152, s61, v143
	s_add_u32 s6, vcc_lo, s5
	v_cmp_ne_u32_e32 vcc, 1, v148
	ds_read_b128 v[148:151], v152
	ds_read_b128 v[166:169], v152 offset:1024
	ds_read_b128 v[170:173], v152 offset:2048
	ds_read_b128 v[174:177], v152 offset:3072
	v_add_u32_e32 v152, s53, v143
	ds_read_b128 v[192:195], v152
	ds_read_b128 v[196:199], v152 offset:1024
	ds_read_b128 v[200:203], v152 offset:2048
	ds_read_b128 v[204:207], v152 offset:3072
	s_addc_u32 s7, s67, s7
	v_lshl_add_u64 v[152:153], s[38:39], 0, v[134:135]
	s_mov_b32 m0, s33
	v_lshl_add_u64 v[152:153], v[152:153], 0, s[36:37]
	ds_read_b128 v[208:211], v131
	ds_read_b128 v[212:215], v131 offset:1024
	ds_read_b128 v[216:219], v131 offset:2048
	ds_read_b128 v[220:223], v131 offset:3072
	ds_read_b128 v[224:227], v131 offset:4096
	ds_read_b128 v[228:231], v131 offset:5120
	ds_read_b128 v[232:235], v131 offset:6144
	ds_read_b128 v[236:239], v131 offset:7168
	global_load_lds_dwordx4 v[152:153], off
	v_lshl_add_u64 v[152:153], s[38:39], 0, v[136:137]
	v_lshl_add_u64 v[152:153], v[152:153], 0, s[36:37]
	s_mov_b32 m0, s69
	s_nop 0
	global_load_lds_dwordx4 v[152:153], off
	s_waitcnt vmcnt(8)
	s_waitcnt lgkmcnt(0)
	s_barrier
	s_waitcnt lgkmcnt(0)
	v_mfma_f32_16x16x32_bf16 v[126:129], v[148:151], v[208:211], v[126:129]
	v_mfma_f32_16x16x32_bf16 v[122:125], v[170:173], v[208:211], v[122:125]
	v_mfma_f32_16x16x32_bf16 v[118:121], v[148:151], v[216:219], v[118:121]
	v_mfma_f32_16x16x32_bf16 v[114:117], v[170:173], v[216:219], v[114:117]
	v_mfma_f32_16x16x32_bf16 v[108:111], v[148:151], v[224:227], v[108:111]
	v_mfma_f32_16x16x32_bf16 v[104:107], v[170:173], v[224:227], v[104:107]
	v_mfma_f32_16x16x32_bf16 v[100:103], v[148:151], v[232:235], v[100:103]
	v_mfma_f32_16x16x32_bf16 v[96:99], v[170:173], v[232:235], v[96:99]
	v_mfma_f32_16x16x32_bf16 v[126:129], v[166:169], v[212:215], v[126:129]
	v_mfma_f32_16x16x32_bf16 v[122:125], v[174:177], v[212:215], v[122:125]
	v_mfma_f32_16x16x32_bf16 v[118:121], v[166:169], v[220:223], v[118:121]
	v_mfma_f32_16x16x32_bf16 v[114:117], v[174:177], v[220:223], v[114:117]
	v_mfma_f32_16x16x32_bf16 v[108:111], v[166:169], v[228:231], v[108:111]
	v_mfma_f32_16x16x32_bf16 v[104:107], v[174:177], v[228:231], v[104:107]
	v_mfma_f32_16x16x32_bf16 v[100:103], v[166:169], v[236:239], v[100:103]
	v_mfma_f32_16x16x32_bf16 v[96:99], v[174:177], v[236:239], v[96:99]
	v_mfma_f32_16x16x32_bf16 v[80:83], v[192:195], v[208:211], v[80:83]
	v_mfma_f32_16x16x32_bf16 v[64:67], v[200:203], v[208:211], v[64:67]
	v_mfma_f32_16x16x32_bf16 v[44:47], v[192:195], v[216:219], v[44:47]
	v_mfma_f32_16x16x32_bf16 v[40:43], v[200:203], v[216:219], v[40:43]
	v_mfma_f32_16x16x32_bf16 v[36:39], v[192:195], v[224:227], v[36:39]
	v_mfma_f32_16x16x32_bf16 v[32:35], v[200:203], v[224:227], v[32:35]
	v_mfma_f32_16x16x32_bf16 v[28:31], v[192:195], v[232:235], v[28:31]
	v_mfma_f32_16x16x32_bf16 v[24:27], v[200:203], v[232:235], v[24:27]
	v_mfma_f32_16x16x32_bf16 v[80:83], v[196:199], v[212:215], v[80:83]
	v_mfma_f32_16x16x32_bf16 v[64:67], v[204:207], v[212:215], v[64:67]
	v_mfma_f32_16x16x32_bf16 v[44:47], v[196:199], v[220:223], v[44:47]
	v_mfma_f32_16x16x32_bf16 v[40:43], v[204:207], v[220:223], v[40:43]
	v_mfma_f32_16x16x32_bf16 v[36:39], v[196:199], v[228:231], v[36:39]
	v_mfma_f32_16x16x32_bf16 v[32:35], v[204:207], v[228:231], v[32:35]
	v_mfma_f32_16x16x32_bf16 v[28:31], v[196:199], v[236:239], v[28:31]
	v_mfma_f32_16x16x32_bf16 v[24:27], v[204:207], v[236:239], v[24:27]
	s_barrier
	v_lshl_add_u64 v[152:153], s[12:13], 0, v[112:113]
	s_mov_b32 m0, s59
	v_lshl_add_u64 v[154:155], v[152:153], 0, s[34:35]
	ds_read_b128 v[208:211], v131 offset:16384
	ds_read_b128 v[212:215], v131 offset:17408
	ds_read_b128 v[216:219], v131 offset:18432
	ds_read_b128 v[220:223], v131 offset:19456
	ds_read_b128 v[224:227], v131 offset:20480
	ds_read_b128 v[228:231], v131 offset:21504
	ds_read_b128 v[232:235], v131 offset:22528
	ds_read_b128 v[236:239], v131 offset:23552
	global_load_lds_dwordx4 v[154:155], off
	v_lshl_add_u64 v[154:155], s[12:13], 0, v[138:139]
	v_lshl_add_u64 v[178:179], v[154:155], 0, s[34:35]
	s_mov_b32 m0, s60
	s_mov_b64 s[12:13], 0x180
	global_load_lds_dwordx4 v[178:179], off
	v_lshl_add_u64 v[178:179], v[144:145], 0, s[10:11]
	s_mov_b32 m0, s58
	s_nop 0
	global_load_lds_dwordx4 v[178:179], off
	v_lshl_add_u64 v[178:179], v[164:165], 0, s[10:11]
	s_mov_b32 m0, s66
	s_nop 0
	global_load_lds_dwordx4 v[178:179], off
	v_cndmask_b32_e64 v178, v133, v130, s[2:3]
	s_mov_b32 m0, s74
	v_cndmask_b32_e64 v179, v141, v132, s[2:3]
	global_load_lds_dwordx4 v178, s[8:9]
	s_mov_b32 m0, s97
	s_nop 0
	global_load_lds_dwordx4 v179, s[8:9]
	s_waitcnt vmcnt(8)
	s_waitcnt lgkmcnt(0)
	s_barrier
	s_waitcnt lgkmcnt(0)
	v_mfma_f32_16x16x32_bf16 v[20:23], v[148:151], v[208:211], v[20:23]
	v_mfma_f32_16x16x32_bf16 v[16:19], v[170:173], v[208:211], v[16:19]
	v_mfma_f32_16x16x32_bf16 v[12:15], v[148:151], v[216:219], v[12:15]
	v_mfma_f32_16x16x32_bf16 v[8:11], v[170:173], v[216:219], v[8:11]
	v_mfma_f32_16x16x32_bf16 v[4:7], v[148:151], v[224:227], v[4:7]
	v_mfma_f32_16x16x32_bf16 v[0:3], v[170:173], v[224:227], v[0:3]
	v_mfma_f32_16x16x32_bf16 v[48:51], v[148:151], v[232:235], v[48:51]
	v_mfma_f32_16x16x32_bf16 v[52:55], v[170:173], v[232:235], v[52:55]
	v_mfma_f32_16x16x32_bf16 v[20:23], v[166:169], v[212:215], v[20:23]
	v_mfma_f32_16x16x32_bf16 v[16:19], v[174:177], v[212:215], v[16:19]
	v_mfma_f32_16x16x32_bf16 v[12:15], v[166:169], v[220:223], v[12:15]
	v_mfma_f32_16x16x32_bf16 v[8:11], v[174:177], v[220:223], v[8:11]
	v_mfma_f32_16x16x32_bf16 v[4:7], v[166:169], v[228:231], v[4:7]
	v_mfma_f32_16x16x32_bf16 v[0:3], v[174:177], v[228:231], v[0:3]
	v_mfma_f32_16x16x32_bf16 v[48:51], v[166:169], v[236:239], v[48:51]
	v_mfma_f32_16x16x32_bf16 v[52:55], v[174:177], v[236:239], v[52:55]
	v_mfma_f32_16x16x32_bf16 v[56:59], v[192:195], v[208:211], v[56:59]
	v_mfma_f32_16x16x32_bf16 v[60:63], v[200:203], v[208:211], v[60:63]
	v_mfma_f32_16x16x32_bf16 v[68:71], v[192:195], v[216:219], v[68:71]
	v_mfma_f32_16x16x32_bf16 v[72:75], v[200:203], v[216:219], v[72:75]
	v_mfma_f32_16x16x32_bf16 v[76:79], v[192:195], v[224:227], v[76:79]
	v_mfma_f32_16x16x32_bf16 v[84:87], v[200:203], v[224:227], v[84:87]
	v_mfma_f32_16x16x32_bf16 v[88:91], v[192:195], v[232:235], v[88:91]
	v_mfma_f32_16x16x32_bf16 v[92:95], v[200:203], v[232:235], v[92:95]
	v_mfma_f32_16x16x32_bf16 v[56:59], v[196:199], v[212:215], v[56:59]
	v_mfma_f32_16x16x32_bf16 v[60:63], v[204:207], v[212:215], v[60:63]
	v_mfma_f32_16x16x32_bf16 v[68:71], v[196:199], v[220:223], v[68:71]
	v_mfma_f32_16x16x32_bf16 v[72:75], v[204:207], v[220:223], v[72:75]
	v_mfma_f32_16x16x32_bf16 v[76:79], v[196:199], v[228:231], v[76:79]
	v_mfma_f32_16x16x32_bf16 v[84:87], v[204:207], v[228:231], v[84:87]
	v_mfma_f32_16x16x32_bf16 v[88:91], v[196:199], v[236:239], v[88:91]
	v_mfma_f32_16x16x32_bf16 v[92:95], v[204:207], v[236:239], v[92:95]
	s_barrier
	v_add_u32_e32 v174, s25, v143
	v_add_u32_e32 v204, s93, v143
	ds_read_b128 v[148:151], v174
	ds_read_b128 v[166:169], v174 offset:1024
	ds_read_b128 v[170:173], v174 offset:2048
	ds_read_b128 v[174:177], v174 offset:3072
	ds_read_b128 v[192:195], v204
	ds_read_b128 v[196:199], v204 offset:1024
	ds_read_b128 v[200:203], v204 offset:2048
	ds_read_b128 v[204:207], v204 offset:3072
	s_mov_b32 m0, s46
	v_cndmask_b32_e64 v240, v142, v134, s[2:3]
	ds_read_b128 v[208:211], v131 offset:32768
	ds_read_b128 v[212:215], v131 offset:33792
	ds_read_b128 v[216:219], v131 offset:34816
	ds_read_b128 v[220:223], v131 offset:35840
	ds_read_b128 v[224:227], v131 offset:36864
	ds_read_b128 v[228:231], v131 offset:37888
	ds_read_b128 v[232:235], v131 offset:38912
	ds_read_b128 v[236:239], v131 offset:39936
	global_load_lds_dwordx4 v240, s[8:9]
	v_cndmask_b32_e64 v240, v140, v136, s[2:3]
	s_mov_b32 m0, s47
	s_nop 0
	global_load_lds_dwordx4 v240, s[8:9]
	s_waitcnt vmcnt(8)
	s_waitcnt lgkmcnt(0)
	s_barrier
	s_waitcnt lgkmcnt(0)
	v_mfma_f32_16x16x32_bf16 v[126:129], v[148:151], v[208:211], v[126:129]
	v_mfma_f32_16x16x32_bf16 v[122:125], v[170:173], v[208:211], v[122:125]
	v_mfma_f32_16x16x32_bf16 v[118:121], v[148:151], v[216:219], v[118:121]
	v_mfma_f32_16x16x32_bf16 v[114:117], v[170:173], v[216:219], v[114:117]
	v_mfma_f32_16x16x32_bf16 v[108:111], v[148:151], v[224:227], v[108:111]
	v_mfma_f32_16x16x32_bf16 v[104:107], v[170:173], v[224:227], v[104:107]
	v_mfma_f32_16x16x32_bf16 v[100:103], v[148:151], v[232:235], v[100:103]
	v_mfma_f32_16x16x32_bf16 v[96:99], v[170:173], v[232:235], v[96:99]
	v_mfma_f32_16x16x32_bf16 v[126:129], v[166:169], v[212:215], v[126:129]
	v_mfma_f32_16x16x32_bf16 v[122:125], v[174:177], v[212:215], v[122:125]
	v_mfma_f32_16x16x32_bf16 v[118:121], v[166:169], v[220:223], v[118:121]
	v_mfma_f32_16x16x32_bf16 v[114:117], v[174:177], v[220:223], v[114:117]
	v_mfma_f32_16x16x32_bf16 v[108:111], v[166:169], v[228:231], v[108:111]
	v_mfma_f32_16x16x32_bf16 v[104:107], v[174:177], v[228:231], v[104:107]
	v_mfma_f32_16x16x32_bf16 v[100:103], v[166:169], v[236:239], v[100:103]
	v_mfma_f32_16x16x32_bf16 v[96:99], v[174:177], v[236:239], v[96:99]
	v_mfma_f32_16x16x32_bf16 v[80:83], v[192:195], v[208:211], v[80:83]
	v_mfma_f32_16x16x32_bf16 v[64:67], v[200:203], v[208:211], v[64:67]
	v_mfma_f32_16x16x32_bf16 v[44:47], v[192:195], v[216:219], v[44:47]
	v_mfma_f32_16x16x32_bf16 v[40:43], v[200:203], v[216:219], v[40:43]
	v_mfma_f32_16x16x32_bf16 v[36:39], v[192:195], v[224:227], v[36:39]
	v_mfma_f32_16x16x32_bf16 v[32:35], v[200:203], v[224:227], v[32:35]
	v_mfma_f32_16x16x32_bf16 v[28:31], v[192:195], v[232:235], v[28:31]
	v_mfma_f32_16x16x32_bf16 v[24:27], v[200:203], v[232:235], v[24:27]
	v_mfma_f32_16x16x32_bf16 v[80:83], v[196:199], v[212:215], v[80:83]
	v_mfma_f32_16x16x32_bf16 v[64:67], v[204:207], v[212:215], v[64:67]
	v_mfma_f32_16x16x32_bf16 v[44:47], v[196:199], v[220:223], v[44:47]
	v_mfma_f32_16x16x32_bf16 v[40:43], v[204:207], v[220:223], v[40:43]
	v_mfma_f32_16x16x32_bf16 v[36:39], v[196:199], v[228:231], v[36:39]
	v_mfma_f32_16x16x32_bf16 v[32:35], v[204:207], v[228:231], v[32:35]
	v_mfma_f32_16x16x32_bf16 v[28:31], v[196:199], v[236:239], v[28:31]
	v_mfma_f32_16x16x32_bf16 v[24:27], v[204:207], v[236:239], v[24:27]
	s_barrier
	s_mov_b32 m0, s92
	v_lshl_add_u64 v[152:153], v[152:153], 0, s[12:13]
	ds_read_b128 v[208:211], v131 offset:49152
	ds_read_b128 v[212:215], v131 offset:50176
	ds_read_b128 v[216:219], v131 offset:51200
	ds_read_b128 v[220:223], v131 offset:52224
	ds_read_b128 v[224:227], v131 offset:53248
	ds_read_b128 v[228:231], v131 offset:54272
	ds_read_b128 v[232:235], v131 offset:55296
	ds_read_b128 v[236:239], v131 offset:56320
	s_mov_b32 s5, s11
	global_load_lds_dwordx4 v[152:153], off
	v_lshl_add_u64 v[152:153], v[154:155], 0, s[12:13]
	s_mov_b32 m0, s52
	s_nop 0
	global_load_lds_dwordx4 v[152:153], off
	v_lshl_add_u64 v[152:153], v[144:145], 0, s[4:5]
	s_mov_b32 m0, s75
	s_nop 0
	global_load_lds_dwordx4 v[152:153], off
	v_lshl_add_u64 v[152:153], v[164:165], 0, s[4:5]
	s_mov_b32 m0, s24
	s_nop 0
	global_load_lds_dwordx4 v[152:153], off
	s_mov_b32 m0, s50
	s_nop 0
	global_load_lds_dwordx4 v178, s[6:7]
	s_mov_b32 m0, s54
	s_nop 0
	global_load_lds_dwordx4 v179, s[6:7]
	s_waitcnt vmcnt(8)
	s_waitcnt lgkmcnt(0)
	s_barrier
	s_waitcnt lgkmcnt(0)
	v_mfma_f32_16x16x32_bf16 v[20:23], v[148:151], v[208:211], v[20:23]
	v_mfma_f32_16x16x32_bf16 v[16:19], v[170:173], v[208:211], v[16:19]
	v_mfma_f32_16x16x32_bf16 v[12:15], v[148:151], v[216:219], v[12:15]
	v_mfma_f32_16x16x32_bf16 v[8:11], v[170:173], v[216:219], v[8:11]
	v_mfma_f32_16x16x32_bf16 v[4:7], v[148:151], v[224:227], v[4:7]
	v_mfma_f32_16x16x32_bf16 v[0:3], v[170:173], v[224:227], v[0:3]
	v_mfma_f32_16x16x32_bf16 v[48:51], v[148:151], v[232:235], v[48:51]
	v_mfma_f32_16x16x32_bf16 v[52:55], v[170:173], v[232:235], v[52:55]
	v_mfma_f32_16x16x32_bf16 v[20:23], v[166:169], v[212:215], v[20:23]
	v_mfma_f32_16x16x32_bf16 v[16:19], v[174:177], v[212:215], v[16:19]
	v_mfma_f32_16x16x32_bf16 v[12:15], v[166:169], v[220:223], v[12:15]
	v_mfma_f32_16x16x32_bf16 v[8:11], v[174:177], v[220:223], v[8:11]
	v_mfma_f32_16x16x32_bf16 v[4:7], v[166:169], v[228:231], v[4:7]
	v_mfma_f32_16x16x32_bf16 v[0:3], v[174:177], v[228:231], v[0:3]
	v_mfma_f32_16x16x32_bf16 v[48:51], v[166:169], v[236:239], v[48:51]
	v_mfma_f32_16x16x32_bf16 v[52:55], v[174:177], v[236:239], v[52:55]
	v_mfma_f32_16x16x32_bf16 v[56:59], v[192:195], v[208:211], v[56:59]
	v_mfma_f32_16x16x32_bf16 v[60:63], v[200:203], v[208:211], v[60:63]
	v_mfma_f32_16x16x32_bf16 v[68:71], v[192:195], v[216:219], v[68:71]
	v_mfma_f32_16x16x32_bf16 v[72:75], v[200:203], v[216:219], v[72:75]
	v_mfma_f32_16x16x32_bf16 v[76:79], v[192:195], v[224:227], v[76:79]
	v_mfma_f32_16x16x32_bf16 v[84:87], v[200:203], v[224:227], v[84:87]
	v_mfma_f32_16x16x32_bf16 v[88:91], v[192:195], v[232:235], v[88:91]
	v_mfma_f32_16x16x32_bf16 v[92:95], v[200:203], v[232:235], v[92:95]
	v_mfma_f32_16x16x32_bf16 v[56:59], v[196:199], v[212:215], v[56:59]
	v_mfma_f32_16x16x32_bf16 v[60:63], v[204:207], v[212:215], v[60:63]
	v_mfma_f32_16x16x32_bf16 v[68:71], v[196:199], v[220:223], v[68:71]
	v_mfma_f32_16x16x32_bf16 v[72:75], v[204:207], v[220:223], v[72:75]
	v_mfma_f32_16x16x32_bf16 v[76:79], v[196:199], v[228:231], v[76:79]
	v_mfma_f32_16x16x32_bf16 v[84:87], v[204:207], v[228:231], v[84:87]
	v_mfma_f32_16x16x32_bf16 v[88:91], v[196:199], v[236:239], v[88:91]
	v_mfma_f32_16x16x32_bf16 v[92:95], v[204:207], v[236:239], v[92:95]
	s_barrier
	s_mov_b64 s[2:3], 0
	s_movk_i32 s5, 0x100
	s_cbranch_vccz .LBB0_444
	v_add_u32_e32 v112, 0, v143
	v_add_u32_e32 v130, 0x10000, v112
	ds_read_b128 v[132:135], v130
	ds_read_b128 v[136:139], v130 offset:1024
	ds_read_b128 v[148:151], v130 offset:2048
	ds_read_b128 v[164:167], v130 offset:3072
	v_add_u32_e32 v130, 0x14000, v112
	ds_read_b128 v[168:171], v130
	ds_read_b128 v[172:175], v130 offset:1024
	ds_read_b128 v[176:179], v130 offset:2048
	ds_read_b128 v[192:195], v130 offset:3072
	s_add_u32 s0, s40, s30
	s_addc_u32 s1, s41, s96
	v_mov_b32_e32 v143, v113
	v_lshl_add_u64 v[142:143], s[0:1], 0, v[142:143]
	v_mov_b32_e32 v141, v113
	s_mov_b32 m0, s33
	v_lshl_add_u64 v[142:143], v[142:143], 0, s[36:37]
	v_lshl_add_u64 v[140:141], s[0:1], 0, v[140:141]
	ds_read_b128 v[196:199], v131
	ds_read_b128 v[200:203], v131 offset:1024
	ds_read_b128 v[204:207], v131 offset:2048
	ds_read_b128 v[208:211], v131 offset:3072
	ds_read_b128 v[212:215], v131 offset:4096
	ds_read_b128 v[216:219], v131 offset:5120
	ds_read_b128 v[220:223], v131 offset:6144
	ds_read_b128 v[224:227], v131 offset:7168
	global_load_lds_dwordx4 v[142:143], off
	v_lshl_add_u64 v[140:141], v[140:141], 0, s[36:37]
	s_mov_b32 m0, s69
	s_nop 0
	global_load_lds_dwordx4 v[140:141], off
	s_waitcnt vmcnt(8)
	s_waitcnt lgkmcnt(0)
	s_barrier
	s_waitcnt lgkmcnt(0)
	v_mfma_f32_16x16x32_bf16 v[126:129], v[132:135], v[196:199], v[126:129]
	v_mfma_f32_16x16x32_bf16 v[122:125], v[148:151], v[196:199], v[122:125]
	v_mfma_f32_16x16x32_bf16 v[118:121], v[132:135], v[204:207], v[118:121]
	v_mfma_f32_16x16x32_bf16 v[114:117], v[148:151], v[204:207], v[114:117]
	v_mfma_f32_16x16x32_bf16 v[100:103], v[132:135], v[220:223], v[100:103]
	v_mfma_f32_16x16x32_bf16 v[96:99], v[148:151], v[220:223], v[96:99]
	v_mfma_f32_16x16x32_bf16 v[126:129], v[136:139], v[200:203], v[126:129]
	v_mfma_f32_16x16x32_bf16 v[122:125], v[164:167], v[200:203], v[122:125]
	v_mfma_f32_16x16x32_bf16 v[118:121], v[136:139], v[208:211], v[118:121]
	v_mfma_f32_16x16x32_bf16 v[114:117], v[164:167], v[208:211], v[114:117]
	v_mfma_f32_16x16x32_bf16 v[108:111], v[132:135], v[212:215], v[108:111]
	v_mfma_f32_16x16x32_bf16 v[104:107], v[148:151], v[212:215], v[104:107]
	v_mfma_f32_16x16x32_bf16 v[100:103], v[136:139], v[224:227], v[100:103]
	v_mfma_f32_16x16x32_bf16 v[96:99], v[164:167], v[224:227], v[96:99]
	v_mfma_f32_16x16x32_bf16 v[140:143], v[136:139], v[216:219], v[108:111]
	v_mfma_f32_16x16x32_bf16 v[228:231], v[164:167], v[216:219], v[104:107]
	v_mfma_f32_16x16x32_bf16 v[80:83], v[168:171], v[196:199], v[80:83]
	v_mfma_f32_16x16x32_bf16 v[64:67], v[176:179], v[196:199], v[64:67]
	v_mfma_f32_16x16x32_bf16 v[44:47], v[168:171], v[204:207], v[44:47]
	v_mfma_f32_16x16x32_bf16 v[40:43], v[176:179], v[204:207], v[40:43]
	v_mfma_f32_16x16x32_bf16 v[36:39], v[168:171], v[212:215], v[36:39]
	v_mfma_f32_16x16x32_bf16 v[32:35], v[176:179], v[212:215], v[32:35]
	v_mfma_f32_16x16x32_bf16 v[28:31], v[168:171], v[220:223], v[28:31]
	v_mfma_f32_16x16x32_bf16 v[24:27], v[176:179], v[220:223], v[24:27]
	v_mfma_f32_16x16x32_bf16 v[80:83], v[172:175], v[200:203], v[80:83]
	v_mfma_f32_16x16x32_bf16 v[64:67], v[192:195], v[200:203], v[64:67]
	v_mfma_f32_16x16x32_bf16 v[44:47], v[172:175], v[208:211], v[44:47]
	v_mfma_f32_16x16x32_bf16 v[40:43], v[192:195], v[208:211], v[40:43]
	v_mfma_f32_16x16x32_bf16 v[36:39], v[172:175], v[216:219], v[36:39]
	v_mfma_f32_16x16x32_bf16 v[32:35], v[192:195], v[216:219], v[32:35]
	v_mfma_f32_16x16x32_bf16 v[28:31], v[172:175], v[224:227], v[28:31]
	v_mfma_f32_16x16x32_bf16 v[24:27], v[192:195], v[224:227], v[24:27]
	s_barrier
	ds_read_b128 v[104:107], v131 offset:16384
	ds_read_b128 v[108:111], v131 offset:17408
	ds_read_b128 v[196:199], v131 offset:18432
	ds_read_b128 v[200:203], v131 offset:19456
	ds_read_b128 v[204:207], v131 offset:20480
	ds_read_b128 v[208:211], v131 offset:21504
	ds_read_b128 v[212:215], v131 offset:22528
	ds_read_b128 v[216:219], v131 offset:23552
	s_waitcnt vmcnt(2)
	s_waitcnt lgkmcnt(0)
	s_barrier
	s_waitcnt lgkmcnt(0)
	v_mfma_f32_16x16x32_bf16 v[20:23], v[132:135], v[104:107], v[20:23]
	v_mfma_f32_16x16x32_bf16 v[16:19], v[148:151], v[104:107], v[16:19]
	v_mfma_f32_16x16x32_bf16 v[12:15], v[132:135], v[196:199], v[12:15]
	v_mfma_f32_16x16x32_bf16 v[8:11], v[148:151], v[196:199], v[8:11]
	v_mfma_f32_16x16x32_bf16 v[4:7], v[132:135], v[204:207], v[4:7]
	v_mfma_f32_16x16x32_bf16 v[0:3], v[148:151], v[204:207], v[0:3]
	v_mfma_f32_16x16x32_bf16 v[48:51], v[132:135], v[212:215], v[48:51]
	v_mfma_f32_16x16x32_bf16 v[52:55], v[148:151], v[212:215], v[52:55]
	v_mfma_f32_16x16x32_bf16 v[20:23], v[136:139], v[108:111], v[20:23]
	v_mfma_f32_16x16x32_bf16 v[16:19], v[164:167], v[108:111], v[16:19]
	v_mfma_f32_16x16x32_bf16 v[12:15], v[136:139], v[200:203], v[12:15]
	v_mfma_f32_16x16x32_bf16 v[8:11], v[164:167], v[200:203], v[8:11]
	v_mfma_f32_16x16x32_bf16 v[4:7], v[136:139], v[208:211], v[4:7]
	v_mfma_f32_16x16x32_bf16 v[0:3], v[164:167], v[208:211], v[0:3]
	v_mfma_f32_16x16x32_bf16 v[48:51], v[136:139], v[216:219], v[48:51]
	v_mfma_f32_16x16x32_bf16 v[52:55], v[164:167], v[216:219], v[52:55]
	v_mfma_f32_16x16x32_bf16 v[56:59], v[168:171], v[104:107], v[56:59]
	v_mfma_f32_16x16x32_bf16 v[132:135], v[172:175], v[108:111], v[56:59]
	v_mfma_f32_16x16x32_bf16 v[56:59], v[176:179], v[104:107], v[60:63]
	v_mfma_f32_16x16x32_bf16 v[136:139], v[192:195], v[108:111], v[56:59]
	v_mfma_f32_16x16x32_bf16 v[56:59], v[168:171], v[196:199], v[68:71]
	v_mfma_f32_16x16x32_bf16 v[148:151], v[172:175], v[200:203], v[56:59]
	v_mfma_f32_16x16x32_bf16 v[56:59], v[176:179], v[196:199], v[72:75]
	v_mfma_f32_16x16x32_bf16 v[164:167], v[192:195], v[200:203], v[56:59]
	v_mfma_f32_16x16x32_bf16 v[56:59], v[168:171], v[204:207], v[76:79]
	v_mfma_f32_16x16x32_bf16 v[196:199], v[172:175], v[208:211], v[56:59]
	v_mfma_f32_16x16x32_bf16 v[56:59], v[176:179], v[204:207], v[84:87]
	v_mfma_f32_16x16x32_bf16 v[200:203], v[192:195], v[208:211], v[56:59]
	v_mfma_f32_16x16x32_bf16 v[56:59], v[168:171], v[212:215], v[88:91]
	v_mfma_f32_16x16x32_bf16 v[168:171], v[172:175], v[216:219], v[56:59]
	v_mfma_f32_16x16x32_bf16 v[56:59], v[176:179], v[212:215], v[92:95]
	v_mfma_f32_16x16x32_bf16 v[172:175], v[192:195], v[216:219], v[56:59]
	s_barrier
	s_nop 4
	v_add_u32_e32 v56, 0x18000, v112
	ds_read_b128 v[176:179], v56
	ds_read_b128 v[192:195], v56 offset:1024
	ds_read_b128 v[204:207], v56 offset:2048
	ds_read_b128 v[208:211], v56 offset:3072
	v_add_u32_e32 v56, 0x1c000, v112
	ds_read_b128 v[212:215], v56
	ds_read_b128 v[216:219], v56 offset:1024
	ds_read_b128 v[220:223], v56 offset:2048
	ds_read_b128 v[224:227], v56 offset:3072
	ds_read_b128 v[56:59], v131 offset:32768
	ds_read_b128 v[60:63], v131 offset:33792
	ds_read_b128 v[68:71], v131 offset:34816
	ds_read_b128 v[84:87], v131 offset:35840
	ds_read_b128 v[232:235], v131 offset:36864
	ds_read_b128 v[236:239], v131 offset:37888
	ds_read_b128 v[240:243], v131 offset:38912
	ds_read_b128 v[244:247], v131 offset:39936
	s_waitcnt vmcnt(0)
	s_waitcnt lgkmcnt(0)
	s_barrier
	s_waitcnt lgkmcnt(0)
	v_mfma_f32_16x16x32_bf16 v[72:75], v[176:179], v[56:59], v[126:129]
	v_mfma_f32_16x16x32_bf16 v[126:129], v[192:195], v[60:63], v[72:75]
	v_mfma_f32_16x16x32_bf16 v[72:75], v[204:207], v[56:59], v[122:125]
	v_mfma_f32_16x16x32_bf16 v[122:125], v[208:211], v[60:63], v[72:75]
	v_mfma_f32_16x16x32_bf16 v[72:75], v[176:179], v[68:71], v[118:121]
	v_mfma_f32_16x16x32_bf16 v[108:111], v[192:195], v[84:87], v[72:75]
	v_mfma_f32_16x16x32_bf16 v[72:75], v[204:207], v[68:71], v[114:117]
	v_mfma_f32_16x16x32_bf16 v[104:107], v[208:211], v[84:87], v[72:75]
	v_mfma_f32_16x16x32_bf16 v[72:75], v[176:179], v[232:235], v[140:143]
	v_mfma_f32_16x16x32_bf16 v[92:95], v[192:195], v[236:239], v[72:75]
	v_mfma_f32_16x16x32_bf16 v[72:75], v[204:207], v[232:235], v[228:231]
	v_mfma_f32_16x16x32_bf16 v[88:91], v[208:211], v[236:239], v[72:75]
	v_mfma_f32_16x16x32_bf16 v[72:75], v[176:179], v[240:243], v[100:103]
	v_mfma_f32_16x16x32_bf16 v[76:79], v[192:195], v[244:247], v[72:75]
	v_mfma_f32_16x16x32_bf16 v[72:75], v[204:207], v[240:243], v[96:99]
	v_mfma_f32_16x16x32_bf16 v[72:75], v[208:211], v[244:247], v[72:75]
	v_mfma_f32_16x16x32_bf16 v[80:83], v[212:215], v[56:59], v[80:83]
	v_mfma_f32_16x16x32_bf16 v[56:59], v[220:223], v[56:59], v[64:67]
	v_mfma_f32_16x16x32_bf16 v[44:47], v[212:215], v[68:71], v[44:47]
	v_mfma_f32_16x16x32_bf16 v[40:43], v[220:223], v[68:71], v[40:43]
	v_mfma_f32_16x16x32_bf16 v[36:39], v[212:215], v[232:235], v[36:39]
	v_mfma_f32_16x16x32_bf16 v[32:35], v[220:223], v[232:235], v[32:35]
	v_mfma_f32_16x16x32_bf16 v[28:31], v[212:215], v[240:243], v[28:31]
	v_mfma_f32_16x16x32_bf16 v[24:27], v[220:223], v[240:243], v[24:27]
	v_mfma_f32_16x16x32_bf16 v[118:121], v[216:219], v[60:63], v[80:83]
	v_mfma_f32_16x16x32_bf16 v[114:117], v[224:227], v[60:63], v[56:59]
	v_mfma_f32_16x16x32_bf16 v[100:103], v[216:219], v[84:87], v[44:47]
	v_mfma_f32_16x16x32_bf16 v[96:99], v[224:227], v[84:87], v[40:43]
	v_mfma_f32_16x16x32_bf16 v[84:87], v[216:219], v[236:239], v[36:39]
	v_mfma_f32_16x16x32_bf16 v[80:83], v[224:227], v[236:239], v[32:35]
	v_mfma_f32_16x16x32_bf16 v[68:71], v[216:219], v[244:247], v[28:31]
	v_mfma_f32_16x16x32_bf16 v[64:67], v[224:227], v[244:247], v[24:27]
	s_barrier
	ds_read_b128 v[32:35], v131 offset:49152
	ds_read_b128 v[36:39], v131 offset:50176
	ds_read_b128 v[140:143], v131 offset:51200
	ds_read_b128 v[228:231], v131 offset:52224
	ds_read_b128 v[232:235], v131 offset:53248
	ds_read_b128 v[236:239], v131 offset:54272
	ds_read_b128 v[240:243], v131 offset:55296
	ds_read_b128 v[244:247], v131 offset:56320
	s_waitcnt lgkmcnt(0)
	s_barrier
	s_waitcnt lgkmcnt(0)
	v_mfma_f32_16x16x32_bf16 v[0:3], v[204:207], v[232:235], v[0:3]
	v_mfma_f32_16x16x32_bf16 v[12:15], v[176:179], v[140:143], v[12:15]
	v_mfma_f32_16x16x32_bf16 v[24:27], v[208:211], v[236:239], v[0:3]
	v_mfma_f32_16x16x32_bf16 v[0:3], v[176:179], v[240:243], v[48:51]
	v_mfma_f32_16x16x32_bf16 v[20:23], v[176:179], v[32:35], v[20:23]
	v_mfma_f32_16x16x32_bf16 v[16:19], v[204:207], v[32:35], v[16:19]
	v_mfma_f32_16x16x32_bf16 v[44:47], v[192:195], v[228:231], v[12:15]
	v_mfma_f32_16x16x32_bf16 v[8:11], v[204:207], v[140:143], v[8:11]
	v_mfma_f32_16x16x32_bf16 v[4:7], v[176:179], v[232:235], v[4:7]
	v_mfma_f32_16x16x32_bf16 v[12:15], v[192:195], v[244:247], v[0:3]
	v_mfma_f32_16x16x32_bf16 v[0:3], v[204:207], v[240:243], v[52:55]
	v_mfma_f32_16x16x32_bf16 v[60:63], v[192:195], v[36:39], v[20:23]
	v_mfma_f32_16x16x32_bf16 v[56:59], v[208:211], v[36:39], v[16:19]
	v_mfma_f32_16x16x32_bf16 v[40:43], v[208:211], v[228:231], v[8:11]
	v_mfma_f32_16x16x32_bf16 v[28:31], v[192:195], v[236:239], v[4:7]
	v_mfma_f32_16x16x32_bf16 v[8:11], v[208:211], v[244:247], v[0:3]
	v_mfma_f32_16x16x32_bf16 v[0:3], v[212:215], v[32:35], v[132:135]
	v_mfma_f32_16x16x32_bf16 v[52:55], v[216:219], v[36:39], v[0:3]
	v_mfma_f32_16x16x32_bf16 v[0:3], v[220:223], v[32:35], v[136:139]
	v_mfma_f32_16x16x32_bf16 v[48:51], v[224:227], v[36:39], v[0:3]
	v_mfma_f32_16x16x32_bf16 v[0:3], v[212:215], v[140:143], v[148:151]
	v_mfma_f32_16x16x32_bf16 v[36:39], v[216:219], v[228:231], v[0:3]
	v_mfma_f32_16x16x32_bf16 v[0:3], v[220:223], v[140:143], v[164:167]
	v_mfma_f32_16x16x32_bf16 v[32:35], v[224:227], v[228:231], v[0:3]
	v_mfma_f32_16x16x32_bf16 v[0:3], v[212:215], v[232:235], v[196:199]
	v_mfma_f32_16x16x32_bf16 v[20:23], v[216:219], v[236:239], v[0:3]
	v_mfma_f32_16x16x32_bf16 v[0:3], v[220:223], v[232:235], v[200:203]
	v_mfma_f32_16x16x32_bf16 v[16:19], v[224:227], v[236:239], v[0:3]
	v_mfma_f32_16x16x32_bf16 v[0:3], v[212:215], v[240:243], v[168:171]
	v_mfma_f32_16x16x32_bf16 v[4:7], v[216:219], v[244:247], v[0:3]
	v_mfma_f32_16x16x32_bf16 v[0:3], v[220:223], v[240:243], v[172:175]
	v_mfma_f32_16x16x32_bf16 v[0:3], v[224:227], v[244:247], v[0:3]
	s_barrier
	s_waitcnt vmcnt(0)
	s_cmpk_lt_u32 s15, 0x100
	s_cbranch_scc0 .LBB0_447
	s_barrier

.LBB0_495:
	s_setprio 0
	s_getreg_b32 s2, hwreg(HW_REG_XCC_ID, 0, 4)
	s_waitcnt vmcnt(0)
	s_waitcnt vmcnt(0)
	s_barrier
	s_mov_b64 s[0:1], exec
	v_readlane_b32 s4, v253, 14
	v_readlane_b32 s5, v253, 15
	s_and_b64 s[4:5], s[0:1], s[4:5]
	s_mov_b64 exec, s[4:5]
	s_cbranch_execz .LBB0_547
	v_readlane_b32 s3, v252, 5
	s_waitcnt vmcnt(0) expcnt(0) lgkmcnt(0)
	s_and_b32 s8, s2, 15
	v_mov_b32_e32 v0, s3
	ds_read_b32 v2, v0
	v_readlane_b32 s3, v252, 6
	s_waitcnt lgkmcnt(0)
	v_cmp_ne_u32_e32 vcc, 0, v2
	v_mov_b32_e32 v0, s3
	ds_read_b32 v0, v0
	s_cbranch_vccnz .LBB0_511
	s_mov_b32 s9, 1
	s_branch .LBB0_499

.LBB0_547:
	s_or_b64 exec, exec, s[0:1]
	v_readlane_b32 s0, v252, 20
	v_readlane_b32 s1, v252, 21
	s_lshl_b64 s[0:1], s[0:1], 22
	v_readlane_b32 s2, v254, 13
	s_add_u32 s10, s2, s0
	v_readlane_b32 s0, v254, 14
	s_addc_u32 s12, s0, s1
	s_mov_b32 s0, s92
	s_mov_b32 s13, 0
	s_waitcnt lgkmcnt(0)
	s_barrier
	s_cselect_b32 s5, 1, 0
	v_readfirstlane_b32 s6, v180
	s_nop 1
	s_bitcmp1_b32 s6, 8
	s_cbranch_scc1 .Lmy_prio_2
	s_setprio 1
.Lmy_prio_2:
	s_cmp_lg_u32 s5, 0
	s_branch .LBB0_550

.LBB0_556:
	s_add_i32 s7, 0, 0x10000
	v_add_u32_e32 v143, s7, v142
	s_add_i32 s8, 0, 0x14000
	ds_read_b128 v[148:151], v143
	ds_read_b128 v[152:155], v143 offset:1024
	ds_read_b128 v[164:167], v143 offset:2048
	ds_read_b128 v[168:171], v143 offset:3072
	v_add_u32_e32 v143, s8, v142
	ds_read_b128 v[172:175], v143
	ds_read_b128 v[176:179], v143 offset:1024
	ds_read_b128 v[192:195], v143 offset:2048
	ds_read_b128 v[196:199], v143 offset:3072
	v_lshl_add_u64 v[144:145], s[78:79], 0, v[138:139]
	s_add_i32 s6, s31, 0xc000
	v_lshl_add_u64 v[232:233], v[144:145], 0, s[72:73]
	s_mov_b32 m0, s6
	ds_read_b128 v[200:203], v112
	ds_read_b128 v[204:207], v112 offset:1024
	ds_read_b128 v[208:211], v112 offset:2048
	ds_read_b128 v[212:215], v112 offset:3072
	ds_read_b128 v[216:219], v112 offset:4096
	ds_read_b128 v[220:223], v112 offset:5120
	ds_read_b128 v[224:227], v112 offset:6144
	ds_read_b128 v[228:231], v112 offset:7168
	global_load_lds_dwordx4 v[232:233], off
	v_lshl_add_u64 v[232:233], s[78:79], 0, v[140:141]
	s_add_i32 s5, s31, 0xe000
	v_lshl_add_u64 v[234:235], v[232:233], 0, s[72:73]
	s_mov_b32 m0, s5
	s_nop 0
	global_load_lds_dwordx4 v[234:235], off
	s_waitcnt vmcnt(8)
	s_waitcnt lgkmcnt(0)
	s_barrier
	s_waitcnt lgkmcnt(0)
	v_mfma_f32_16x16x32_bf16 v[126:129], v[148:151], v[200:203], v[126:129]
	v_mfma_f32_16x16x32_bf16 v[122:125], v[164:167], v[200:203], v[122:125]
	v_mfma_f32_16x16x32_bf16 v[118:121], v[148:151], v[208:211], v[118:121]
	v_mfma_f32_16x16x32_bf16 v[114:117], v[164:167], v[208:211], v[114:117]
	v_mfma_f32_16x16x32_bf16 v[108:111], v[148:151], v[216:219], v[108:111]
	v_mfma_f32_16x16x32_bf16 v[104:107], v[164:167], v[216:219], v[104:107]
	v_mfma_f32_16x16x32_bf16 v[100:103], v[148:151], v[224:227], v[100:103]
	v_mfma_f32_16x16x32_bf16 v[96:99], v[164:167], v[224:227], v[96:99]
	v_mfma_f32_16x16x32_bf16 v[126:129], v[152:155], v[204:207], v[126:129]
	v_mfma_f32_16x16x32_bf16 v[122:125], v[168:171], v[204:207], v[122:125]
	v_mfma_f32_16x16x32_bf16 v[118:121], v[152:155], v[212:215], v[118:121]
	v_mfma_f32_16x16x32_bf16 v[114:117], v[168:171], v[212:215], v[114:117]
	v_mfma_f32_16x16x32_bf16 v[108:111], v[152:155], v[220:223], v[108:111]
	v_mfma_f32_16x16x32_bf16 v[104:107], v[168:171], v[220:223], v[104:107]
	v_mfma_f32_16x16x32_bf16 v[100:103], v[152:155], v[228:231], v[100:103]
	v_mfma_f32_16x16x32_bf16 v[96:99], v[168:171], v[228:231], v[96:99]
	v_mfma_f32_16x16x32_bf16 v[92:95], v[172:175], v[200:203], v[92:95]
	v_mfma_f32_16x16x32_bf16 v[88:91], v[192:195], v[200:203], v[88:91]
	v_mfma_f32_16x16x32_bf16 v[84:87], v[172:175], v[208:211], v[84:87]
	v_mfma_f32_16x16x32_bf16 v[80:83], v[192:195], v[208:211], v[80:83]
	v_mfma_f32_16x16x32_bf16 v[68:71], v[172:175], v[216:219], v[68:71]
	v_mfma_f32_16x16x32_bf16 v[60:63], v[192:195], v[216:219], v[60:63]
	v_mfma_f32_16x16x32_bf16 v[56:59], v[172:175], v[224:227], v[56:59]
	v_mfma_f32_16x16x32_bf16 v[52:55], v[192:195], v[224:227], v[52:55]
	v_mfma_f32_16x16x32_bf16 v[92:95], v[176:179], v[204:207], v[92:95]
	v_mfma_f32_16x16x32_bf16 v[88:91], v[196:199], v[204:207], v[88:91]
	v_mfma_f32_16x16x32_bf16 v[84:87], v[176:179], v[212:215], v[84:87]
	v_mfma_f32_16x16x32_bf16 v[80:83], v[196:199], v[212:215], v[80:83]
	v_mfma_f32_16x16x32_bf16 v[68:71], v[176:179], v[220:223], v[68:71]
	v_mfma_f32_16x16x32_bf16 v[60:63], v[196:199], v[220:223], v[60:63]
	v_mfma_f32_16x16x32_bf16 v[56:59], v[176:179], v[228:231], v[56:59]
	v_mfma_f32_16x16x32_bf16 v[52:55], v[196:199], v[228:231], v[52:55]
	s_barrier
	v_lshl_add_u64 v[234:235], s[78:79], 0, v[134:135]
	s_add_i32 s7, s7, s30
	v_lshl_add_u64 v[236:237], v[234:235], 0, s[52:53]
	s_mov_b32 m0, s7
	ds_read_b128 v[200:203], v112 offset:16384
	ds_read_b128 v[204:207], v112 offset:17408
	ds_read_b128 v[208:211], v112 offset:18432
	ds_read_b128 v[212:215], v112 offset:19456
	ds_read_b128 v[216:219], v112 offset:20480
	ds_read_b128 v[220:223], v112 offset:21504
	ds_read_b128 v[224:227], v112 offset:22528
	ds_read_b128 v[228:231], v112 offset:23552
	global_load_lds_dwordx4 v[236:237], off
	v_lshl_add_u64 v[236:237], s[78:79], 0, v[136:137]
	v_lshl_add_u64 v[238:239], v[236:237], 0, s[52:53]
	s_add_i32 m0, s7, 0x2000
	s_add_i32 s7, s8, s30
	global_load_lds_dwordx4 v[238:239], off
	v_lshl_add_u64 v[238:239], v[234:235], 0, s[54:55]
	s_mov_b32 m0, s7
	s_nop 0
	global_load_lds_dwordx4 v[238:239], off
	v_lshl_add_u64 v[238:239], v[236:237], 0, s[54:55]
	s_add_i32 m0, s7, 0x2000
	s_nop 0
	global_load_lds_dwordx4 v[238:239], off
	v_lshl_add_u64 v[238:239], v[144:145], 0, s[82:83]
	s_mov_b32 m0, s31
	s_nop 0
	global_load_lds_dwordx4 v[238:239], off
	v_lshl_add_u64 v[238:239], v[232:233], 0, s[82:83]
	s_mov_b32 m0, s33
	s_nop 0
	global_load_lds_dwordx4 v[238:239], off
	s_waitcnt vmcnt(8)
	s_waitcnt lgkmcnt(0)
	s_barrier
	s_waitcnt lgkmcnt(0)
	v_mfma_f32_16x16x32_bf16 v[48:51], v[148:151], v[200:203], v[48:51]
	v_mfma_f32_16x16x32_bf16 v[44:47], v[164:167], v[200:203], v[44:47]
	v_mfma_f32_16x16x32_bf16 v[40:43], v[148:151], v[208:211], v[40:43]
	v_mfma_f32_16x16x32_bf16 v[36:39], v[164:167], v[208:211], v[36:39]
	v_mfma_f32_16x16x32_bf16 v[32:35], v[148:151], v[216:219], v[32:35]
	v_mfma_f32_16x16x32_bf16 v[28:31], v[164:167], v[216:219], v[28:31]
	v_mfma_f32_16x16x32_bf16 v[24:27], v[148:151], v[224:227], v[24:27]
	v_mfma_f32_16x16x32_bf16 v[20:23], v[164:167], v[224:227], v[20:23]
	v_mfma_f32_16x16x32_bf16 v[48:51], v[152:155], v[204:207], v[48:51]
	v_mfma_f32_16x16x32_bf16 v[44:47], v[168:171], v[204:207], v[44:47]
	v_mfma_f32_16x16x32_bf16 v[40:43], v[152:155], v[212:215], v[40:43]
	v_mfma_f32_16x16x32_bf16 v[36:39], v[168:171], v[212:215], v[36:39]
	v_mfma_f32_16x16x32_bf16 v[32:35], v[152:155], v[220:223], v[32:35]
	v_mfma_f32_16x16x32_bf16 v[28:31], v[168:171], v[220:223], v[28:31]
	v_mfma_f32_16x16x32_bf16 v[24:27], v[152:155], v[228:231], v[24:27]
	v_mfma_f32_16x16x32_bf16 v[20:23], v[168:171], v[228:231], v[20:23]
	v_mfma_f32_16x16x32_bf16 v[16:19], v[172:175], v[200:203], v[16:19]
	v_mfma_f32_16x16x32_bf16 v[12:15], v[192:195], v[200:203], v[12:15]
	v_mfma_f32_16x16x32_bf16 v[8:11], v[172:175], v[208:211], v[8:11]
	v_mfma_f32_16x16x32_bf16 v[4:7], v[192:195], v[208:211], v[4:7]
	v_mfma_f32_16x16x32_bf16 v[0:3], v[172:175], v[216:219], v[0:3]
	v_mfma_f32_16x16x32_bf16 v[64:67], v[192:195], v[216:219], v[64:67]
	v_mfma_f32_16x16x32_bf16 v[72:75], v[172:175], v[224:227], v[72:75]
	v_mfma_f32_16x16x32_bf16 v[76:79], v[192:195], v[224:227], v[76:79]
	v_mfma_f32_16x16x32_bf16 v[16:19], v[176:179], v[204:207], v[16:19]
	v_mfma_f32_16x16x32_bf16 v[12:15], v[196:199], v[204:207], v[12:15]
	v_mfma_f32_16x16x32_bf16 v[8:11], v[176:179], v[212:215], v[8:11]
	v_mfma_f32_16x16x32_bf16 v[4:7], v[196:199], v[212:215], v[4:7]
	v_mfma_f32_16x16x32_bf16 v[0:3], v[176:179], v[220:223], v[0:3]
	v_mfma_f32_16x16x32_bf16 v[64:67], v[196:199], v[220:223], v[64:67]
	v_mfma_f32_16x16x32_bf16 v[72:75], v[176:179], v[228:231], v[72:75]
	v_mfma_f32_16x16x32_bf16 v[76:79], v[196:199], v[228:231], v[76:79]
	s_barrier
	s_add_i32 s7, 0, 0x18000
	v_add_u32_e32 v143, s7, v142
	s_add_i32 s8, 0, 0x1c000
	ds_read_b128 v[148:151], v143
	ds_read_b128 v[152:155], v143 offset:1024
	ds_read_b128 v[164:167], v143 offset:2048
	ds_read_b128 v[168:171], v143 offset:3072
	v_add_u32_e32 v143, s8, v142
	ds_read_b128 v[172:175], v143
	ds_read_b128 v[176:179], v143 offset:1024
	ds_read_b128 v[192:195], v143 offset:2048
	ds_read_b128 v[196:199], v143 offset:3072
	s_mov_b32 m0, s38
	v_lshl_add_u64 v[238:239], v[144:145], 0, s[64:65]
	ds_read_b128 v[200:203], v112 offset:32768
	ds_read_b128 v[204:207], v112 offset:33792
	ds_read_b128 v[208:211], v112 offset:34816
	ds_read_b128 v[212:215], v112 offset:35840
	ds_read_b128 v[216:219], v112 offset:36864
	ds_read_b128 v[220:223], v112 offset:37888
	ds_read_b128 v[224:227], v112 offset:38912
	ds_read_b128 v[228:231], v112 offset:39936
	global_load_lds_dwordx4 v[238:239], off
	v_lshl_add_u64 v[238:239], v[232:233], 0, s[64:65]
	s_mov_b32 m0, s39
	s_nop 0
	global_load_lds_dwordx4 v[238:239], off
	s_waitcnt vmcnt(8)
	s_waitcnt lgkmcnt(0)
	s_barrier
	s_waitcnt lgkmcnt(0)
	v_mfma_f32_16x16x32_bf16 v[126:129], v[148:151], v[200:203], v[126:129]
	v_mfma_f32_16x16x32_bf16 v[122:125], v[164:167], v[200:203], v[122:125]
	v_mfma_f32_16x16x32_bf16 v[118:121], v[148:151], v[208:211], v[118:121]
	v_mfma_f32_16x16x32_bf16 v[114:117], v[164:167], v[208:211], v[114:117]
	v_mfma_f32_16x16x32_bf16 v[108:111], v[148:151], v[216:219], v[108:111]
	v_mfma_f32_16x16x32_bf16 v[104:107], v[164:167], v[216:219], v[104:107]
	v_mfma_f32_16x16x32_bf16 v[100:103], v[148:151], v[224:227], v[100:103]
	v_mfma_f32_16x16x32_bf16 v[96:99], v[164:167], v[224:227], v[96:99]
	v_mfma_f32_16x16x32_bf16 v[126:129], v[152:155], v[204:207], v[126:129]
	v_mfma_f32_16x16x32_bf16 v[122:125], v[168:171], v[204:207], v[122:125]
	v_mfma_f32_16x16x32_bf16 v[118:121], v[152:155], v[212:215], v[118:121]
	v_mfma_f32_16x16x32_bf16 v[114:117], v[168:171], v[212:215], v[114:117]
	v_mfma_f32_16x16x32_bf16 v[108:111], v[152:155], v[220:223], v[108:111]
	v_mfma_f32_16x16x32_bf16 v[104:107], v[168:171], v[220:223], v[104:107]
	v_mfma_f32_16x16x32_bf16 v[100:103], v[152:155], v[228:231], v[100:103]
	v_mfma_f32_16x16x32_bf16 v[96:99], v[168:171], v[228:231], v[96:99]
	v_mfma_f32_16x16x32_bf16 v[92:95], v[172:175], v[200:203], v[92:95]
	v_mfma_f32_16x16x32_bf16 v[88:91], v[192:195], v[200:203], v[88:91]
	v_mfma_f32_16x16x32_bf16 v[84:87], v[172:175], v[208:211], v[84:87]
	v_mfma_f32_16x16x32_bf16 v[80:83], v[192:195], v[208:211], v[80:83]
	v_mfma_f32_16x16x32_bf16 v[68:71], v[172:175], v[216:219], v[68:71]
	v_mfma_f32_16x16x32_bf16 v[60:63], v[192:195], v[216:219], v[60:63]
	v_mfma_f32_16x16x32_bf16 v[56:59], v[172:175], v[224:227], v[56:59]
	v_mfma_f32_16x16x32_bf16 v[52:55], v[192:195], v[224:227], v[52:55]
	v_mfma_f32_16x16x32_bf16 v[92:95], v[176:179], v[204:207], v[92:95]
	v_mfma_f32_16x16x32_bf16 v[88:91], v[196:199], v[204:207], v[88:91]
	v_mfma_f32_16x16x32_bf16 v[84:87], v[176:179], v[212:215], v[84:87]
	v_mfma_f32_16x16x32_bf16 v[80:83], v[196:199], v[212:215], v[80:83]
	v_mfma_f32_16x16x32_bf16 v[68:71], v[176:179], v[220:223], v[68:71]
	v_mfma_f32_16x16x32_bf16 v[60:63], v[196:199], v[220:223], v[60:63]
	v_mfma_f32_16x16x32_bf16 v[56:59], v[176:179], v[228:231], v[56:59]
	v_mfma_f32_16x16x32_bf16 v[52:55], v[196:199], v[228:231], v[52:55]
	s_barrier
	s_add_i32 s7, s7, s30
	v_lshl_add_u64 v[238:239], v[234:235], 0, s[56:57]
	s_mov_b32 m0, s7
	ds_read_b128 v[200:203], v112 offset:49152
	ds_read_b128 v[204:207], v112 offset:50176
	ds_read_b128 v[208:211], v112 offset:51200
	ds_read_b128 v[212:215], v112 offset:52224
	ds_read_b128 v[216:219], v112 offset:53248
	ds_read_b128 v[220:223], v112 offset:54272
	ds_read_b128 v[224:227], v112 offset:55296
	ds_read_b128 v[228:231], v112 offset:56320
	global_load_lds_dwordx4 v[238:239], off
	v_lshl_add_u64 v[238:239], v[236:237], 0, s[56:57]
	s_add_i32 m0, s7, 0x2000
	s_add_i32 s7, s8, s30
	global_load_lds_dwordx4 v[238:239], off
	v_lshl_add_u64 v[234:235], v[234:235], 0, s[58:59]
	s_mov_b32 m0, s7
	v_lshl_add_u64 v[144:145], v[144:145], 0, s[80:81]
	global_load_lds_dwordx4 v[234:235], off
	v_lshl_add_u64 v[234:235], v[236:237], 0, s[58:59]
	s_add_i32 m0, s7, 0x2000
	s_nop 0
	global_load_lds_dwordx4 v[234:235], off
	s_mov_b32 m0, s46
	s_nop 0
	global_load_lds_dwordx4 v[144:145], off
	v_lshl_add_u64 v[144:145], v[232:233], 0, s[80:81]
	s_mov_b32 m0, s47
	s_nop 0
	global_load_lds_dwordx4 v[144:145], off
	s_waitcnt vmcnt(8)
	s_waitcnt lgkmcnt(0)
	s_barrier
	s_waitcnt lgkmcnt(0)
	v_mfma_f32_16x16x32_bf16 v[48:51], v[148:151], v[200:203], v[48:51]
	v_mfma_f32_16x16x32_bf16 v[44:47], v[164:167], v[200:203], v[44:47]
	v_mfma_f32_16x16x32_bf16 v[40:43], v[148:151], v[208:211], v[40:43]
	v_mfma_f32_16x16x32_bf16 v[36:39], v[164:167], v[208:211], v[36:39]
	v_mfma_f32_16x16x32_bf16 v[32:35], v[148:151], v[216:219], v[32:35]
	v_mfma_f32_16x16x32_bf16 v[28:31], v[164:167], v[216:219], v[28:31]
	v_mfma_f32_16x16x32_bf16 v[24:27], v[148:151], v[224:227], v[24:27]
	v_mfma_f32_16x16x32_bf16 v[20:23], v[164:167], v[224:227], v[20:23]
	v_mfma_f32_16x16x32_bf16 v[48:51], v[152:155], v[204:207], v[48:51]
	v_mfma_f32_16x16x32_bf16 v[44:47], v[168:171], v[204:207], v[44:47]
	v_mfma_f32_16x16x32_bf16 v[40:43], v[152:155], v[212:215], v[40:43]
	v_mfma_f32_16x16x32_bf16 v[36:39], v[168:171], v[212:215], v[36:39]
	v_mfma_f32_16x16x32_bf16 v[32:35], v[152:155], v[220:223], v[32:35]
	v_mfma_f32_16x16x32_bf16 v[28:31], v[168:171], v[220:223], v[28:31]
	v_mfma_f32_16x16x32_bf16 v[24:27], v[152:155], v[228:231], v[24:27]
	v_mfma_f32_16x16x32_bf16 v[20:23], v[168:171], v[228:231], v[20:23]
	v_mfma_f32_16x16x32_bf16 v[16:19], v[172:175], v[200:203], v[16:19]
	v_mfma_f32_16x16x32_bf16 v[12:15], v[192:195], v[200:203], v[12:15]
	v_mfma_f32_16x16x32_bf16 v[8:11], v[172:175], v[208:211], v[8:11]
	v_mfma_f32_16x16x32_bf16 v[4:7], v[192:195], v[208:211], v[4:7]
	v_mfma_f32_16x16x32_bf16 v[0:3], v[172:175], v[216:219], v[0:3]
	v_mfma_f32_16x16x32_bf16 v[64:67], v[192:195], v[216:219], v[64:67]
	v_mfma_f32_16x16x32_bf16 v[72:75], v[172:175], v[224:227], v[72:75]
	v_mfma_f32_16x16x32_bf16 v[76:79], v[192:195], v[224:227], v[76:79]
	v_mfma_f32_16x16x32_bf16 v[16:19], v[176:179], v[204:207], v[16:19]
	v_mfma_f32_16x16x32_bf16 v[12:15], v[196:199], v[204:207], v[12:15]
	v_mfma_f32_16x16x32_bf16 v[8:11], v[176:179], v[212:215], v[8:11]
	v_mfma_f32_16x16x32_bf16 v[4:7], v[196:199], v[212:215], v[4:7]
	v_mfma_f32_16x16x32_bf16 v[0:3], v[176:179], v[220:223], v[0:3]
	v_mfma_f32_16x16x32_bf16 v[64:67], v[196:199], v[220:223], v[64:67]
	v_mfma_f32_16x16x32_bf16 v[72:75], v[176:179], v[228:231], v[72:75]
	v_mfma_f32_16x16x32_bf16 v[76:79], v[196:199], v[228:231], v[76:79]
	s_barrier
	s_add_i32 s4, s4, 2
	v_lshl_add_u64 v[134:135], v[134:135], 0, s[34:35]
	v_lshl_add_u64 v[136:137], v[136:137], 0, s[34:35]
	v_lshl_add_u64 v[138:139], v[138:139], 0, s[34:35]
	s_cmp_gt_u32 s4, 11
	v_lshl_add_u64 v[140:141], v[140:141], 0, s[34:35]
	s_cbranch_scc0 .LBB0_556
	v_add_u32_e32 v152, 0, v142
	v_add_u32_e32 v148, 0x10000, v152
	v_add_u32_e32 v153, 0x14000, v152
	ds_read_b128 v[134:137], v148
	ds_read_b128 v[138:141], v148 offset:1024
	ds_read_b128 v[142:145], v148 offset:2048
	ds_read_b128 v[148:151], v148 offset:3072
	ds_read_b128 v[164:167], v153
	ds_read_b128 v[168:171], v153 offset:1024
	ds_read_b128 v[172:175], v153 offset:2048
	ds_read_b128 v[176:179], v153 offset:3072
	s_add_u32 s2, s2, 0x40780
	s_addc_u32 s3, s3, 0
	s_mov_b32 m0, s6
	v_lshl_add_u64 v[130:131], s[2:3], 0, v[130:131]
	ds_read_b128 v[192:195], v112
	ds_read_b128 v[196:199], v112 offset:1024
	ds_read_b128 v[200:203], v112 offset:2048
	ds_read_b128 v[204:207], v112 offset:3072
	ds_read_b128 v[208:211], v112 offset:4096
	ds_read_b128 v[212:215], v112 offset:5120
	ds_read_b128 v[216:219], v112 offset:6144
	ds_read_b128 v[220:223], v112 offset:7168
	global_load_lds_dwordx4 v[130:131], off
	v_lshl_add_u64 v[130:131], s[2:3], 0, v[132:133]
	s_mov_b32 m0, s5
	s_nop 0
	global_load_lds_dwordx4 v[130:131], off
	s_waitcnt vmcnt(8)
	s_waitcnt lgkmcnt(0)
	s_barrier
	s_waitcnt lgkmcnt(0)
	v_mfma_f32_16x16x32_bf16 v[126:129], v[134:137], v[192:195], v[126:129]
	v_mfma_f32_16x16x32_bf16 v[122:125], v[142:145], v[192:195], v[122:125]
	v_mfma_f32_16x16x32_bf16 v[108:111], v[134:137], v[208:211], v[108:111]
	v_mfma_f32_16x16x32_bf16 v[104:107], v[142:145], v[208:211], v[104:107]
	v_mfma_f32_16x16x32_bf16 v[126:129], v[138:141], v[196:199], v[126:129]
	v_mfma_f32_16x16x32_bf16 v[130:133], v[148:151], v[196:199], v[122:125]
	v_mfma_f32_16x16x32_bf16 v[118:121], v[134:137], v[200:203], v[118:121]
	v_mfma_f32_16x16x32_bf16 v[114:117], v[142:145], v[200:203], v[114:117]
	v_mfma_f32_16x16x32_bf16 v[108:111], v[138:141], v[212:215], v[108:111]
	v_mfma_f32_16x16x32_bf16 v[104:107], v[148:151], v[212:215], v[104:107]
	v_mfma_f32_16x16x32_bf16 v[100:103], v[134:137], v[216:219], v[100:103]
	v_mfma_f32_16x16x32_bf16 v[96:99], v[142:145], v[216:219], v[96:99]
	v_mfma_f32_16x16x32_bf16 v[224:227], v[138:141], v[204:207], v[118:121]
	v_mfma_f32_16x16x32_bf16 v[228:231], v[148:151], v[204:207], v[114:117]
	v_mfma_f32_16x16x32_bf16 v[232:235], v[138:141], v[220:223], v[100:103]
	v_mfma_f32_16x16x32_bf16 v[236:239], v[148:151], v[220:223], v[96:99]
	v_mfma_f32_16x16x32_bf16 v[92:95], v[164:167], v[192:195], v[92:95]
	v_mfma_f32_16x16x32_bf16 v[88:91], v[172:175], v[192:195], v[88:91]
	v_mfma_f32_16x16x32_bf16 v[60:63], v[172:175], v[208:211], v[60:63]
	v_mfma_f32_16x16x32_bf16 v[56:59], v[164:167], v[216:219], v[56:59]
	v_mfma_f32_16x16x32_bf16 v[52:55], v[172:175], v[216:219], v[52:55]
	v_mfma_f32_16x16x32_bf16 v[92:95], v[168:171], v[196:199], v[92:95]
	v_mfma_f32_16x16x32_bf16 v[88:91], v[176:179], v[196:199], v[88:91]
	v_mfma_f32_16x16x32_bf16 v[84:87], v[164:167], v[200:203], v[84:87]
	v_mfma_f32_16x16x32_bf16 v[80:83], v[172:175], v[200:203], v[80:83]
	v_mfma_f32_16x16x32_bf16 v[68:71], v[164:167], v[208:211], v[68:71]
	v_mfma_f32_16x16x32_bf16 v[60:63], v[176:179], v[212:215], v[60:63]
	v_mfma_f32_16x16x32_bf16 v[56:59], v[168:171], v[220:223], v[56:59]
	v_mfma_f32_16x16x32_bf16 v[52:55], v[176:179], v[220:223], v[52:55]
	v_mfma_f32_16x16x32_bf16 v[192:195], v[168:171], v[204:207], v[84:87]
	v_mfma_f32_16x16x32_bf16 v[196:199], v[176:179], v[204:207], v[80:83]
	v_mfma_f32_16x16x32_bf16 v[200:203], v[168:171], v[212:215], v[68:71]
	s_barrier
	s_nop 0
	ds_read_b128 v[68:71], v112 offset:16384
	ds_read_b128 v[80:83], v112 offset:17408
	ds_read_b128 v[84:87], v112 offset:18432
	ds_read_b128 v[96:99], v112 offset:19456
	ds_read_b128 v[100:103], v112 offset:20480
	ds_read_b128 v[114:117], v112 offset:21504
	ds_read_b128 v[118:121], v112 offset:22528
	ds_read_b128 v[122:125], v112 offset:23552
	s_waitcnt vmcnt(2)
	s_waitcnt lgkmcnt(0)
	s_barrier
	s_waitcnt lgkmcnt(0)
	v_mfma_f32_16x16x32_bf16 v[48:51], v[134:137], v[68:71], v[48:51]
	v_mfma_f32_16x16x32_bf16 v[44:47], v[142:145], v[68:71], v[44:47]
	v_mfma_f32_16x16x32_bf16 v[40:43], v[134:137], v[84:87], v[40:43]
	v_mfma_f32_16x16x32_bf16 v[28:31], v[142:145], v[100:103], v[28:31]
	v_mfma_f32_16x16x32_bf16 v[24:27], v[134:137], v[118:121], v[24:27]
	v_mfma_f32_16x16x32_bf16 v[48:51], v[138:141], v[80:83], v[48:51]
	v_mfma_f32_16x16x32_bf16 v[44:47], v[148:151], v[80:83], v[44:47]
	v_mfma_f32_16x16x32_bf16 v[40:43], v[138:141], v[96:99], v[40:43]
	v_mfma_f32_16x16x32_bf16 v[36:39], v[142:145], v[84:87], v[36:39]
	v_mfma_f32_16x16x32_bf16 v[32:35], v[134:137], v[100:103], v[32:35]
	v_mfma_f32_16x16x32_bf16 v[28:31], v[148:151], v[114:117], v[28:31]
	v_mfma_f32_16x16x32_bf16 v[24:27], v[138:141], v[122:125], v[24:27]
	v_mfma_f32_16x16x32_bf16 v[20:23], v[142:145], v[118:121], v[20:23]
	v_mfma_f32_16x16x32_bf16 v[204:207], v[148:151], v[96:99], v[36:39]
	v_mfma_f32_16x16x32_bf16 v[208:211], v[138:141], v[114:117], v[32:35]
	v_mfma_f32_16x16x32_bf16 v[134:137], v[148:151], v[122:125], v[20:23]
	v_mfma_f32_16x16x32_bf16 v[0:3], v[164:167], v[100:103], v[0:3]
	v_mfma_f32_16x16x32_bf16 v[148:151], v[168:171], v[114:117], v[0:3]
	v_mfma_f32_16x16x32_bf16 v[0:3], v[172:175], v[100:103], v[64:67]
	v_mfma_f32_16x16x32_bf16 v[12:15], v[172:175], v[68:71], v[12:15]
	v_mfma_f32_16x16x32_bf16 v[8:11], v[164:167], v[84:87], v[8:11]
	v_mfma_f32_16x16x32_bf16 v[212:215], v[176:179], v[114:117], v[0:3]
	v_mfma_f32_16x16x32_bf16 v[0:3], v[164:167], v[118:121], v[72:75]
	v_mfma_f32_16x16x32_bf16 v[16:19], v[164:167], v[68:71], v[16:19]
	v_mfma_f32_16x16x32_bf16 v[12:15], v[176:179], v[80:83], v[12:15]
	v_mfma_f32_16x16x32_bf16 v[8:11], v[168:171], v[96:99], v[8:11]
	v_mfma_f32_16x16x32_bf16 v[4:7], v[172:175], v[84:87], v[4:7]
	v_mfma_f32_16x16x32_bf16 v[164:167], v[168:171], v[122:125], v[0:3]
	v_mfma_f32_16x16x32_bf16 v[0:3], v[172:175], v[118:121], v[76:79]
	v_mfma_f32_16x16x32_bf16 v[138:141], v[168:171], v[80:83], v[16:19]
	v_mfma_f32_16x16x32_bf16 v[142:145], v[176:179], v[96:99], v[4:7]
	v_mfma_f32_16x16x32_bf16 v[168:171], v[176:179], v[122:125], v[0:3]
	s_barrier
	v_add_u32_e32 v16, 0x18000, v152
	s_nop 1
	ds_read_b128 v[0:3], v16
	ds_read_b128 v[4:7], v16 offset:1024
	ds_read_b128 v[172:175], v16 offset:2048
	ds_read_b128 v[176:179], v16 offset:3072
	v_add_u32_e32 v16, 0x1c000, v152
	ds_read_b128 v[216:219], v16
	ds_read_b128 v[220:223], v16 offset:1024
	ds_read_b128 v[240:243], v16 offset:2048
	ds_read_b128 v[244:247], v16 offset:3072
	ds_read_b128 v[16:19], v112 offset:32768
	ds_read_b128 v[20:23], v112 offset:33792
	ds_read_b128 v[32:35], v112 offset:34816
	ds_read_b128 v[36:39], v112 offset:35840
	ds_read_b128 v[72:75], v112 offset:36864
	ds_read_b128 v[76:79], v112 offset:37888
	ds_read_b128 v[248:251], v112 offset:38912
	ds_read_b128 v[152:155], v112 offset:39936
	s_waitcnt vmcnt(0)
	s_waitcnt lgkmcnt(0)
	s_barrier
	s_waitcnt lgkmcnt(0)
	v_mfma_f32_16x16x32_bf16 v[64:67], v[0:3], v[16:19], v[126:129]
	v_mfma_f32_16x16x32_bf16 v[120:123], v[4:7], v[20:23], v[64:67]
	v_mfma_f32_16x16x32_bf16 v[64:67], v[172:175], v[16:19], v[130:133]
	v_mfma_f32_16x16x32_bf16 v[116:119], v[176:179], v[20:23], v[64:67]
	v_mfma_f32_16x16x32_bf16 v[64:67], v[0:3], v[32:35], v[224:227]
	v_mfma_f32_16x16x32_bf16 v[100:103], v[4:7], v[36:39], v[64:67]
	v_mfma_f32_16x16x32_bf16 v[64:67], v[172:175], v[32:35], v[228:231]
	v_mfma_f32_16x16x32_bf16 v[96:99], v[176:179], v[36:39], v[64:67]
	v_mfma_f32_16x16x32_bf16 v[64:67], v[0:3], v[72:75], v[108:111]
	v_mfma_f32_16x16x32_bf16 v[84:87], v[4:7], v[76:79], v[64:67]
	v_mfma_f32_16x16x32_bf16 v[64:67], v[172:175], v[72:75], v[104:107]
	v_mfma_f32_16x16x32_bf16 v[80:83], v[176:179], v[76:79], v[64:67]
	v_mfma_f32_16x16x32_bf16 v[64:67], v[0:3], v[248:251], v[232:235]
	v_mfma_f32_16x16x32_bf16 v[68:71], v[4:7], v[152:155], v[64:67]
	v_mfma_f32_16x16x32_bf16 v[64:67], v[172:175], v[248:251], v[236:239]
	v_mfma_f32_16x16x32_bf16 v[64:67], v[176:179], v[152:155], v[64:67]
	v_mfma_f32_16x16x32_bf16 v[92:95], v[216:219], v[16:19], v[92:95]
	v_mfma_f32_16x16x32_bf16 v[16:19], v[240:243], v[16:19], v[88:91]
	v_mfma_f32_16x16x32_bf16 v[124:127], v[244:247], v[20:23], v[16:19]
	v_mfma_f32_16x16x32_bf16 v[16:19], v[216:219], v[32:35], v[192:195]
	v_mfma_f32_16x16x32_bf16 v[108:111], v[220:223], v[36:39], v[16:19]
	v_mfma_f32_16x16x32_bf16 v[16:19], v[240:243], v[32:35], v[196:199]
	v_mfma_f32_16x16x32_bf16 v[104:107], v[244:247], v[36:39], v[16:19]
	v_mfma_f32_16x16x32_bf16 v[16:19], v[216:219], v[72:75], v[200:203]
	v_mfma_f32_16x16x32_bf16 v[128:131], v[220:223], v[20:23], v[92:95]
	v_mfma_f32_16x16x32_bf16 v[92:95], v[220:223], v[76:79], v[16:19]
	v_mfma_f32_16x16x32_bf16 v[16:19], v[240:243], v[72:75], v[60:63]
	v_mfma_f32_16x16x32_bf16 v[88:91], v[244:247], v[76:79], v[16:19]
	v_mfma_f32_16x16x32_bf16 v[16:19], v[216:219], v[248:251], v[56:59]
	v_mfma_f32_16x16x32_bf16 v[76:79], v[220:223], v[152:155], v[16:19]
	v_mfma_f32_16x16x32_bf16 v[16:19], v[240:243], v[248:251], v[52:55]
	v_mfma_f32_16x16x32_bf16 v[72:75], v[244:247], v[152:155], v[16:19]
	s_barrier
	ds_read_b128 v[56:59], v112 offset:49152
	ds_read_b128 v[152:155], v112 offset:50176
	ds_read_b128 v[192:195], v112 offset:51200
	ds_read_b128 v[196:199], v112 offset:52224
	ds_read_b128 v[200:203], v112 offset:53248
	ds_read_b128 v[224:227], v112 offset:54272
	ds_read_b128 v[228:231], v112 offset:55296
	ds_read_b128 v[232:235], v112 offset:56320
	s_waitcnt lgkmcnt(0)
	s_barrier
	s_waitcnt lgkmcnt(0)
	v_mfma_f32_16x16x32_bf16 v[16:19], v[0:3], v[56:59], v[48:51]
	v_mfma_f32_16x16x32_bf16 v[52:55], v[4:7], v[152:155], v[16:19]
	v_mfma_f32_16x16x32_bf16 v[16:19], v[172:175], v[56:59], v[44:47]
	v_mfma_f32_16x16x32_bf16 v[48:51], v[176:179], v[152:155], v[16:19]
	v_mfma_f32_16x16x32_bf16 v[16:19], v[0:3], v[192:195], v[40:43]
	v_mfma_f32_16x16x32_bf16 v[36:39], v[4:7], v[196:199], v[16:19]
	v_mfma_f32_16x16x32_bf16 v[16:19], v[172:175], v[192:195], v[204:207]
	v_mfma_f32_16x16x32_bf16 v[32:35], v[176:179], v[196:199], v[16:19]
	v_mfma_f32_16x16x32_bf16 v[16:19], v[0:3], v[200:203], v[208:211]
	v_mfma_f32_16x16x32_bf16 v[0:3], v[0:3], v[228:231], v[24:27]
	v_mfma_f32_16x16x32_bf16 v[20:23], v[4:7], v[224:227], v[16:19]
	v_mfma_f32_16x16x32_bf16 v[16:19], v[172:175], v[200:203], v[28:31]
	v_mfma_f32_16x16x32_bf16 v[4:7], v[4:7], v[232:235], v[0:3]
	v_mfma_f32_16x16x32_bf16 v[0:3], v[172:175], v[228:231], v[134:137]
	v_mfma_f32_16x16x32_bf16 v[16:19], v[176:179], v[224:227], v[16:19]
	v_mfma_f32_16x16x32_bf16 v[0:3], v[176:179], v[232:235], v[0:3]
	v_mfma_f32_16x16x32_bf16 v[8:11], v[216:219], v[192:195], v[8:11]
	v_mfma_f32_16x16x32_bf16 v[44:47], v[220:223], v[196:199], v[8:11]
	v_mfma_f32_16x16x32_bf16 v[8:11], v[240:243], v[192:195], v[142:145]
	v_mfma_f32_16x16x32_bf16 v[40:43], v[244:247], v[196:199], v[8:11]
	v_mfma_f32_16x16x32_bf16 v[8:11], v[216:219], v[200:203], v[148:151]
	v_mfma_f32_16x16x32_bf16 v[24:27], v[216:219], v[56:59], v[138:141]
	v_mfma_f32_16x16x32_bf16 v[28:31], v[220:223], v[224:227], v[8:11]
	v_mfma_f32_16x16x32_bf16 v[8:11], v[240:243], v[200:203], v[212:215]
	v_mfma_f32_16x16x32_bf16 v[60:63], v[220:223], v[152:155], v[24:27]
	v_mfma_f32_16x16x32_bf16 v[12:15], v[240:243], v[56:59], v[12:15]
	v_mfma_f32_16x16x32_bf16 v[24:27], v[244:247], v[224:227], v[8:11]
	v_mfma_f32_16x16x32_bf16 v[8:11], v[216:219], v[228:231], v[164:167]
	v_mfma_f32_16x16x32_bf16 v[56:59], v[244:247], v[152:155], v[12:15]
	v_mfma_f32_16x16x32_bf16 v[12:15], v[220:223], v[232:235], v[8:11]
	v_mfma_f32_16x16x32_bf16 v[8:11], v[240:243], v[228:231], v[168:171]
	v_mfma_f32_16x16x32_bf16 v[8:11], v[244:247], v[232:235], v[8:11]
	s_barrier
	s_waitcnt vmcnt(0)
	s_cmpk_lt_u32 s1, 0x100
	s_cbranch_scc0 .LBB0_559
	s_barrier

.LBB0_687:
	s_setprio 0
	s_getreg_b32 s2, hwreg(HW_REG_XCC_ID, 0, 4)
	s_waitcnt vmcnt(0)
	s_barrier
	s_mov_b64 s[0:1], exec
	v_readlane_b32 s4, v253, 14
	v_readlane_b32 s5, v253, 15
	s_and_b64 s[4:5], s[0:1], s[4:5]
	s_mov_b64 s[56:57], 0x1a8a9500
	s_mov_b64 exec, s[4:5]
	s_cbranch_execz .LBB0_739
	v_readlane_b32 s3, v252, 5
	s_waitcnt vmcnt(0) expcnt(0) lgkmcnt(0)
	s_and_b32 s8, s2, 15
	v_mov_b32_e32 v0, s3
	ds_read_b32 v2, v0
	v_readlane_b32 s3, v252, 6
	s_waitcnt lgkmcnt(0)
	v_cmp_ne_u32_e32 vcc, 0, v2
	v_mov_b32_e32 v0, s3
	ds_read_b32 v0, v0
	s_cbranch_vccnz .LBB0_703
	s_mov_b32 s9, 1
	s_branch .LBB0_691

.LBB0_811:
	s_or_b64 exec, exec, s[0:1]
	v_readlane_b32 s0, v252, 20
	v_readlane_b32 s1, v252, 21
	s_cmp_eq_u32 s0, 2
	s_cselect_b64 s[58:59], -1, 0
	s_cmp_lg_u32 s0, 2
	s_mov_b64 s[0:1], -1
	s_waitcnt lgkmcnt(0)
	s_barrier
	s_cselect_b32 s5, 1, 0
	v_readfirstlane_b32 s6, v180
	s_nop 1
	s_bitcmp1_b32 s6, 8
	s_cbranch_scc1 .Lmy_prio_3
	s_setprio 1
.Lmy_prio_3:
	s_cmp_lg_u32 s5, 0
	s_cbranch_scc0 .LBB0_967
	v_mov_b32_e32 v6, v180
	s_mov_b32 s0, s92
	s_mov_b32 s2, s95
	s_cmpk_lt_i32 s2, 0x214
	s_cselect_b64 s[0:1], -1, 0
	s_cmpk_gt_i32 s2, 0x213
	v_readfirstlane_b32 s6, v6
	s_cbranch_scc1 .LBB0_818
	s_ashr_i32 s3, s2, 31
	s_lshr_b32 s3, s3, 29
	s_add_i32 s4, s2, s3
	s_and_b32 s3, s4, -8
	s_sub_i32 s5, s2, s3
	s_cmp_gt_i32 s5, 3
	s_mov_b64 s[2:3], -1
	s_cbranch_scc0 .LBB0_815
	s_mul_i32 s2, s5, 0x42
	s_add_i32 s7, s2, 4
	s_mov_b64 s[2:3], 0

.LBB0_831:
	s_add_u32 s12, vcc_lo, 0xfffc0080
	s_addc_u32 s13, vcc_hi, -1
	s_add_i32 s24, 0, 0x10000
	s_cmp_eq_u32 s69, 12
	s_cselect_b32 s51, s5, s13
	s_cselect_b32 s50, s49, s12
	v_add_u32_e32 v112, s24, v192
	s_cselect_b32 s13, s39, s68
	s_cselect_b32 s12, s54, s55
	s_add_i32 s52, 0, 0x14000
	ds_read_b128 v[148:151], v112
	ds_read_b128 v[152:155], v112 offset:1024
	ds_read_b128 v[172:175], v112 offset:2048
	ds_read_b128 v[176:179], v112 offset:3072
	v_add_u32_e32 v112, s52, v192
	ds_read_b128 v[194:197], v112
	ds_read_b128 v[198:201], v112 offset:1024
	ds_read_b128 v[202:205], v112 offset:2048
	ds_read_b128 v[206:209], v112 offset:3072
	v_lshl_add_u64 v[242:243], vcc, 0, v[138:139]
	s_add_i32 m0, s14, 0xc000
	ds_read_b128 v[210:213], v193
	ds_read_b128 v[214:217], v193 offset:1024
	ds_read_b128 v[218:221], v193 offset:2048
	ds_read_b128 v[222:225], v193 offset:3072
	ds_read_b128 v[226:229], v193 offset:4096
	ds_read_b128 v[230:233], v193 offset:5120
	ds_read_b128 v[234:237], v193 offset:6144
	ds_read_b128 v[238:241], v193 offset:7168
	global_load_lds_dwordx4 v[242:243], off
	v_lshl_add_u64 v[242:243], vcc, 0, v[140:141]
	s_add_i32 m0, s14, 0xe000
	s_nop 0
	global_load_lds_dwordx4 v[242:243], off
	s_waitcnt vmcnt(8)
	s_waitcnt lgkmcnt(0)
	s_barrier
	s_waitcnt lgkmcnt(0)
	v_mfma_f32_16x16x32_bf16 v[126:129], v[148:151], v[210:213], v[126:129]
	v_mfma_f32_16x16x32_bf16 v[122:125], v[172:175], v[210:213], v[122:125]
	v_mfma_f32_16x16x32_bf16 v[108:111], v[148:151], v[218:221], v[108:111]
	v_mfma_f32_16x16x32_bf16 v[104:107], v[172:175], v[218:221], v[104:107]
	v_mfma_f32_16x16x32_bf16 v[92:95], v[148:151], v[226:229], v[92:95]
	v_mfma_f32_16x16x32_bf16 v[88:91], v[172:175], v[226:229], v[88:91]
	v_mfma_f32_16x16x32_bf16 v[76:79], v[148:151], v[234:237], v[76:79]
	v_mfma_f32_16x16x32_bf16 v[72:75], v[172:175], v[234:237], v[72:75]
	v_mfma_f32_16x16x32_bf16 v[126:129], v[152:155], v[214:217], v[126:129]
	v_mfma_f32_16x16x32_bf16 v[122:125], v[176:179], v[214:217], v[122:125]
	v_mfma_f32_16x16x32_bf16 v[108:111], v[152:155], v[222:225], v[108:111]
	v_mfma_f32_16x16x32_bf16 v[104:107], v[176:179], v[222:225], v[104:107]
	v_mfma_f32_16x16x32_bf16 v[92:95], v[152:155], v[230:233], v[92:95]
	v_mfma_f32_16x16x32_bf16 v[88:91], v[176:179], v[230:233], v[88:91]
	v_mfma_f32_16x16x32_bf16 v[76:79], v[152:155], v[238:241], v[76:79]
	v_mfma_f32_16x16x32_bf16 v[72:75], v[176:179], v[238:241], v[72:75]
	v_mfma_f32_16x16x32_bf16 v[118:121], v[194:197], v[210:213], v[118:121]
	v_mfma_f32_16x16x32_bf16 v[114:117], v[202:205], v[210:213], v[114:117]
	v_mfma_f32_16x16x32_bf16 v[100:103], v[194:197], v[218:221], v[100:103]
	v_mfma_f32_16x16x32_bf16 v[96:99], v[202:205], v[218:221], v[96:99]
	v_mfma_f32_16x16x32_bf16 v[84:87], v[194:197], v[226:229], v[84:87]
	v_mfma_f32_16x16x32_bf16 v[80:83], v[202:205], v[226:229], v[80:83]
	v_mfma_f32_16x16x32_bf16 v[68:71], v[194:197], v[234:237], v[68:71]
	v_mfma_f32_16x16x32_bf16 v[64:67], v[202:205], v[234:237], v[64:67]
	v_mfma_f32_16x16x32_bf16 v[118:121], v[198:201], v[214:217], v[118:121]
	v_mfma_f32_16x16x32_bf16 v[114:117], v[206:209], v[214:217], v[114:117]
	v_mfma_f32_16x16x32_bf16 v[100:103], v[198:201], v[222:225], v[100:103]
	v_mfma_f32_16x16x32_bf16 v[96:99], v[206:209], v[222:225], v[96:99]
	v_mfma_f32_16x16x32_bf16 v[84:87], v[198:201], v[230:233], v[84:87]
	v_mfma_f32_16x16x32_bf16 v[80:83], v[206:209], v[230:233], v[80:83]
	v_mfma_f32_16x16x32_bf16 v[68:71], v[198:201], v[238:241], v[68:71]
	v_mfma_f32_16x16x32_bf16 v[64:67], v[206:209], v[238:241], v[64:67]
	s_barrier
	s_add_i32 s24, s24, s10
	v_lshl_add_u64 v[242:243], s[12:13], 0, v[130:131]
	s_mov_b32 m0, s24
	ds_read_b128 v[210:213], v193 offset:16384
	ds_read_b128 v[214:217], v193 offset:17408
	ds_read_b128 v[218:221], v193 offset:18432
	ds_read_b128 v[222:225], v193 offset:19456
	ds_read_b128 v[226:229], v193 offset:20480
	ds_read_b128 v[230:233], v193 offset:21504
	ds_read_b128 v[234:237], v193 offset:22528
	ds_read_b128 v[238:241], v193 offset:23552
	global_load_lds_dwordx4 v[242:243], off
	s_add_i32 m0, s24, 0x2000
	s_add_u32 s24, s12, 0x40000
	v_lshl_add_u64 v[244:245], s[12:13], 0, v[132:133]
	s_addc_u32 s25, s13, 0
	s_add_i32 s52, s52, s10
	global_load_lds_dwordx4 v[244:245], off
	v_lshl_add_u64 v[246:247], s[24:25], 0, v[130:131]
	s_mov_b32 m0, s52
	v_lshl_add_u64 v[248:249], s[50:51], 0, v[132:133]
	global_load_lds_dwordx4 v[246:247], off
	v_lshl_add_u64 v[246:247], s[24:25], 0, v[132:133]
	s_add_i32 m0, s52, 0x2000
	s_nop 0
	global_load_lds_dwordx4 v[246:247], off
	v_lshl_add_u64 v[246:247], s[50:51], 0, v[130:131]
	s_mov_b32 m0, s14
	s_nop 0
	global_load_lds_dwordx4 v[246:247], off
	s_mov_b32 m0, s15
	s_nop 0
	global_load_lds_dwordx4 v[248:249], off
	s_waitcnt vmcnt(8)
	s_waitcnt lgkmcnt(0)
	s_barrier
	s_waitcnt lgkmcnt(0)
	v_mfma_f32_16x16x32_bf16 v[60:63], v[148:151], v[210:213], v[60:63]
	v_mfma_f32_16x16x32_bf16 v[56:59], v[172:175], v[210:213], v[56:59]
	v_mfma_f32_16x16x32_bf16 v[44:47], v[148:151], v[218:221], v[44:47]
	v_mfma_f32_16x16x32_bf16 v[40:43], v[172:175], v[218:221], v[40:43]
	v_mfma_f32_16x16x32_bf16 v[28:31], v[148:151], v[226:229], v[28:31]
	v_mfma_f32_16x16x32_bf16 v[24:27], v[172:175], v[226:229], v[24:27]
	v_mfma_f32_16x16x32_bf16 v[12:15], v[148:151], v[234:237], v[12:15]
	v_mfma_f32_16x16x32_bf16 v[8:11], v[172:175], v[234:237], v[8:11]
	v_mfma_f32_16x16x32_bf16 v[60:63], v[152:155], v[214:217], v[60:63]
	v_mfma_f32_16x16x32_bf16 v[56:59], v[176:179], v[214:217], v[56:59]
	v_mfma_f32_16x16x32_bf16 v[44:47], v[152:155], v[222:225], v[44:47]
	v_mfma_f32_16x16x32_bf16 v[40:43], v[176:179], v[222:225], v[40:43]
	v_mfma_f32_16x16x32_bf16 v[28:31], v[152:155], v[230:233], v[28:31]
	v_mfma_f32_16x16x32_bf16 v[24:27], v[176:179], v[230:233], v[24:27]
	v_mfma_f32_16x16x32_bf16 v[12:15], v[152:155], v[238:241], v[12:15]
	v_mfma_f32_16x16x32_bf16 v[8:11], v[176:179], v[238:241], v[8:11]
	v_mfma_f32_16x16x32_bf16 v[52:55], v[194:197], v[210:213], v[52:55]
	v_mfma_f32_16x16x32_bf16 v[48:51], v[202:205], v[210:213], v[48:51]
	v_mfma_f32_16x16x32_bf16 v[36:39], v[194:197], v[218:221], v[36:39]
	v_mfma_f32_16x16x32_bf16 v[32:35], v[202:205], v[218:221], v[32:35]
	v_mfma_f32_16x16x32_bf16 v[20:23], v[194:197], v[226:229], v[20:23]
	v_mfma_f32_16x16x32_bf16 v[16:19], v[202:205], v[226:229], v[16:19]
	v_mfma_f32_16x16x32_bf16 v[4:7], v[194:197], v[234:237], v[4:7]
	v_mfma_f32_16x16x32_bf16 v[0:3], v[202:205], v[234:237], v[0:3]
	v_mfma_f32_16x16x32_bf16 v[52:55], v[198:201], v[214:217], v[52:55]
	v_mfma_f32_16x16x32_bf16 v[48:51], v[206:209], v[214:217], v[48:51]
	v_mfma_f32_16x16x32_bf16 v[36:39], v[198:201], v[222:225], v[36:39]
	v_mfma_f32_16x16x32_bf16 v[32:35], v[206:209], v[222:225], v[32:35]
	v_mfma_f32_16x16x32_bf16 v[20:23], v[198:201], v[230:233], v[20:23]
	v_mfma_f32_16x16x32_bf16 v[16:19], v[206:209], v[230:233], v[16:19]
	v_mfma_f32_16x16x32_bf16 v[4:7], v[198:201], v[238:241], v[4:7]
	v_mfma_f32_16x16x32_bf16 v[0:3], v[206:209], v[238:241], v[0:3]
	s_barrier
	s_add_i32 s52, 0, 0x18000
	v_add_u32_e32 v112, s52, v192
	s_add_i32 s53, 0, 0x1c000
	ds_read_b128 v[148:151], v112
	ds_read_b128 v[152:155], v112 offset:1024
	ds_read_b128 v[172:175], v112 offset:2048
	ds_read_b128 v[176:179], v112 offset:3072
	v_add_u32_e32 v112, s53, v192
	ds_read_b128 v[194:197], v112
	ds_read_b128 v[198:201], v112 offset:1024
	ds_read_b128 v[202:205], v112 offset:2048
	ds_read_b128 v[206:209], v112 offset:3072
	s_add_u32 s24, s50, 0x40000
	s_addc_u32 s25, s51, 0
	s_mov_b32 m0, s30
	v_lshl_add_u64 v[250:251], s[24:25], 0, v[130:131]
	ds_read_b128 v[210:213], v193 offset:32768
	ds_read_b128 v[214:217], v193 offset:33792
	ds_read_b128 v[218:221], v193 offset:34816
	ds_read_b128 v[222:225], v193 offset:35840
	ds_read_b128 v[226:229], v193 offset:36864
	ds_read_b128 v[230:233], v193 offset:37888
	ds_read_b128 v[234:237], v193 offset:38912
	ds_read_b128 v[238:241], v193 offset:39936
	global_load_lds_dwordx4 v[250:251], off
	v_lshl_add_u64 v[250:251], s[24:25], 0, v[132:133]
	s_mov_b32 m0, s31
	s_nop 0
	global_load_lds_dwordx4 v[250:251], off
	s_waitcnt vmcnt(8)
	s_waitcnt lgkmcnt(0)
	s_barrier
	s_waitcnt lgkmcnt(0)
	v_mfma_f32_16x16x32_bf16 v[126:129], v[148:151], v[210:213], v[126:129]
	v_mfma_f32_16x16x32_bf16 v[122:125], v[172:175], v[210:213], v[122:125]
	v_mfma_f32_16x16x32_bf16 v[108:111], v[148:151], v[218:221], v[108:111]
	v_mfma_f32_16x16x32_bf16 v[104:107], v[172:175], v[218:221], v[104:107]
	v_mfma_f32_16x16x32_bf16 v[92:95], v[148:151], v[226:229], v[92:95]
	v_mfma_f32_16x16x32_bf16 v[88:91], v[172:175], v[226:229], v[88:91]
	v_mfma_f32_16x16x32_bf16 v[76:79], v[148:151], v[234:237], v[76:79]
	v_mfma_f32_16x16x32_bf16 v[72:75], v[172:175], v[234:237], v[72:75]
	v_mfma_f32_16x16x32_bf16 v[126:129], v[152:155], v[214:217], v[126:129]
	v_mfma_f32_16x16x32_bf16 v[122:125], v[176:179], v[214:217], v[122:125]
	v_mfma_f32_16x16x32_bf16 v[108:111], v[152:155], v[222:225], v[108:111]
	v_mfma_f32_16x16x32_bf16 v[104:107], v[176:179], v[222:225], v[104:107]
	v_mfma_f32_16x16x32_bf16 v[92:95], v[152:155], v[230:233], v[92:95]
	v_mfma_f32_16x16x32_bf16 v[88:91], v[176:179], v[230:233], v[88:91]
	v_mfma_f32_16x16x32_bf16 v[76:79], v[152:155], v[238:241], v[76:79]
	v_mfma_f32_16x16x32_bf16 v[72:75], v[176:179], v[238:241], v[72:75]
	v_mfma_f32_16x16x32_bf16 v[118:121], v[194:197], v[210:213], v[118:121]
	v_mfma_f32_16x16x32_bf16 v[114:117], v[202:205], v[210:213], v[114:117]
	v_mfma_f32_16x16x32_bf16 v[100:103], v[194:197], v[218:221], v[100:103]
	v_mfma_f32_16x16x32_bf16 v[96:99], v[202:205], v[218:221], v[96:99]
	v_mfma_f32_16x16x32_bf16 v[84:87], v[194:197], v[226:229], v[84:87]
	v_mfma_f32_16x16x32_bf16 v[80:83], v[202:205], v[226:229], v[80:83]
	v_mfma_f32_16x16x32_bf16 v[68:71], v[194:197], v[234:237], v[68:71]
	v_mfma_f32_16x16x32_bf16 v[64:67], v[202:205], v[234:237], v[64:67]
	v_mfma_f32_16x16x32_bf16 v[118:121], v[198:201], v[214:217], v[118:121]
	v_mfma_f32_16x16x32_bf16 v[114:117], v[206:209], v[214:217], v[114:117]
	v_mfma_f32_16x16x32_bf16 v[100:103], v[198:201], v[222:225], v[100:103]
	v_mfma_f32_16x16x32_bf16 v[96:99], v[206:209], v[222:225], v[96:99]
	v_mfma_f32_16x16x32_bf16 v[84:87], v[198:201], v[230:233], v[84:87]
	v_mfma_f32_16x16x32_bf16 v[80:83], v[206:209], v[230:233], v[80:83]
	v_mfma_f32_16x16x32_bf16 v[68:71], v[198:201], v[238:241], v[68:71]
	v_mfma_f32_16x16x32_bf16 v[64:67], v[206:209], v[238:241], v[64:67]
	s_barrier
	s_add_i32 s24, s52, s10
	v_lshl_add_u64 v[242:243], v[242:243], 0, s[36:37]
	s_mov_b32 m0, s24
	ds_read_b128 v[210:213], v193 offset:49152
	ds_read_b128 v[214:217], v193 offset:50176
	ds_read_b128 v[218:221], v193 offset:51200
	ds_read_b128 v[222:225], v193 offset:52224
	ds_read_b128 v[226:229], v193 offset:53248
	ds_read_b128 v[230:233], v193 offset:54272
	ds_read_b128 v[234:237], v193 offset:55296
	ds_read_b128 v[238:241], v193 offset:56320
	global_load_lds_dwordx4 v[242:243], off
	s_add_i32 m0, s24, 0x2000
	s_add_u32 s12, s12, 0x40080
	v_lshl_add_u64 v[242:243], v[244:245], 0, s[36:37]
	s_addc_u32 s13, s13, 0
	s_add_i32 s24, s53, s10
	global_load_lds_dwordx4 v[242:243], off
	v_lshl_add_u64 v[242:243], s[12:13], 0, v[130:131]
	s_mov_b32 m0, s24
	s_nop 0
	global_load_lds_dwordx4 v[242:243], off
	v_lshl_add_u64 v[242:243], s[12:13], 0, v[132:133]
	s_add_i32 m0, s24, 0x2000
	s_nop 0
	global_load_lds_dwordx4 v[242:243], off
	v_lshl_add_u64 v[242:243], v[246:247], 0, s[36:37]
	s_mov_b32 m0, s33
	s_nop 0
	global_load_lds_dwordx4 v[242:243], off
	v_lshl_add_u64 v[242:243], v[248:249], 0, s[36:37]
	s_mov_b32 m0, s46
	s_nop 0
	global_load_lds_dwordx4 v[242:243], off
	s_waitcnt vmcnt(8)
	s_waitcnt lgkmcnt(0)
	s_barrier
	s_waitcnt lgkmcnt(0)
	v_mfma_f32_16x16x32_bf16 v[60:63], v[148:151], v[210:213], v[60:63]
	v_mfma_f32_16x16x32_bf16 v[56:59], v[172:175], v[210:213], v[56:59]
	v_mfma_f32_16x16x32_bf16 v[44:47], v[148:151], v[218:221], v[44:47]
	v_mfma_f32_16x16x32_bf16 v[40:43], v[172:175], v[218:221], v[40:43]
	v_mfma_f32_16x16x32_bf16 v[28:31], v[148:151], v[226:229], v[28:31]
	v_mfma_f32_16x16x32_bf16 v[24:27], v[172:175], v[226:229], v[24:27]
	v_mfma_f32_16x16x32_bf16 v[12:15], v[148:151], v[234:237], v[12:15]
	v_mfma_f32_16x16x32_bf16 v[8:11], v[172:175], v[234:237], v[8:11]
	v_mfma_f32_16x16x32_bf16 v[60:63], v[152:155], v[214:217], v[60:63]
	v_mfma_f32_16x16x32_bf16 v[56:59], v[176:179], v[214:217], v[56:59]
	v_mfma_f32_16x16x32_bf16 v[44:47], v[152:155], v[222:225], v[44:47]
	v_mfma_f32_16x16x32_bf16 v[40:43], v[176:179], v[222:225], v[40:43]
	v_mfma_f32_16x16x32_bf16 v[28:31], v[152:155], v[230:233], v[28:31]
	v_mfma_f32_16x16x32_bf16 v[24:27], v[176:179], v[230:233], v[24:27]
	v_mfma_f32_16x16x32_bf16 v[12:15], v[152:155], v[238:241], v[12:15]
	v_mfma_f32_16x16x32_bf16 v[8:11], v[176:179], v[238:241], v[8:11]
	v_mfma_f32_16x16x32_bf16 v[52:55], v[194:197], v[210:213], v[52:55]
	v_mfma_f32_16x16x32_bf16 v[48:51], v[202:205], v[210:213], v[48:51]
	v_mfma_f32_16x16x32_bf16 v[36:39], v[194:197], v[218:221], v[36:39]
	v_mfma_f32_16x16x32_bf16 v[32:35], v[202:205], v[218:221], v[32:35]
	v_mfma_f32_16x16x32_bf16 v[20:23], v[194:197], v[226:229], v[20:23]
	v_mfma_f32_16x16x32_bf16 v[16:19], v[202:205], v[226:229], v[16:19]
	v_mfma_f32_16x16x32_bf16 v[4:7], v[194:197], v[234:237], v[4:7]
	v_mfma_f32_16x16x32_bf16 v[0:3], v[202:205], v[234:237], v[0:3]
	v_mfma_f32_16x16x32_bf16 v[52:55], v[198:201], v[214:217], v[52:55]
	v_mfma_f32_16x16x32_bf16 v[48:51], v[206:209], v[214:217], v[48:51]
	v_mfma_f32_16x16x32_bf16 v[36:39], v[198:201], v[222:225], v[36:39]
	v_mfma_f32_16x16x32_bf16 v[32:35], v[206:209], v[222:225], v[32:35]
	v_mfma_f32_16x16x32_bf16 v[20:23], v[198:201], v[230:233], v[20:23]
	v_mfma_f32_16x16x32_bf16 v[16:19], v[206:209], v[230:233], v[16:19]
	v_mfma_f32_16x16x32_bf16 v[4:7], v[198:201], v[238:241], v[4:7]
	v_mfma_f32_16x16x32_bf16 v[0:3], v[206:209], v[238:241], v[0:3]
	s_barrier
	s_add_i32 s69, s69, 2
	s_add_u32 vcc_lo, vcc_lo, 0x100
	s_addc_u32 vcc_hi, vcc_hi, 0
	s_add_u32 s55, s55, 0x100
	s_addc_u32 s68, s68, 0
	s_cmp_gt_u32 s69, 13
	s_cbranch_scc0 .LBB0_831
	s_and_b64 vcc, exec, s[8:9]
	s_cbranch_vccz .LBB0_834
	s_barrier

.LBB0_1122:
	s_setprio 0
	s_getreg_b32 s2, hwreg(HW_REG_XCC_ID, 0, 4)
	s_waitcnt vmcnt(0)
	s_waitcnt vmcnt(63) expcnt(7) lgkmcnt(15)
	s_barrier
	s_mov_b64 s[0:1], exec
	v_readlane_b32 s4, v253, 14
	v_readlane_b32 s5, v253, 15
	s_and_b64 s[4:5], s[0:1], s[4:5]
	s_mov_b64 exec, s[4:5]
	s_cbranch_execz .LBB0_1174
	v_readlane_b32 s3, v252, 5
	s_waitcnt vmcnt(0) expcnt(0) lgkmcnt(0)
	s_and_b32 s8, s2, 15
	v_mov_b32_e32 v0, s3
	ds_read_b32 v2, v0
	v_readlane_b32 s3, v252, 6
	s_waitcnt lgkmcnt(0)
	v_cmp_ne_u32_e32 vcc, 0, v2
	v_mov_b32_e32 v0, s3
	ds_read_b32 v0, v0
	s_cbranch_vccnz .LBB0_1138
	s_mov_b32 s9, 1
	s_branch .LBB0_1126

.LBB0_1462:
	s_or_b64 exec, exec, s[0:1]
	v_readlane_b32 s0, v252, 7
	s_mov_b32 s2, s0
	v_readlane_b32 s1, v252, 8
	v_writelane_b32 v252, s2, 7
	s_mov_b32 s1, s11
	s_lshl_b64 s[0:1], s[0:1], 21
	v_writelane_b32 v252, s3, 8
	v_readlane_b32 s4, v254, 3
	v_readlane_b32 s2, v252, 29
	v_readlane_b32 s3, v252, 30
	s_mov_b32 s3, s11
	s_lshl_b64 s[2:3], s[2:3], 21
	s_add_u32 s58, s4, s2
	v_readlane_b32 s2, v254, 4
	s_mov_b32 s33, s92
	s_waitcnt lgkmcnt(0)
	s_barrier
	s_cselect_b32 s5, 1, 0
	v_readfirstlane_b32 s6, v180
	s_nop 1
	s_bitcmp1_b32 s6, 8
	s_cbranch_scc1 .Lmy_prio_4
	s_setprio 1
.Lmy_prio_4:
	s_cmp_lg_u32 s5, 0
	s_addc_u32 s15, s2, s3
	s_abs_i32 s2, s33
	v_cvt_f32_u32_e32 v0, s2
	s_sub_i32 s5, 0, s2
	s_add_i32 s3, s33, 0x1ff
	s_xor_b32 s4, s3, s33
	v_rcp_iflag_f32_e32 v0, v0
	s_abs_i32 s3, s3
	s_ashr_i32 s4, s4, 31
	s_mov_b32 s46, 0
	v_mul_f32_e32 v0, 0x4f7ffffe, v0
	v_cvt_u32_f32_e32 v0, v0
	s_nop 0
	v_readfirstlane_b32 s6, v0
	s_mul_i32 s5, s5, s6
	s_mul_hi_u32 s5, s6, s5
	s_add_i32 s6, s6, s5
	s_mul_hi_u32 s5, s3, s6
	s_mul_i32 s6, s5, s2
	s_sub_i32 s3, s3, s6
	s_add_i32 s6, s5, 1
	s_sub_i32 s7, s3, s2
	s_cmp_ge_u32 s3, s2
	s_cselect_b32 s5, s6, s5
	s_cselect_b32 s3, s7, s3
	s_add_i32 s6, s5, 1
	s_cmp_ge_u32 s3, s2
	s_cselect_b32 s2, s6, s5
	s_xor_b32 s2, s2, s4
	s_sub_i32 s30, s2, s4
	s_add_u32 s31, s78, s0
	s_addc_u32 s47, s79, s1
	s_branch .LBB0_1464

.LBB0_1471:
	s_add_i32 s24, 0, 0x10000
	v_add_u32_e32 v143, s24, v142
	s_add_i32 s25, 0, 0x14000
	ds_read_b128 v[148:151], v143
	ds_read_b128 v[152:155], v143 offset:1024
	ds_read_b128 v[164:167], v143 offset:2048
	ds_read_b128 v[168:171], v143 offset:3072
	v_add_u32_e32 v143, s25, v142
	ds_read_b128 v[172:175], v143
	ds_read_b128 v[176:179], v143 offset:1024
	ds_read_b128 v[192:195], v143 offset:2048
	ds_read_b128 v[196:199], v143 offset:3072
	s_add_i32 s12, s12, 2
	v_lshl_add_u64 v[144:145], v[138:139], 0, s[6:7]
	s_add_i32 s38, s97, 0xc000
	v_lshl_add_u64 v[232:233], v[144:145], 0, s[72:73]
	s_mov_b32 m0, s38
	ds_read_b128 v[200:203], v112
	ds_read_b128 v[204:207], v112 offset:1024
	ds_read_b128 v[208:211], v112 offset:2048
	ds_read_b128 v[212:215], v112 offset:3072
	ds_read_b128 v[216:219], v112 offset:4096
	ds_read_b128 v[220:223], v112 offset:5120
	ds_read_b128 v[224:227], v112 offset:6144
	ds_read_b128 v[228:231], v112 offset:7168
	global_load_lds_dwordx4 v[232:233], off
	v_lshl_add_u64 v[232:233], v[140:141], 0, s[6:7]
	s_add_i32 s13, s97, 0xe000
	v_lshl_add_u64 v[234:235], v[232:233], 0, s[72:73]
	s_mov_b32 m0, s13
	s_nop 0
	global_load_lds_dwordx4 v[234:235], off
	s_waitcnt vmcnt(8)
	s_waitcnt lgkmcnt(0)
	s_barrier
	s_waitcnt lgkmcnt(0)
	v_mfma_f32_16x16x32_bf16 v[126:129], v[148:151], v[200:203], v[126:129]
	v_mfma_f32_16x16x32_bf16 v[122:125], v[164:167], v[200:203], v[122:125]
	v_mfma_f32_16x16x32_bf16 v[118:121], v[148:151], v[208:211], v[118:121]
	v_mfma_f32_16x16x32_bf16 v[114:117], v[164:167], v[208:211], v[114:117]
	v_mfma_f32_16x16x32_bf16 v[108:111], v[148:151], v[216:219], v[108:111]
	v_mfma_f32_16x16x32_bf16 v[104:107], v[164:167], v[216:219], v[104:107]
	v_mfma_f32_16x16x32_bf16 v[100:103], v[148:151], v[224:227], v[100:103]
	v_mfma_f32_16x16x32_bf16 v[96:99], v[164:167], v[224:227], v[96:99]
	v_mfma_f32_16x16x32_bf16 v[126:129], v[152:155], v[204:207], v[126:129]
	v_mfma_f32_16x16x32_bf16 v[122:125], v[168:171], v[204:207], v[122:125]
	v_mfma_f32_16x16x32_bf16 v[118:121], v[152:155], v[212:215], v[118:121]
	v_mfma_f32_16x16x32_bf16 v[114:117], v[168:171], v[212:215], v[114:117]
	v_mfma_f32_16x16x32_bf16 v[108:111], v[152:155], v[220:223], v[108:111]
	v_mfma_f32_16x16x32_bf16 v[104:107], v[168:171], v[220:223], v[104:107]
	v_mfma_f32_16x16x32_bf16 v[100:103], v[152:155], v[228:231], v[100:103]
	v_mfma_f32_16x16x32_bf16 v[96:99], v[168:171], v[228:231], v[96:99]
	v_mfma_f32_16x16x32_bf16 v[92:95], v[172:175], v[200:203], v[92:95]
	v_mfma_f32_16x16x32_bf16 v[88:91], v[192:195], v[200:203], v[88:91]
	v_mfma_f32_16x16x32_bf16 v[84:87], v[172:175], v[208:211], v[84:87]
	v_mfma_f32_16x16x32_bf16 v[80:83], v[192:195], v[208:211], v[80:83]
	v_mfma_f32_16x16x32_bf16 v[68:71], v[172:175], v[216:219], v[68:71]
	v_mfma_f32_16x16x32_bf16 v[60:63], v[192:195], v[216:219], v[60:63]
	v_mfma_f32_16x16x32_bf16 v[56:59], v[172:175], v[224:227], v[56:59]
	v_mfma_f32_16x16x32_bf16 v[52:55], v[192:195], v[224:227], v[52:55]
	v_mfma_f32_16x16x32_bf16 v[92:95], v[176:179], v[204:207], v[92:95]
	v_mfma_f32_16x16x32_bf16 v[88:91], v[196:199], v[204:207], v[88:91]
	v_mfma_f32_16x16x32_bf16 v[84:87], v[176:179], v[212:215], v[84:87]
	v_mfma_f32_16x16x32_bf16 v[80:83], v[196:199], v[212:215], v[80:83]
	v_mfma_f32_16x16x32_bf16 v[68:71], v[176:179], v[220:223], v[68:71]
	v_mfma_f32_16x16x32_bf16 v[60:63], v[196:199], v[220:223], v[60:63]
	v_mfma_f32_16x16x32_bf16 v[56:59], v[176:179], v[228:231], v[56:59]
	v_mfma_f32_16x16x32_bf16 v[52:55], v[196:199], v[228:231], v[52:55]
	s_barrier
	v_lshl_add_u64 v[234:235], v[134:135], 0, s[6:7]
	s_add_i32 s24, s24, s3
	v_lshl_add_u64 v[236:237], v[234:235], 0, s[56:57]
	s_mov_b32 m0, s24
	ds_read_b128 v[200:203], v112 offset:16384
	ds_read_b128 v[204:207], v112 offset:17408
	ds_read_b128 v[208:211], v112 offset:18432
	ds_read_b128 v[212:215], v112 offset:19456
	ds_read_b128 v[216:219], v112 offset:20480
	ds_read_b128 v[220:223], v112 offset:21504
	ds_read_b128 v[224:227], v112 offset:22528
	ds_read_b128 v[228:231], v112 offset:23552
	global_load_lds_dwordx4 v[236:237], off
	v_lshl_add_u64 v[236:237], v[136:137], 0, s[6:7]
	v_lshl_add_u64 v[238:239], v[236:237], 0, s[56:57]
	s_add_i32 m0, s24, 0x2000
	s_add_i32 s24, s25, s3
	global_load_lds_dwordx4 v[238:239], off
	v_lshl_add_u64 v[238:239], v[234:235], 0, s[84:85]
	s_mov_b32 m0, s24
	s_nop 0
	global_load_lds_dwordx4 v[238:239], off
	v_lshl_add_u64 v[238:239], v[236:237], 0, s[84:85]
	s_add_i32 m0, s24, 0x2000
	s_nop 0
	global_load_lds_dwordx4 v[238:239], off
	v_lshl_add_u64 v[238:239], v[144:145], 0, s[82:83]
	s_mov_b32 m0, s97
	s_nop 0
	global_load_lds_dwordx4 v[238:239], off
	v_lshl_add_u64 v[238:239], v[232:233], 0, s[82:83]
	s_mov_b32 m0, vcc_lo
	s_nop 0
	global_load_lds_dwordx4 v[238:239], off
	s_waitcnt vmcnt(8)
	s_waitcnt lgkmcnt(0)
	s_barrier
	s_waitcnt lgkmcnt(0)
	v_mfma_f32_16x16x32_bf16 v[48:51], v[148:151], v[200:203], v[48:51]
	v_mfma_f32_16x16x32_bf16 v[44:47], v[164:167], v[200:203], v[44:47]
	v_mfma_f32_16x16x32_bf16 v[40:43], v[148:151], v[208:211], v[40:43]
	v_mfma_f32_16x16x32_bf16 v[36:39], v[164:167], v[208:211], v[36:39]
	v_mfma_f32_16x16x32_bf16 v[32:35], v[148:151], v[216:219], v[32:35]
	v_mfma_f32_16x16x32_bf16 v[28:31], v[164:167], v[216:219], v[28:31]
	v_mfma_f32_16x16x32_bf16 v[24:27], v[148:151], v[224:227], v[24:27]
	v_mfma_f32_16x16x32_bf16 v[20:23], v[164:167], v[224:227], v[20:23]
	v_mfma_f32_16x16x32_bf16 v[48:51], v[152:155], v[204:207], v[48:51]
	v_mfma_f32_16x16x32_bf16 v[44:47], v[168:171], v[204:207], v[44:47]
	v_mfma_f32_16x16x32_bf16 v[40:43], v[152:155], v[212:215], v[40:43]
	v_mfma_f32_16x16x32_bf16 v[36:39], v[168:171], v[212:215], v[36:39]
	v_mfma_f32_16x16x32_bf16 v[32:35], v[152:155], v[220:223], v[32:35]
	v_mfma_f32_16x16x32_bf16 v[28:31], v[168:171], v[220:223], v[28:31]
	v_mfma_f32_16x16x32_bf16 v[24:27], v[152:155], v[228:231], v[24:27]
	v_mfma_f32_16x16x32_bf16 v[20:23], v[168:171], v[228:231], v[20:23]
	v_mfma_f32_16x16x32_bf16 v[16:19], v[172:175], v[200:203], v[16:19]
	v_mfma_f32_16x16x32_bf16 v[12:15], v[192:195], v[200:203], v[12:15]
	v_mfma_f32_16x16x32_bf16 v[8:11], v[172:175], v[208:211], v[8:11]
	v_mfma_f32_16x16x32_bf16 v[4:7], v[192:195], v[208:211], v[4:7]
	v_mfma_f32_16x16x32_bf16 v[0:3], v[172:175], v[216:219], v[0:3]
	v_mfma_f32_16x16x32_bf16 v[64:67], v[192:195], v[216:219], v[64:67]
	v_mfma_f32_16x16x32_bf16 v[72:75], v[172:175], v[224:227], v[72:75]
	v_mfma_f32_16x16x32_bf16 v[76:79], v[192:195], v[224:227], v[76:79]
	v_mfma_f32_16x16x32_bf16 v[16:19], v[176:179], v[204:207], v[16:19]
	v_mfma_f32_16x16x32_bf16 v[12:15], v[196:199], v[204:207], v[12:15]
	v_mfma_f32_16x16x32_bf16 v[8:11], v[176:179], v[212:215], v[8:11]
	v_mfma_f32_16x16x32_bf16 v[4:7], v[196:199], v[212:215], v[4:7]
	v_mfma_f32_16x16x32_bf16 v[0:3], v[176:179], v[220:223], v[0:3]
	v_mfma_f32_16x16x32_bf16 v[64:67], v[196:199], v[220:223], v[64:67]
	v_mfma_f32_16x16x32_bf16 v[72:75], v[176:179], v[228:231], v[72:75]
	v_mfma_f32_16x16x32_bf16 v[76:79], v[196:199], v[228:231], v[76:79]
	s_barrier
	s_add_i32 s24, 0, 0x18000
	v_add_u32_e32 v143, s24, v142
	s_add_i32 s25, 0, 0x1c000
	ds_read_b128 v[148:151], v143
	ds_read_b128 v[152:155], v143 offset:1024
	ds_read_b128 v[164:167], v143 offset:2048
	ds_read_b128 v[168:171], v143 offset:3072
	v_add_u32_e32 v143, s25, v142
	ds_read_b128 v[172:175], v143
	ds_read_b128 v[176:179], v143 offset:1024
	ds_read_b128 v[192:195], v143 offset:2048
	ds_read_b128 v[196:199], v143 offset:3072
	s_mov_b32 m0, vcc_hi
	v_lshl_add_u64 v[238:239], v[144:145], 0, s[64:65]
	ds_read_b128 v[200:203], v112 offset:32768
	ds_read_b128 v[204:207], v112 offset:33792
	ds_read_b128 v[208:211], v112 offset:34816
	ds_read_b128 v[212:215], v112 offset:35840
	ds_read_b128 v[216:219], v112 offset:36864
	ds_read_b128 v[220:223], v112 offset:37888
	ds_read_b128 v[224:227], v112 offset:38912
	ds_read_b128 v[228:231], v112 offset:39936
	global_load_lds_dwordx4 v[238:239], off
	v_lshl_add_u64 v[238:239], v[232:233], 0, s[64:65]
	s_mov_b32 m0, s14
	s_nop 0
	global_load_lds_dwordx4 v[238:239], off
	s_waitcnt vmcnt(8)
	s_waitcnt lgkmcnt(0)
	s_barrier
	s_waitcnt lgkmcnt(0)
	v_mfma_f32_16x16x32_bf16 v[126:129], v[148:151], v[200:203], v[126:129]
	v_mfma_f32_16x16x32_bf16 v[122:125], v[164:167], v[200:203], v[122:125]
	v_mfma_f32_16x16x32_bf16 v[118:121], v[148:151], v[208:211], v[118:121]
	v_mfma_f32_16x16x32_bf16 v[114:117], v[164:167], v[208:211], v[114:117]
	v_mfma_f32_16x16x32_bf16 v[108:111], v[148:151], v[216:219], v[108:111]
	v_mfma_f32_16x16x32_bf16 v[104:107], v[164:167], v[216:219], v[104:107]
	v_mfma_f32_16x16x32_bf16 v[100:103], v[148:151], v[224:227], v[100:103]
	v_mfma_f32_16x16x32_bf16 v[96:99], v[164:167], v[224:227], v[96:99]
	v_mfma_f32_16x16x32_bf16 v[126:129], v[152:155], v[204:207], v[126:129]
	v_mfma_f32_16x16x32_bf16 v[122:125], v[168:171], v[204:207], v[122:125]
	v_mfma_f32_16x16x32_bf16 v[118:121], v[152:155], v[212:215], v[118:121]
	v_mfma_f32_16x16x32_bf16 v[114:117], v[168:171], v[212:215], v[114:117]
	v_mfma_f32_16x16x32_bf16 v[108:111], v[152:155], v[220:223], v[108:111]
	v_mfma_f32_16x16x32_bf16 v[104:107], v[168:171], v[220:223], v[104:107]
	v_mfma_f32_16x16x32_bf16 v[100:103], v[152:155], v[228:231], v[100:103]
	v_mfma_f32_16x16x32_bf16 v[96:99], v[168:171], v[228:231], v[96:99]
	v_mfma_f32_16x16x32_bf16 v[92:95], v[172:175], v[200:203], v[92:95]
	v_mfma_f32_16x16x32_bf16 v[88:91], v[192:195], v[200:203], v[88:91]
	v_mfma_f32_16x16x32_bf16 v[84:87], v[172:175], v[208:211], v[84:87]
	v_mfma_f32_16x16x32_bf16 v[80:83], v[192:195], v[208:211], v[80:83]
	v_mfma_f32_16x16x32_bf16 v[68:71], v[172:175], v[216:219], v[68:71]
	v_mfma_f32_16x16x32_bf16 v[60:63], v[192:195], v[216:219], v[60:63]
	v_mfma_f32_16x16x32_bf16 v[56:59], v[172:175], v[224:227], v[56:59]
	v_mfma_f32_16x16x32_bf16 v[52:55], v[192:195], v[224:227], v[52:55]
	v_mfma_f32_16x16x32_bf16 v[92:95], v[176:179], v[204:207], v[92:95]
	v_mfma_f32_16x16x32_bf16 v[88:91], v[196:199], v[204:207], v[88:91]
	v_mfma_f32_16x16x32_bf16 v[84:87], v[176:179], v[212:215], v[84:87]
	v_mfma_f32_16x16x32_bf16 v[80:83], v[196:199], v[212:215], v[80:83]
	v_mfma_f32_16x16x32_bf16 v[68:71], v[176:179], v[220:223], v[68:71]
	v_mfma_f32_16x16x32_bf16 v[60:63], v[196:199], v[220:223], v[60:63]
	v_mfma_f32_16x16x32_bf16 v[56:59], v[176:179], v[228:231], v[56:59]
	v_mfma_f32_16x16x32_bf16 v[52:55], v[196:199], v[228:231], v[52:55]
	s_barrier
	s_add_i32 s24, s24, s3
	v_lshl_add_u64 v[238:239], v[234:235], 0, s[86:87]
	s_mov_b32 m0, s24
	ds_read_b128 v[200:203], v112 offset:49152
	ds_read_b128 v[204:207], v112 offset:50176
	ds_read_b128 v[208:211], v112 offset:51200
	ds_read_b128 v[212:215], v112 offset:52224
	ds_read_b128 v[216:219], v112 offset:53248
	ds_read_b128 v[220:223], v112 offset:54272
	ds_read_b128 v[224:227], v112 offset:55296
	ds_read_b128 v[228:231], v112 offset:56320
	global_load_lds_dwordx4 v[238:239], off
	v_lshl_add_u64 v[238:239], v[236:237], 0, s[86:87]
	s_add_i32 m0, s24, 0x2000
	s_add_i32 s24, s25, s3
	global_load_lds_dwordx4 v[238:239], off
	v_lshl_add_u64 v[234:235], v[234:235], 0, s[88:89]
	s_mov_b32 m0, s24
	v_lshl_add_u64 v[144:145], v[144:145], 0, s[80:81]
	global_load_lds_dwordx4 v[234:235], off
	v_lshl_add_u64 v[234:235], v[236:237], 0, s[88:89]
	s_add_i32 m0, s24, 0x2000
	s_nop 0
	global_load_lds_dwordx4 v[234:235], off
	s_mov_b32 m0, s54
	s_nop 0
	global_load_lds_dwordx4 v[144:145], off
	v_lshl_add_u64 v[144:145], v[232:233], 0, s[80:81]
	s_mov_b32 m0, s55
	s_nop 0
	global_load_lds_dwordx4 v[144:145], off
	s_waitcnt vmcnt(8)
	s_waitcnt lgkmcnt(0)
	s_barrier
	s_waitcnt lgkmcnt(0)
	v_mfma_f32_16x16x32_bf16 v[48:51], v[148:151], v[200:203], v[48:51]
	v_mfma_f32_16x16x32_bf16 v[44:47], v[164:167], v[200:203], v[44:47]
	v_mfma_f32_16x16x32_bf16 v[40:43], v[148:151], v[208:211], v[40:43]
	v_mfma_f32_16x16x32_bf16 v[36:39], v[164:167], v[208:211], v[36:39]
	v_mfma_f32_16x16x32_bf16 v[32:35], v[148:151], v[216:219], v[32:35]
	v_mfma_f32_16x16x32_bf16 v[28:31], v[164:167], v[216:219], v[28:31]
	v_mfma_f32_16x16x32_bf16 v[24:27], v[148:151], v[224:227], v[24:27]
	v_mfma_f32_16x16x32_bf16 v[20:23], v[164:167], v[224:227], v[20:23]
	v_mfma_f32_16x16x32_bf16 v[48:51], v[152:155], v[204:207], v[48:51]
	v_mfma_f32_16x16x32_bf16 v[44:47], v[168:171], v[204:207], v[44:47]
	v_mfma_f32_16x16x32_bf16 v[40:43], v[152:155], v[212:215], v[40:43]
	v_mfma_f32_16x16x32_bf16 v[36:39], v[168:171], v[212:215], v[36:39]
	v_mfma_f32_16x16x32_bf16 v[32:35], v[152:155], v[220:223], v[32:35]
	v_mfma_f32_16x16x32_bf16 v[28:31], v[168:171], v[220:223], v[28:31]
	v_mfma_f32_16x16x32_bf16 v[24:27], v[152:155], v[228:231], v[24:27]
	v_mfma_f32_16x16x32_bf16 v[20:23], v[168:171], v[228:231], v[20:23]
	v_mfma_f32_16x16x32_bf16 v[16:19], v[172:175], v[200:203], v[16:19]
	v_mfma_f32_16x16x32_bf16 v[12:15], v[192:195], v[200:203], v[12:15]
	v_mfma_f32_16x16x32_bf16 v[8:11], v[172:175], v[208:211], v[8:11]
	v_mfma_f32_16x16x32_bf16 v[4:7], v[192:195], v[208:211], v[4:7]
	v_mfma_f32_16x16x32_bf16 v[0:3], v[172:175], v[216:219], v[0:3]
	v_mfma_f32_16x16x32_bf16 v[64:67], v[192:195], v[216:219], v[64:67]
	v_mfma_f32_16x16x32_bf16 v[72:75], v[172:175], v[224:227], v[72:75]
	v_mfma_f32_16x16x32_bf16 v[76:79], v[192:195], v[224:227], v[76:79]
	v_mfma_f32_16x16x32_bf16 v[16:19], v[176:179], v[204:207], v[16:19]
	v_mfma_f32_16x16x32_bf16 v[12:15], v[196:199], v[204:207], v[12:15]
	v_mfma_f32_16x16x32_bf16 v[8:11], v[176:179], v[212:215], v[8:11]
	v_mfma_f32_16x16x32_bf16 v[4:7], v[196:199], v[212:215], v[4:7]
	v_mfma_f32_16x16x32_bf16 v[0:3], v[176:179], v[220:223], v[0:3]
	v_mfma_f32_16x16x32_bf16 v[64:67], v[196:199], v[220:223], v[64:67]
	v_mfma_f32_16x16x32_bf16 v[72:75], v[176:179], v[228:231], v[72:75]
	v_mfma_f32_16x16x32_bf16 v[76:79], v[196:199], v[228:231], v[76:79]
	s_barrier
	v_lshl_add_u64 v[134:135], v[134:135], 0, s[34:35]
	v_lshl_add_u64 v[136:137], v[136:137], 0, s[34:35]
	v_lshl_add_u64 v[138:139], v[138:139], 0, s[34:35]
	s_cmp_ge_u32 s12, s48
	v_lshl_add_u64 v[140:141], v[140:141], 0, s[34:35]
	s_cbranch_scc0 .LBB0_1471
	v_add_u32_e32 v228, 0, v142
	v_add_u32_e32 v148, 0x10000, v228
	v_add_u32_e32 v172, 0x14000, v228
	ds_read_b128 v[134:137], v148
	ds_read_b128 v[138:141], v148 offset:1024
	ds_read_b128 v[142:145], v148 offset:2048
	ds_read_b128 v[148:151], v148 offset:3072
	ds_read_b128 v[152:155], v172
	ds_read_b128 v[164:167], v172 offset:1024
	ds_read_b128 v[168:171], v172 offset:2048
	ds_read_b128 v[172:175], v172 offset:3072
	s_add_i32 s10, s10, -1
	s_lshl_b64 s[6:7], s[10:11], 7
	s_add_u32 s6, s8, s6
	s_addc_u32 s7, s9, s7
	s_mov_b32 m0, s38
	v_lshl_add_u64 v[130:131], s[6:7], 0, v[130:131]
	ds_read_b128 v[176:179], v112
	ds_read_b128 v[192:195], v112 offset:1024
	ds_read_b128 v[196:199], v112 offset:2048
	ds_read_b128 v[200:203], v112 offset:3072
	ds_read_b128 v[204:207], v112 offset:4096
	ds_read_b128 v[208:211], v112 offset:5120
	ds_read_b128 v[212:215], v112 offset:6144
	ds_read_b128 v[216:219], v112 offset:7168
	global_load_lds_dwordx4 v[130:131], off
	v_lshl_add_u64 v[130:131], s[6:7], 0, v[132:133]
	s_mov_b32 m0, s13
	s_nop 0
	global_load_lds_dwordx4 v[130:131], off
	s_waitcnt vmcnt(8)
	s_waitcnt lgkmcnt(0)
	s_barrier
	s_waitcnt lgkmcnt(0)
	v_mfma_f32_16x16x32_bf16 v[126:129], v[134:137], v[176:179], v[126:129]
	v_mfma_f32_16x16x32_bf16 v[122:125], v[142:145], v[176:179], v[122:125]
	v_mfma_f32_16x16x32_bf16 v[118:121], v[134:137], v[196:199], v[118:121]
	v_mfma_f32_16x16x32_bf16 v[114:117], v[142:145], v[196:199], v[114:117]
	v_mfma_f32_16x16x32_bf16 v[100:103], v[134:137], v[212:215], v[100:103]
	v_mfma_f32_16x16x32_bf16 v[96:99], v[142:145], v[212:215], v[96:99]
	v_mfma_f32_16x16x32_bf16 v[126:129], v[138:141], v[192:195], v[126:129]
	v_mfma_f32_16x16x32_bf16 v[122:125], v[148:151], v[192:195], v[122:125]
	v_mfma_f32_16x16x32_bf16 v[118:121], v[138:141], v[200:203], v[118:121]
	v_mfma_f32_16x16x32_bf16 v[114:117], v[148:151], v[200:203], v[114:117]
	v_mfma_f32_16x16x32_bf16 v[108:111], v[134:137], v[204:207], v[108:111]
	v_mfma_f32_16x16x32_bf16 v[104:107], v[142:145], v[204:207], v[104:107]
	v_mfma_f32_16x16x32_bf16 v[100:103], v[138:141], v[216:219], v[100:103]
	v_mfma_f32_16x16x32_bf16 v[96:99], v[148:151], v[216:219], v[96:99]
	v_mfma_f32_16x16x32_bf16 v[130:133], v[138:141], v[208:211], v[108:111]
	v_mfma_f32_16x16x32_bf16 v[220:223], v[148:151], v[208:211], v[104:107]
	v_mfma_f32_16x16x32_bf16 v[84:87], v[152:155], v[196:199], v[84:87]
	v_mfma_f32_16x16x32_bf16 v[80:83], v[168:171], v[196:199], v[80:83]
	v_mfma_f32_16x16x32_bf16 v[68:71], v[152:155], v[204:207], v[68:71]
	v_mfma_f32_16x16x32_bf16 v[60:63], v[168:171], v[204:207], v[60:63]
	v_mfma_f32_16x16x32_bf16 v[56:59], v[152:155], v[212:215], v[56:59]
	v_mfma_f32_16x16x32_bf16 v[52:55], v[168:171], v[212:215], v[52:55]
	v_mfma_f32_16x16x32_bf16 v[92:95], v[152:155], v[176:179], v[92:95]
	v_mfma_f32_16x16x32_bf16 v[88:91], v[168:171], v[176:179], v[88:91]
	v_mfma_f32_16x16x32_bf16 v[84:87], v[164:167], v[200:203], v[84:87]
	v_mfma_f32_16x16x32_bf16 v[80:83], v[172:175], v[200:203], v[80:83]
	v_mfma_f32_16x16x32_bf16 v[68:71], v[164:167], v[208:211], v[68:71]
	v_mfma_f32_16x16x32_bf16 v[60:63], v[172:175], v[208:211], v[60:63]
	v_mfma_f32_16x16x32_bf16 v[56:59], v[164:167], v[216:219], v[56:59]
	v_mfma_f32_16x16x32_bf16 v[52:55], v[172:175], v[216:219], v[52:55]
	v_mfma_f32_16x16x32_bf16 v[224:227], v[164:167], v[192:195], v[92:95]
	v_mfma_f32_16x16x32_bf16 v[176:179], v[172:175], v[192:195], v[88:91]
	s_barrier
	s_nop 0
	ds_read_b128 v[88:91], v112 offset:16384
	ds_read_b128 v[92:95], v112 offset:17408
	ds_read_b128 v[104:107], v112 offset:18432
	ds_read_b128 v[108:111], v112 offset:19456
	ds_read_b128 v[192:195], v112 offset:20480
	ds_read_b128 v[196:199], v112 offset:21504
	ds_read_b128 v[200:203], v112 offset:22528
	ds_read_b128 v[204:207], v112 offset:23552
	s_waitcnt vmcnt(2)
	s_waitcnt lgkmcnt(0)
	s_barrier
	s_waitcnt lgkmcnt(0)
	v_mfma_f32_16x16x32_bf16 v[48:51], v[134:137], v[88:91], v[48:51]
	v_mfma_f32_16x16x32_bf16 v[44:47], v[142:145], v[88:91], v[44:47]
	v_mfma_f32_16x16x32_bf16 v[40:43], v[134:137], v[104:107], v[40:43]
	v_mfma_f32_16x16x32_bf16 v[36:39], v[142:145], v[104:107], v[36:39]
	v_mfma_f32_16x16x32_bf16 v[32:35], v[134:137], v[192:195], v[32:35]
	v_mfma_f32_16x16x32_bf16 v[20:23], v[142:145], v[200:203], v[20:23]
	v_mfma_f32_16x16x32_bf16 v[48:51], v[138:141], v[92:95], v[48:51]
	v_mfma_f32_16x16x32_bf16 v[44:47], v[148:151], v[92:95], v[44:47]
	v_mfma_f32_16x16x32_bf16 v[40:43], v[138:141], v[108:111], v[40:43]
	v_mfma_f32_16x16x32_bf16 v[36:39], v[148:151], v[108:111], v[36:39]
	v_mfma_f32_16x16x32_bf16 v[32:35], v[138:141], v[196:199], v[32:35]
	v_mfma_f32_16x16x32_bf16 v[28:31], v[142:145], v[192:195], v[28:31]
	v_mfma_f32_16x16x32_bf16 v[24:27], v[134:137], v[200:203], v[24:27]
	v_mfma_f32_16x16x32_bf16 v[20:23], v[148:151], v[204:207], v[20:23]
	v_mfma_f32_16x16x32_bf16 v[208:211], v[148:151], v[196:199], v[28:31]
	v_mfma_f32_16x16x32_bf16 v[134:137], v[138:141], v[204:207], v[24:27]
	v_mfma_f32_16x16x32_bf16 v[8:11], v[152:155], v[104:107], v[8:11]
	v_mfma_f32_16x16x32_bf16 v[142:145], v[164:167], v[108:111], v[8:11]
	v_mfma_f32_16x16x32_bf16 v[8:11], v[168:171], v[192:195], v[64:67]
	v_mfma_f32_16x16x32_bf16 v[16:19], v[152:155], v[88:91], v[16:19]
	v_mfma_f32_16x16x32_bf16 v[4:7], v[168:171], v[104:107], v[4:7]
	v_mfma_f32_16x16x32_bf16 v[0:3], v[152:155], v[192:195], v[0:3]
	v_mfma_f32_16x16x32_bf16 v[148:151], v[172:175], v[196:199], v[8:11]
	v_mfma_f32_16x16x32_bf16 v[8:11], v[152:155], v[200:203], v[72:75]
	v_mfma_f32_16x16x32_bf16 v[16:19], v[164:167], v[92:95], v[16:19]
	v_mfma_f32_16x16x32_bf16 v[12:15], v[168:171], v[88:91], v[12:15]
	v_mfma_f32_16x16x32_bf16 v[4:7], v[172:175], v[108:111], v[4:7]
	v_mfma_f32_16x16x32_bf16 v[0:3], v[164:167], v[196:199], v[0:3]
	v_mfma_f32_16x16x32_bf16 v[152:155], v[164:167], v[204:207], v[8:11]
	v_mfma_f32_16x16x32_bf16 v[8:11], v[168:171], v[200:203], v[76:79]
	v_mfma_f32_16x16x32_bf16 v[138:141], v[172:175], v[92:95], v[12:15]
	v_mfma_f32_16x16x32_bf16 v[164:167], v[172:175], v[204:207], v[8:11]
	s_barrier
	v_add_u32_e32 v24, 0x18000, v228
	s_nop 2
	ds_read_b128 v[8:11], v24
	ds_read_b128 v[12:15], v24 offset:1024
	ds_read_b128 v[168:171], v24 offset:2048
	ds_read_b128 v[172:175], v24 offset:3072
	v_add_u32_e32 v24, 0x1c000, v228
	ds_read_b128 v[192:195], v24
	ds_read_b128 v[196:199], v24 offset:1024
	ds_read_b128 v[200:203], v24 offset:2048
	ds_read_b128 v[204:207], v24 offset:3072
	ds_read_b128 v[24:27], v112 offset:32768
	ds_read_b128 v[28:31], v112 offset:33792
	ds_read_b128 v[64:67], v112 offset:34816
	ds_read_b128 v[212:215], v112 offset:35840
	ds_read_b128 v[216:219], v112 offset:36864
	ds_read_b128 v[228:231], v112 offset:37888
	ds_read_b128 v[232:235], v112 offset:38912
	ds_read_b128 v[236:239], v112 offset:39936
	s_waitcnt vmcnt(0)
	s_waitcnt lgkmcnt(0)
	s_barrier
	s_waitcnt lgkmcnt(0)
	v_mfma_f32_16x16x32_bf16 v[72:75], v[8:11], v[24:27], v[126:129]
	v_mfma_f32_16x16x32_bf16 v[126:129], v[12:15], v[28:31], v[72:75]
	v_mfma_f32_16x16x32_bf16 v[72:75], v[168:171], v[24:27], v[122:125]
	v_mfma_f32_16x16x32_bf16 v[122:125], v[172:175], v[28:31], v[72:75]
	v_mfma_f32_16x16x32_bf16 v[72:75], v[8:11], v[64:67], v[118:121]
	v_mfma_f32_16x16x32_bf16 v[108:111], v[12:15], v[212:215], v[72:75]
	v_mfma_f32_16x16x32_bf16 v[72:75], v[168:171], v[64:67], v[114:117]
	v_mfma_f32_16x16x32_bf16 v[104:107], v[172:175], v[212:215], v[72:75]
	v_mfma_f32_16x16x32_bf16 v[72:75], v[8:11], v[216:219], v[130:133]
	v_mfma_f32_16x16x32_bf16 v[92:95], v[12:15], v[228:231], v[72:75]
	v_mfma_f32_16x16x32_bf16 v[72:75], v[168:171], v[216:219], v[220:223]
	v_mfma_f32_16x16x32_bf16 v[88:91], v[172:175], v[228:231], v[72:75]
	v_mfma_f32_16x16x32_bf16 v[72:75], v[8:11], v[232:235], v[100:103]
	v_mfma_f32_16x16x32_bf16 v[76:79], v[12:15], v[236:239], v[72:75]
	v_mfma_f32_16x16x32_bf16 v[72:75], v[168:171], v[232:235], v[96:99]
	v_mfma_f32_16x16x32_bf16 v[72:75], v[172:175], v[236:239], v[72:75]
	v_mfma_f32_16x16x32_bf16 v[96:99], v[192:195], v[24:27], v[224:227]
	v_mfma_f32_16x16x32_bf16 v[24:27], v[200:203], v[24:27], v[176:179]
	v_mfma_f32_16x16x32_bf16 v[114:117], v[204:207], v[28:31], v[24:27]
	v_mfma_f32_16x16x32_bf16 v[24:27], v[192:195], v[64:67], v[84:87]
	v_mfma_f32_16x16x32_bf16 v[100:103], v[196:199], v[212:215], v[24:27]
	v_mfma_f32_16x16x32_bf16 v[24:27], v[200:203], v[64:67], v[80:83]
	v_mfma_f32_16x16x32_bf16 v[118:121], v[196:199], v[28:31], v[96:99]
	v_mfma_f32_16x16x32_bf16 v[96:99], v[204:207], v[212:215], v[24:27]
	v_mfma_f32_16x16x32_bf16 v[24:27], v[192:195], v[216:219], v[68:71]
	v_mfma_f32_16x16x32_bf16 v[84:87], v[196:199], v[228:231], v[24:27]
	v_mfma_f32_16x16x32_bf16 v[24:27], v[200:203], v[216:219], v[60:63]
	v_mfma_f32_16x16x32_bf16 v[80:83], v[204:207], v[228:231], v[24:27]
	v_mfma_f32_16x16x32_bf16 v[24:27], v[192:195], v[232:235], v[56:59]
	v_mfma_f32_16x16x32_bf16 v[68:71], v[196:199], v[236:239], v[24:27]
	v_mfma_f32_16x16x32_bf16 v[24:27], v[200:203], v[232:235], v[52:55]
	v_mfma_f32_16x16x32_bf16 v[64:67], v[204:207], v[236:239], v[24:27]
	s_barrier
	ds_read_b128 v[130:133], v112 offset:49152
	ds_read_b128 v[176:179], v112 offset:50176
	ds_read_b128 v[212:215], v112 offset:51200
	ds_read_b128 v[216:219], v112 offset:52224
	ds_read_b128 v[220:223], v112 offset:53248
	ds_read_b128 v[224:227], v112 offset:54272
	ds_read_b128 v[228:231], v112 offset:55296
	ds_read_b128 v[232:235], v112 offset:56320
	s_waitcnt lgkmcnt(0)
	s_barrier
	s_waitcnt lgkmcnt(0)
	v_mfma_f32_16x16x32_bf16 v[24:27], v[8:11], v[130:133], v[48:51]
	v_mfma_f32_16x16x32_bf16 v[60:63], v[12:15], v[176:179], v[24:27]
	v_mfma_f32_16x16x32_bf16 v[24:27], v[168:171], v[130:133], v[44:47]
	v_mfma_f32_16x16x32_bf16 v[56:59], v[172:175], v[176:179], v[24:27]
	v_mfma_f32_16x16x32_bf16 v[24:27], v[8:11], v[212:215], v[40:43]
	v_mfma_f32_16x16x32_bf16 v[44:47], v[12:15], v[216:219], v[24:27]
	v_mfma_f32_16x16x32_bf16 v[24:27], v[168:171], v[212:215], v[36:39]
	v_mfma_f32_16x16x32_bf16 v[40:43], v[172:175], v[216:219], v[24:27]
	v_mfma_f32_16x16x32_bf16 v[24:27], v[8:11], v[220:223], v[32:35]
	v_mfma_f32_16x16x32_bf16 v[8:11], v[8:11], v[228:231], v[134:137]
	v_mfma_f32_16x16x32_bf16 v[28:31], v[12:15], v[224:227], v[24:27]
	v_mfma_f32_16x16x32_bf16 v[24:27], v[168:171], v[220:223], v[208:211]
	v_mfma_f32_16x16x32_bf16 v[12:15], v[12:15], v[232:235], v[8:11]
	v_mfma_f32_16x16x32_bf16 v[8:11], v[168:171], v[228:231], v[20:23]
	v_mfma_f32_16x16x32_bf16 v[24:27], v[172:175], v[224:227], v[24:27]
	v_mfma_f32_16x16x32_bf16 v[8:11], v[172:175], v[232:235], v[8:11]
	v_mfma_f32_16x16x32_bf16 v[16:19], v[192:195], v[130:133], v[16:19]
	v_mfma_f32_16x16x32_bf16 v[52:55], v[196:199], v[176:179], v[16:19]
	v_mfma_f32_16x16x32_bf16 v[16:19], v[200:203], v[130:133], v[138:141]
	v_mfma_f32_16x16x32_bf16 v[0:3], v[192:195], v[220:223], v[0:3]
	v_mfma_f32_16x16x32_bf16 v[48:51], v[204:207], v[176:179], v[16:19]
	v_mfma_f32_16x16x32_bf16 v[16:19], v[192:195], v[212:215], v[142:145]
	v_mfma_f32_16x16x32_bf16 v[20:23], v[196:199], v[224:227], v[0:3]
	v_mfma_f32_16x16x32_bf16 v[0:3], v[200:203], v[220:223], v[148:151]
	v_mfma_f32_16x16x32_bf16 v[36:39], v[196:199], v[216:219], v[16:19]
	v_mfma_f32_16x16x32_bf16 v[4:7], v[200:203], v[212:215], v[4:7]
	v_mfma_f32_16x16x32_bf16 v[16:19], v[204:207], v[224:227], v[0:3]
	v_mfma_f32_16x16x32_bf16 v[0:3], v[192:195], v[228:231], v[152:155]
	v_mfma_f32_16x16x32_bf16 v[32:35], v[204:207], v[216:219], v[4:7]
	v_mfma_f32_16x16x32_bf16 v[4:7], v[196:199], v[232:235], v[0:3]
	v_mfma_f32_16x16x32_bf16 v[0:3], v[200:203], v[228:231], v[164:167]
	v_mfma_f32_16x16x32_bf16 v[0:3], v[204:207], v[232:235], v[0:3]
	s_barrier
	s_waitcnt vmcnt(0)
	s_cmpk_lt_u32 s5, 0x100
	s_cbranch_scc0 .LBB0_1474
	s_barrier

.LBB0_1739:
	s_or_b64 exec, exec, s[0:1]
	v_mov_b32_e32 v10, v180
	s_mov_b32 s0, s92
	s_waitcnt lgkmcnt(0)
	s_barrier
	s_cselect_b32 s5, 1, 0
	v_readfirstlane_b32 s6, v180
	s_nop 1
	s_bitcmp1_b32 s6, 8
	s_cbranch_scc1 .Lmy_prio_5
	s_setprio 1
.Lmy_prio_5:
	s_cmp_lg_u32 s5, 0
	s_mov_b32 s0, s95
	s_cmpk_gt_i32 s0, 0xb6d
	v_readfirstlane_b32 s5, v10
	s_cbranch_scc1 .LBB0_1763
	s_ashr_i32 s1, s0, 31
	s_lshr_b32 s1, s1, 29
	s_add_i32 s3, s0, s1
	s_and_b32 s1, s3, -8
	s_sub_i32 s4, s0, s1
	s_cmp_gt_i32 s4, 5
	s_mov_b64 s[0:1], -1
	v_readlane_b32 s6, v252, 20
	v_readlane_b32 s7, v252, 21
	s_cbranch_scc0 .LBB0_1742
	s_mul_i32 s0, s4, 0x16d
	s_add_i32 s2, s0, 6
	s_mov_b64 s[0:1], 0

.LBB0_1756:
	s_add_u32 s12, vcc_lo, 0xfffc0080
	s_addc_u32 s13, vcc_hi, -1
	s_add_i32 s24, 0, 0x10000
	s_cmp_eq_u32 s94, 12
	s_cselect_b32 s51, s9, s13
	s_cselect_b32 s50, s54, s12
	v_add_u32_e32 v143, s24, v135
	s_cselect_b32 s13, s7, s69
	s_cselect_b32 s12, s55, s68
	s_add_i32 s52, 0, 0x14000
	ds_read_b128 v[148:151], v143
	ds_read_b128 v[152:155], v143 offset:1024
	ds_read_b128 v[174:177], v143 offset:2048
	ds_read_b128 v[192:195], v143 offset:3072
	v_add_u32_e32 v143, s52, v135
	ds_read_b128 v[196:199], v143
	ds_read_b128 v[200:203], v143 offset:1024
	ds_read_b128 v[204:207], v143 offset:2048
	ds_read_b128 v[208:211], v143 offset:3072
	v_lshl_add_u64 v[168:169], vcc, 0, v[136:137]
	s_add_i32 m0, s33, 0xc000
	ds_read_b128 v[212:215], v141
	ds_read_b128 v[216:219], v141 offset:1024
	ds_read_b128 v[220:223], v141 offset:2048
	ds_read_b128 v[224:227], v141 offset:3072
	ds_read_b128 v[228:231], v141 offset:4096
	ds_read_b128 v[232:235], v141 offset:5120
	ds_read_b128 v[236:239], v141 offset:6144
	ds_read_b128 v[240:243], v141 offset:7168
	global_load_lds_dwordx4 v[168:169], off
	v_lshl_add_u64 v[168:169], vcc, 0, v[138:139]
	s_add_i32 m0, s33, 0xe000
	s_nop 0
	global_load_lds_dwordx4 v[168:169], off
	s_waitcnt vmcnt(8)
	s_waitcnt lgkmcnt(0)
	s_barrier
	s_waitcnt lgkmcnt(0)
	v_mfma_f32_16x16x32_bf16 v[126:129], v[148:151], v[212:215], v[126:129]
	v_mfma_f32_16x16x32_bf16 v[118:121], v[174:177], v[212:215], v[118:121]
	v_mfma_f32_16x16x32_bf16 v[108:111], v[148:151], v[220:223], v[108:111]
	v_mfma_f32_16x16x32_bf16 v[100:103], v[174:177], v[220:223], v[100:103]
	v_mfma_f32_16x16x32_bf16 v[92:95], v[148:151], v[228:231], v[92:95]
	v_mfma_f32_16x16x32_bf16 v[84:87], v[174:177], v[228:231], v[84:87]
	v_mfma_f32_16x16x32_bf16 v[76:79], v[148:151], v[236:239], v[76:79]
	v_mfma_f32_16x16x32_bf16 v[68:71], v[174:177], v[236:239], v[68:71]
	v_mfma_f32_16x16x32_bf16 v[126:129], v[152:155], v[216:219], v[126:129]
	v_mfma_f32_16x16x32_bf16 v[118:121], v[192:195], v[216:219], v[118:121]
	v_mfma_f32_16x16x32_bf16 v[108:111], v[152:155], v[224:227], v[108:111]
	v_mfma_f32_16x16x32_bf16 v[100:103], v[192:195], v[224:227], v[100:103]
	v_mfma_f32_16x16x32_bf16 v[92:95], v[152:155], v[232:235], v[92:95]
	v_mfma_f32_16x16x32_bf16 v[84:87], v[192:195], v[232:235], v[84:87]
	v_mfma_f32_16x16x32_bf16 v[76:79], v[152:155], v[240:243], v[76:79]
	v_mfma_f32_16x16x32_bf16 v[68:71], v[192:195], v[240:243], v[68:71]
	v_mfma_f32_16x16x32_bf16 v[122:125], v[196:199], v[212:215], v[122:125]
	v_mfma_f32_16x16x32_bf16 v[114:117], v[204:207], v[212:215], v[114:117]
	v_mfma_f32_16x16x32_bf16 v[104:107], v[196:199], v[220:223], v[104:107]
	v_mfma_f32_16x16x32_bf16 v[96:99], v[204:207], v[220:223], v[96:99]
	v_mfma_f32_16x16x32_bf16 v[88:91], v[196:199], v[228:231], v[88:91]
	v_mfma_f32_16x16x32_bf16 v[80:83], v[204:207], v[228:231], v[80:83]
	v_mfma_f32_16x16x32_bf16 v[72:75], v[196:199], v[236:239], v[72:75]
	v_mfma_f32_16x16x32_bf16 v[64:67], v[204:207], v[236:239], v[64:67]
	v_mfma_f32_16x16x32_bf16 v[122:125], v[200:203], v[216:219], v[122:125]
	v_mfma_f32_16x16x32_bf16 v[114:117], v[208:211], v[216:219], v[114:117]
	v_mfma_f32_16x16x32_bf16 v[104:107], v[200:203], v[224:227], v[104:107]
	v_mfma_f32_16x16x32_bf16 v[96:99], v[208:211], v[224:227], v[96:99]
	v_mfma_f32_16x16x32_bf16 v[88:91], v[200:203], v[232:235], v[88:91]
	v_mfma_f32_16x16x32_bf16 v[80:83], v[208:211], v[232:235], v[80:83]
	v_mfma_f32_16x16x32_bf16 v[72:75], v[200:203], v[240:243], v[72:75]
	v_mfma_f32_16x16x32_bf16 v[64:67], v[208:211], v[240:243], v[64:67]
	s_barrier
	s_add_i32 s24, s24, s15
	v_lshl_add_u64 v[168:169], s[12:13], 0, v[112:113]
	s_mov_b32 m0, s24
	ds_read_b128 v[212:215], v141 offset:16384
	ds_read_b128 v[216:219], v141 offset:17408
	ds_read_b128 v[220:223], v141 offset:18432
	ds_read_b128 v[224:227], v141 offset:19456
	ds_read_b128 v[228:231], v141 offset:20480
	ds_read_b128 v[232:235], v141 offset:21504
	ds_read_b128 v[236:239], v141 offset:22528
	ds_read_b128 v[240:243], v141 offset:23552
	global_load_lds_dwordx4 v[168:169], off
	s_add_i32 m0, s24, 0x2000
	s_add_u32 s24, s12, 0x40000
	v_lshl_add_u64 v[178:179], s[12:13], 0, v[130:131]
	s_addc_u32 s25, s13, 0
	s_add_i32 s52, s52, s15
	global_load_lds_dwordx4 v[178:179], off
	v_lshl_add_u64 v[244:245], s[24:25], 0, v[112:113]
	s_mov_b32 m0, s52
	v_lshl_add_u64 v[246:247], s[50:51], 0, v[130:131]
	global_load_lds_dwordx4 v[244:245], off
	v_lshl_add_u64 v[244:245], s[24:25], 0, v[130:131]
	s_add_i32 m0, s52, 0x2000
	s_nop 0
	global_load_lds_dwordx4 v[244:245], off
	v_lshl_add_u64 v[244:245], s[50:51], 0, v[112:113]
	s_mov_b32 m0, s33
	s_nop 0
	global_load_lds_dwordx4 v[244:245], off
	s_mov_b32 m0, s46
	s_nop 0
	global_load_lds_dwordx4 v[246:247], off
	s_waitcnt vmcnt(8)
	s_waitcnt lgkmcnt(0)
	s_barrier
	s_waitcnt lgkmcnt(0)
	v_mfma_f32_16x16x32_bf16 v[60:63], v[148:151], v[212:215], v[60:63]
	v_mfma_f32_16x16x32_bf16 v[52:55], v[174:177], v[212:215], v[52:55]
	v_mfma_f32_16x16x32_bf16 v[44:47], v[148:151], v[220:223], v[44:47]
	v_mfma_f32_16x16x32_bf16 v[36:39], v[174:177], v[220:223], v[36:39]
	v_mfma_f32_16x16x32_bf16 v[28:31], v[148:151], v[228:231], v[28:31]
	v_mfma_f32_16x16x32_bf16 v[20:23], v[174:177], v[228:231], v[20:23]
	v_mfma_f32_16x16x32_bf16 v[12:15], v[148:151], v[236:239], v[12:15]
	v_mfma_f32_16x16x32_bf16 v[4:7], v[174:177], v[236:239], v[4:7]
	v_mfma_f32_16x16x32_bf16 v[60:63], v[152:155], v[216:219], v[60:63]
	v_mfma_f32_16x16x32_bf16 v[52:55], v[192:195], v[216:219], v[52:55]
	v_mfma_f32_16x16x32_bf16 v[44:47], v[152:155], v[224:227], v[44:47]
	v_mfma_f32_16x16x32_bf16 v[36:39], v[192:195], v[224:227], v[36:39]
	v_mfma_f32_16x16x32_bf16 v[28:31], v[152:155], v[232:235], v[28:31]
	v_mfma_f32_16x16x32_bf16 v[20:23], v[192:195], v[232:235], v[20:23]
	v_mfma_f32_16x16x32_bf16 v[12:15], v[152:155], v[240:243], v[12:15]
	v_mfma_f32_16x16x32_bf16 v[4:7], v[192:195], v[240:243], v[4:7]
	v_mfma_f32_16x16x32_bf16 v[56:59], v[196:199], v[212:215], v[56:59]
	v_mfma_f32_16x16x32_bf16 v[48:51], v[204:207], v[212:215], v[48:51]
	v_mfma_f32_16x16x32_bf16 v[40:43], v[196:199], v[220:223], v[40:43]
	v_mfma_f32_16x16x32_bf16 v[32:35], v[204:207], v[220:223], v[32:35]
	v_mfma_f32_16x16x32_bf16 v[24:27], v[196:199], v[228:231], v[24:27]
	v_mfma_f32_16x16x32_bf16 v[16:19], v[204:207], v[228:231], v[16:19]
	v_mfma_f32_16x16x32_bf16 v[8:11], v[196:199], v[236:239], v[8:11]
	v_mfma_f32_16x16x32_bf16 v[0:3], v[204:207], v[236:239], v[0:3]
	v_mfma_f32_16x16x32_bf16 v[56:59], v[200:203], v[216:219], v[56:59]
	v_mfma_f32_16x16x32_bf16 v[48:51], v[208:211], v[216:219], v[48:51]
	v_mfma_f32_16x16x32_bf16 v[40:43], v[200:203], v[224:227], v[40:43]
	v_mfma_f32_16x16x32_bf16 v[32:35], v[208:211], v[224:227], v[32:35]
	v_mfma_f32_16x16x32_bf16 v[24:27], v[200:203], v[232:235], v[24:27]
	v_mfma_f32_16x16x32_bf16 v[16:19], v[208:211], v[232:235], v[16:19]
	v_mfma_f32_16x16x32_bf16 v[8:11], v[200:203], v[240:243], v[8:11]
	v_mfma_f32_16x16x32_bf16 v[0:3], v[208:211], v[240:243], v[0:3]
	s_barrier
	s_add_i32 s52, 0, 0x18000
	v_add_u32_e32 v143, s52, v135
	s_add_i32 s53, 0, 0x1c000
	ds_read_b128 v[148:151], v143
	ds_read_b128 v[152:155], v143 offset:1024
	ds_read_b128 v[174:177], v143 offset:2048
	ds_read_b128 v[192:195], v143 offset:3072
	v_add_u32_e32 v143, s53, v135
	ds_read_b128 v[196:199], v143
	ds_read_b128 v[200:203], v143 offset:1024
	ds_read_b128 v[204:207], v143 offset:2048
	ds_read_b128 v[208:211], v143 offset:3072
	s_add_u32 s24, s50, 0x40000
	s_addc_u32 s25, s51, 0
	s_mov_b32 m0, s47
	v_lshl_add_u64 v[248:249], s[24:25], 0, v[112:113]
	ds_read_b128 v[212:215], v141 offset:32768
	ds_read_b128 v[216:219], v141 offset:33792
	ds_read_b128 v[220:223], v141 offset:34816
	ds_read_b128 v[224:227], v141 offset:35840
	ds_read_b128 v[228:231], v141 offset:36864
	ds_read_b128 v[232:235], v141 offset:37888
	ds_read_b128 v[236:239], v141 offset:38912
	ds_read_b128 v[240:243], v141 offset:39936
	global_load_lds_dwordx4 v[248:249], off
	v_lshl_add_u64 v[248:249], s[24:25], 0, v[130:131]
	s_mov_b32 m0, s97
	s_nop 0
	global_load_lds_dwordx4 v[248:249], off
	s_waitcnt vmcnt(8)
	s_waitcnt lgkmcnt(0)
	s_barrier
	s_waitcnt lgkmcnt(0)
	v_mfma_f32_16x16x32_bf16 v[126:129], v[148:151], v[212:215], v[126:129]
	v_mfma_f32_16x16x32_bf16 v[118:121], v[174:177], v[212:215], v[118:121]
	v_mfma_f32_16x16x32_bf16 v[108:111], v[148:151], v[220:223], v[108:111]
	v_mfma_f32_16x16x32_bf16 v[100:103], v[174:177], v[220:223], v[100:103]
	v_mfma_f32_16x16x32_bf16 v[92:95], v[148:151], v[228:231], v[92:95]
	v_mfma_f32_16x16x32_bf16 v[84:87], v[174:177], v[228:231], v[84:87]
	v_mfma_f32_16x16x32_bf16 v[76:79], v[148:151], v[236:239], v[76:79]
	v_mfma_f32_16x16x32_bf16 v[68:71], v[174:177], v[236:239], v[68:71]
	v_mfma_f32_16x16x32_bf16 v[126:129], v[152:155], v[216:219], v[126:129]
	v_mfma_f32_16x16x32_bf16 v[118:121], v[192:195], v[216:219], v[118:121]
	v_mfma_f32_16x16x32_bf16 v[108:111], v[152:155], v[224:227], v[108:111]
	v_mfma_f32_16x16x32_bf16 v[100:103], v[192:195], v[224:227], v[100:103]
	v_mfma_f32_16x16x32_bf16 v[92:95], v[152:155], v[232:235], v[92:95]
	v_mfma_f32_16x16x32_bf16 v[84:87], v[192:195], v[232:235], v[84:87]
	v_mfma_f32_16x16x32_bf16 v[76:79], v[152:155], v[240:243], v[76:79]
	v_mfma_f32_16x16x32_bf16 v[68:71], v[192:195], v[240:243], v[68:71]
	v_mfma_f32_16x16x32_bf16 v[122:125], v[196:199], v[212:215], v[122:125]
	v_mfma_f32_16x16x32_bf16 v[114:117], v[204:207], v[212:215], v[114:117]
	v_mfma_f32_16x16x32_bf16 v[104:107], v[196:199], v[220:223], v[104:107]
	v_mfma_f32_16x16x32_bf16 v[96:99], v[204:207], v[220:223], v[96:99]
	v_mfma_f32_16x16x32_bf16 v[88:91], v[196:199], v[228:231], v[88:91]
	v_mfma_f32_16x16x32_bf16 v[80:83], v[204:207], v[228:231], v[80:83]
	v_mfma_f32_16x16x32_bf16 v[72:75], v[196:199], v[236:239], v[72:75]
	v_mfma_f32_16x16x32_bf16 v[64:67], v[204:207], v[236:239], v[64:67]
	v_mfma_f32_16x16x32_bf16 v[122:125], v[200:203], v[216:219], v[122:125]
	v_mfma_f32_16x16x32_bf16 v[114:117], v[208:211], v[216:219], v[114:117]
	v_mfma_f32_16x16x32_bf16 v[104:107], v[200:203], v[224:227], v[104:107]
	v_mfma_f32_16x16x32_bf16 v[96:99], v[208:211], v[224:227], v[96:99]
	v_mfma_f32_16x16x32_bf16 v[88:91], v[200:203], v[232:235], v[88:91]
	v_mfma_f32_16x16x32_bf16 v[80:83], v[208:211], v[232:235], v[80:83]
	v_mfma_f32_16x16x32_bf16 v[72:75], v[200:203], v[240:243], v[72:75]
	v_mfma_f32_16x16x32_bf16 v[64:67], v[208:211], v[240:243], v[64:67]
	s_barrier
	s_add_i32 s24, s52, s15
	v_lshl_add_u64 v[168:169], v[168:169], 0, s[36:37]
	s_mov_b32 m0, s24
	ds_read_b128 v[212:215], v141 offset:49152
	ds_read_b128 v[216:219], v141 offset:50176
	ds_read_b128 v[220:223], v141 offset:51200
	ds_read_b128 v[224:227], v141 offset:52224
	ds_read_b128 v[228:231], v141 offset:53248
	ds_read_b128 v[232:235], v141 offset:54272
	ds_read_b128 v[236:239], v141 offset:55296
	ds_read_b128 v[240:243], v141 offset:56320
	global_load_lds_dwordx4 v[168:169], off
	s_add_i32 m0, s24, 0x2000
	s_add_u32 s12, s12, 0x40080
	v_lshl_add_u64 v[168:169], v[178:179], 0, s[36:37]
	s_addc_u32 s13, s13, 0
	s_add_i32 s24, s53, s15
	global_load_lds_dwordx4 v[168:169], off
	v_lshl_add_u64 v[168:169], s[12:13], 0, v[112:113]
	s_mov_b32 m0, s24
	s_nop 0
	global_load_lds_dwordx4 v[168:169], off
	v_lshl_add_u64 v[168:169], s[12:13], 0, v[130:131]
	s_add_i32 m0, s24, 0x2000
	s_nop 0
	global_load_lds_dwordx4 v[168:169], off
	v_lshl_add_u64 v[168:169], v[244:245], 0, s[36:37]
	s_mov_b32 m0, s0
	s_nop 0
	global_load_lds_dwordx4 v[168:169], off
	v_lshl_add_u64 v[168:169], v[246:247], 0, s[36:37]
	s_mov_b32 m0, s1
	s_nop 0
	global_load_lds_dwordx4 v[168:169], off
	s_waitcnt vmcnt(8)
	s_waitcnt lgkmcnt(0)
	s_barrier
	s_waitcnt lgkmcnt(0)
	v_mfma_f32_16x16x32_bf16 v[60:63], v[148:151], v[212:215], v[60:63]
	v_mfma_f32_16x16x32_bf16 v[52:55], v[174:177], v[212:215], v[52:55]
	v_mfma_f32_16x16x32_bf16 v[44:47], v[148:151], v[220:223], v[44:47]
	v_mfma_f32_16x16x32_bf16 v[36:39], v[174:177], v[220:223], v[36:39]
	v_mfma_f32_16x16x32_bf16 v[28:31], v[148:151], v[228:231], v[28:31]
	v_mfma_f32_16x16x32_bf16 v[20:23], v[174:177], v[228:231], v[20:23]
	v_mfma_f32_16x16x32_bf16 v[12:15], v[148:151], v[236:239], v[12:15]
	v_mfma_f32_16x16x32_bf16 v[4:7], v[174:177], v[236:239], v[4:7]
	v_mfma_f32_16x16x32_bf16 v[60:63], v[152:155], v[216:219], v[60:63]
	v_mfma_f32_16x16x32_bf16 v[52:55], v[192:195], v[216:219], v[52:55]
	v_mfma_f32_16x16x32_bf16 v[44:47], v[152:155], v[224:227], v[44:47]
	v_mfma_f32_16x16x32_bf16 v[36:39], v[192:195], v[224:227], v[36:39]
	v_mfma_f32_16x16x32_bf16 v[28:31], v[152:155], v[232:235], v[28:31]
	v_mfma_f32_16x16x32_bf16 v[20:23], v[192:195], v[232:235], v[20:23]
	v_mfma_f32_16x16x32_bf16 v[12:15], v[152:155], v[240:243], v[12:15]
	v_mfma_f32_16x16x32_bf16 v[4:7], v[192:195], v[240:243], v[4:7]
	v_mfma_f32_16x16x32_bf16 v[56:59], v[196:199], v[212:215], v[56:59]
	v_mfma_f32_16x16x32_bf16 v[48:51], v[204:207], v[212:215], v[48:51]
	v_mfma_f32_16x16x32_bf16 v[40:43], v[196:199], v[220:223], v[40:43]
	v_mfma_f32_16x16x32_bf16 v[32:35], v[204:207], v[220:223], v[32:35]
	v_mfma_f32_16x16x32_bf16 v[24:27], v[196:199], v[228:231], v[24:27]
	v_mfma_f32_16x16x32_bf16 v[16:19], v[204:207], v[228:231], v[16:19]
	v_mfma_f32_16x16x32_bf16 v[8:11], v[196:199], v[236:239], v[8:11]
	v_mfma_f32_16x16x32_bf16 v[0:3], v[204:207], v[236:239], v[0:3]
	v_mfma_f32_16x16x32_bf16 v[56:59], v[200:203], v[216:219], v[56:59]
	v_mfma_f32_16x16x32_bf16 v[48:51], v[208:211], v[216:219], v[48:51]
	v_mfma_f32_16x16x32_bf16 v[40:43], v[200:203], v[224:227], v[40:43]
	v_mfma_f32_16x16x32_bf16 v[32:35], v[208:211], v[224:227], v[32:35]
	v_mfma_f32_16x16x32_bf16 v[24:27], v[200:203], v[232:235], v[24:27]
	v_mfma_f32_16x16x32_bf16 v[16:19], v[208:211], v[232:235], v[16:19]
	v_mfma_f32_16x16x32_bf16 v[8:11], v[200:203], v[240:243], v[8:11]
	v_mfma_f32_16x16x32_bf16 v[0:3], v[208:211], v[240:243], v[0:3]
	s_barrier
	s_add_i32 s94, s94, 2
	s_add_u32 vcc_lo, vcc_lo, 0x100
	s_addc_u32 vcc_hi, vcc_hi, 0
	s_add_u32 s68, s68, 0x100
	s_addc_u32 s69, s69, 0
	s_cmp_gt_u32 s94, 13
	s_cbranch_scc0 .LBB0_1756
	v_readlane_b32 s66, v252, 15
	v_readlane_b32 s68, v252, 17
	s_and_b64 vcc, exec, s[4:5]
	v_readlane_b32 s67, v252, 16
	v_readlane_b32 s69, v252, 18
	s_mov_b32 s94, s60
	s_cbranch_vccz .LBB0_1759
	s_barrier

.LBB0_1763:
	s_setprio 0
	s_getreg_b32 s2, hwreg(HW_REG_XCC_ID, 0, 4)
	s_waitcnt vmcnt(0)
	s_barrier
	s_mov_b64 s[0:1], exec
	v_readlane_b32 s4, v253, 14
	v_readlane_b32 s5, v253, 15
	s_and_b64 s[4:5], s[0:1], s[4:5]
	s_mov_b64 exec, s[4:5]
	s_cbranch_execz .LBB0_1815
	v_readlane_b32 s3, v252, 5
	s_waitcnt vmcnt(0) expcnt(0) lgkmcnt(0)
	s_and_b32 s8, s2, 15
	v_mov_b32_e32 v0, s3
	ds_read_b32 v2, v0
	v_readlane_b32 s3, v252, 6
	s_waitcnt lgkmcnt(0)
	v_cmp_ne_u32_e32 vcc, 0, v2
	v_mov_b32_e32 v0, s3
	ds_read_b32 v0, v0
	s_cbranch_vccnz .LBB0_1779
	s_mov_b32 s9, 1
	s_branch .LBB0_1767

.LBB0_1815:
	s_or_b64 exec, exec, s[0:1]
	v_readlane_b32 s0, v252, 20
	v_readlane_b32 s1, v252, 21
	s_mov_b32 s4, s0
	s_mul_i32 s1, s4, 0x580000
	v_readlane_b32 s2, v254, 9
	s_mul_hi_u32 s0, s0, 0x580000
	s_add_u32 s12, s2, s1
	v_readlane_b32 s1, v254, 10
	s_addc_u32 s13, s1, s0
	s_cmp_lg_u32 s4, 3
	s_mov_b32 s38, s92
	s_waitcnt lgkmcnt(0)
	s_barrier
	s_cselect_b32 s5, 1, 0
	v_readfirstlane_b32 s6, v180
	s_nop 1
	s_bitcmp1_b32 s6, 8
	s_cbranch_scc1 .Lmy_prio_6
	s_setprio 1
.Lmy_prio_6:
	s_cmp_lg_u32 s5, 0
	s_cselect_b64 s[0:1], -1, 0
	s_abs_i32 s2, s38
	v_cvt_f32_u32_e32 v0, s2
	s_sub_i32 s5, 0, s2
	s_add_i32 s3, s38, 0x1ff
	s_xor_b32 s4, s3, s38
	v_rcp_iflag_f32_e32 v0, v0
	s_abs_i32 s3, s3
	s_ashr_i32 s4, s4, 31
	s_mov_b32 s39, 0
	v_mul_f32_e32 v0, 0x4f7ffffe, v0
	v_cvt_u32_f32_e32 v0, v0
	s_nop 0
	v_readfirstlane_b32 s6, v0
	s_mul_i32 s5, s5, s6
	s_mul_hi_u32 s5, s6, s5
	s_add_i32 s6, s6, s5
	s_mul_hi_u32 s5, s3, s6
	s_mul_i32 s6, s5, s2
	s_sub_i32 s3, s3, s6
	s_add_i32 s6, s5, 1
	s_sub_i32 s7, s3, s2
	s_cmp_ge_u32 s3, s2
	s_cselect_b32 s5, s6, s5
	s_cselect_b32 s3, s7, s3
	s_add_i32 s6, s5, 1
	s_cmp_ge_u32 s3, s2
	s_cselect_b32 s2, s6, s5
	s_xor_b32 s2, s2, s4
	s_sub_i32 s46, s2, s4
	s_branch .LBB0_1817

.LBB0_1824:
	s_add_i32 s24, 0, 0x10000
	v_add_u32_e32 v143, s24, v142
	s_add_i32 s25, 0, 0x14000
	ds_read_b128 v[148:151], v143
	ds_read_b128 v[152:155], v143 offset:1024
	ds_read_b128 v[164:167], v143 offset:2048
	ds_read_b128 v[168:171], v143 offset:3072
	v_add_u32_e32 v143, s25, v142
	ds_read_b128 v[172:175], v143
	ds_read_b128 v[176:179], v143 offset:1024
	ds_read_b128 v[192:195], v143 offset:2048
	ds_read_b128 v[196:199], v143 offset:3072
	s_add_i32 s6, s6, 2
	v_lshl_add_u64 v[144:145], s[78:79], 0, v[138:139]
	s_add_i32 s9, s49, 0xc000
	v_lshl_add_u64 v[232:233], v[144:145], 0, s[90:91]
	s_mov_b32 m0, s9
	ds_read_b128 v[200:203], v112
	ds_read_b128 v[204:207], v112 offset:1024
	ds_read_b128 v[208:211], v112 offset:2048
	ds_read_b128 v[212:215], v112 offset:3072
	ds_read_b128 v[216:219], v112 offset:4096
	ds_read_b128 v[220:223], v112 offset:5120
	ds_read_b128 v[224:227], v112 offset:6144
	ds_read_b128 v[228:231], v112 offset:7168
	global_load_lds_dwordx4 v[232:233], off
	v_lshl_add_u64 v[232:233], s[78:79], 0, v[140:141]
	s_add_i32 s7, s49, 0xe000
	v_lshl_add_u64 v[234:235], v[232:233], 0, s[90:91]
	s_mov_b32 m0, s7
	s_nop 0
	global_load_lds_dwordx4 v[234:235], off
	s_waitcnt vmcnt(8)
	s_waitcnt lgkmcnt(0)
	s_barrier
	s_waitcnt lgkmcnt(0)
	v_mfma_f32_16x16x32_bf16 v[126:129], v[148:151], v[200:203], v[126:129]
	v_mfma_f32_16x16x32_bf16 v[122:125], v[164:167], v[200:203], v[122:125]
	v_mfma_f32_16x16x32_bf16 v[118:121], v[148:151], v[208:211], v[118:121]
	v_mfma_f32_16x16x32_bf16 v[114:117], v[164:167], v[208:211], v[114:117]
	v_mfma_f32_16x16x32_bf16 v[108:111], v[148:151], v[216:219], v[108:111]
	v_mfma_f32_16x16x32_bf16 v[104:107], v[164:167], v[216:219], v[104:107]
	v_mfma_f32_16x16x32_bf16 v[100:103], v[148:151], v[224:227], v[100:103]
	v_mfma_f32_16x16x32_bf16 v[96:99], v[164:167], v[224:227], v[96:99]
	v_mfma_f32_16x16x32_bf16 v[126:129], v[152:155], v[204:207], v[126:129]
	v_mfma_f32_16x16x32_bf16 v[122:125], v[168:171], v[204:207], v[122:125]
	v_mfma_f32_16x16x32_bf16 v[118:121], v[152:155], v[212:215], v[118:121]
	v_mfma_f32_16x16x32_bf16 v[114:117], v[168:171], v[212:215], v[114:117]
	v_mfma_f32_16x16x32_bf16 v[108:111], v[152:155], v[220:223], v[108:111]
	v_mfma_f32_16x16x32_bf16 v[104:107], v[168:171], v[220:223], v[104:107]
	v_mfma_f32_16x16x32_bf16 v[100:103], v[152:155], v[228:231], v[100:103]
	v_mfma_f32_16x16x32_bf16 v[96:99], v[168:171], v[228:231], v[96:99]
	v_mfma_f32_16x16x32_bf16 v[92:95], v[172:175], v[200:203], v[92:95]
	v_mfma_f32_16x16x32_bf16 v[88:91], v[192:195], v[200:203], v[88:91]
	v_mfma_f32_16x16x32_bf16 v[84:87], v[172:175], v[208:211], v[84:87]
	v_mfma_f32_16x16x32_bf16 v[80:83], v[192:195], v[208:211], v[80:83]
	v_mfma_f32_16x16x32_bf16 v[68:71], v[172:175], v[216:219], v[68:71]
	v_mfma_f32_16x16x32_bf16 v[60:63], v[192:195], v[216:219], v[60:63]
	v_mfma_f32_16x16x32_bf16 v[56:59], v[172:175], v[224:227], v[56:59]
	v_mfma_f32_16x16x32_bf16 v[52:55], v[192:195], v[224:227], v[52:55]
	v_mfma_f32_16x16x32_bf16 v[92:95], v[176:179], v[204:207], v[92:95]
	v_mfma_f32_16x16x32_bf16 v[88:91], v[196:199], v[204:207], v[88:91]
	v_mfma_f32_16x16x32_bf16 v[84:87], v[176:179], v[212:215], v[84:87]
	v_mfma_f32_16x16x32_bf16 v[80:83], v[196:199], v[212:215], v[80:83]
	v_mfma_f32_16x16x32_bf16 v[68:71], v[176:179], v[220:223], v[68:71]
	v_mfma_f32_16x16x32_bf16 v[60:63], v[196:199], v[220:223], v[60:63]
	v_mfma_f32_16x16x32_bf16 v[56:59], v[176:179], v[228:231], v[56:59]
	v_mfma_f32_16x16x32_bf16 v[52:55], v[196:199], v[228:231], v[52:55]
	s_barrier
	v_lshl_add_u64 v[234:235], s[78:79], 0, v[134:135]
	s_add_i32 s24, s24, s48
	v_lshl_add_u64 v[236:237], v[234:235], 0, s[16:17]
	s_mov_b32 m0, s24
	ds_read_b128 v[200:203], v112 offset:16384
	ds_read_b128 v[204:207], v112 offset:17408
	ds_read_b128 v[208:211], v112 offset:18432
	ds_read_b128 v[212:215], v112 offset:19456
	ds_read_b128 v[216:219], v112 offset:20480
	ds_read_b128 v[220:223], v112 offset:21504
	ds_read_b128 v[224:227], v112 offset:22528
	ds_read_b128 v[228:231], v112 offset:23552
	global_load_lds_dwordx4 v[236:237], off
	v_lshl_add_u64 v[236:237], s[78:79], 0, v[136:137]
	v_lshl_add_u64 v[238:239], v[236:237], 0, s[16:17]
	s_add_i32 m0, s24, 0x2000
	s_add_i32 s24, s25, s48
	global_load_lds_dwordx4 v[238:239], off
	v_lshl_add_u64 v[238:239], v[234:235], 0, s[18:19]
	s_mov_b32 m0, s24
	s_nop 0
	global_load_lds_dwordx4 v[238:239], off
	v_lshl_add_u64 v[238:239], v[236:237], 0, s[18:19]
	s_add_i32 m0, s24, 0x2000
	s_nop 0
	global_load_lds_dwordx4 v[238:239], off
	v_lshl_add_u64 v[238:239], v[144:145], 0, s[70:71]
	s_mov_b32 m0, s49
	s_nop 0
	global_load_lds_dwordx4 v[238:239], off
	v_lshl_add_u64 v[238:239], v[232:233], 0, s[70:71]
	s_mov_b32 m0, s50
	s_nop 0
	global_load_lds_dwordx4 v[238:239], off
	s_waitcnt vmcnt(8)
	s_waitcnt lgkmcnt(0)
	s_barrier
	s_waitcnt lgkmcnt(0)
	v_mfma_f32_16x16x32_bf16 v[48:51], v[148:151], v[200:203], v[48:51]
	v_mfma_f32_16x16x32_bf16 v[44:47], v[164:167], v[200:203], v[44:47]
	v_mfma_f32_16x16x32_bf16 v[40:43], v[148:151], v[208:211], v[40:43]
	v_mfma_f32_16x16x32_bf16 v[36:39], v[164:167], v[208:211], v[36:39]
	v_mfma_f32_16x16x32_bf16 v[32:35], v[148:151], v[216:219], v[32:35]
	v_mfma_f32_16x16x32_bf16 v[28:31], v[164:167], v[216:219], v[28:31]
	v_mfma_f32_16x16x32_bf16 v[24:27], v[148:151], v[224:227], v[24:27]
	v_mfma_f32_16x16x32_bf16 v[20:23], v[164:167], v[224:227], v[20:23]
	v_mfma_f32_16x16x32_bf16 v[48:51], v[152:155], v[204:207], v[48:51]
	v_mfma_f32_16x16x32_bf16 v[44:47], v[168:171], v[204:207], v[44:47]
	v_mfma_f32_16x16x32_bf16 v[40:43], v[152:155], v[212:215], v[40:43]
	v_mfma_f32_16x16x32_bf16 v[36:39], v[168:171], v[212:215], v[36:39]
	v_mfma_f32_16x16x32_bf16 v[32:35], v[152:155], v[220:223], v[32:35]
	v_mfma_f32_16x16x32_bf16 v[28:31], v[168:171], v[220:223], v[28:31]
	v_mfma_f32_16x16x32_bf16 v[24:27], v[152:155], v[228:231], v[24:27]
	v_mfma_f32_16x16x32_bf16 v[20:23], v[168:171], v[228:231], v[20:23]
	v_mfma_f32_16x16x32_bf16 v[16:19], v[172:175], v[200:203], v[16:19]
	v_mfma_f32_16x16x32_bf16 v[12:15], v[192:195], v[200:203], v[12:15]
	v_mfma_f32_16x16x32_bf16 v[8:11], v[172:175], v[208:211], v[8:11]
	v_mfma_f32_16x16x32_bf16 v[4:7], v[192:195], v[208:211], v[4:7]
	v_mfma_f32_16x16x32_bf16 v[0:3], v[172:175], v[216:219], v[0:3]
	v_mfma_f32_16x16x32_bf16 v[64:67], v[192:195], v[216:219], v[64:67]
	v_mfma_f32_16x16x32_bf16 v[72:75], v[172:175], v[224:227], v[72:75]
	v_mfma_f32_16x16x32_bf16 v[76:79], v[192:195], v[224:227], v[76:79]
	v_mfma_f32_16x16x32_bf16 v[16:19], v[176:179], v[204:207], v[16:19]
	v_mfma_f32_16x16x32_bf16 v[12:15], v[196:199], v[204:207], v[12:15]
	v_mfma_f32_16x16x32_bf16 v[8:11], v[176:179], v[212:215], v[8:11]
	v_mfma_f32_16x16x32_bf16 v[4:7], v[196:199], v[212:215], v[4:7]
	v_mfma_f32_16x16x32_bf16 v[0:3], v[176:179], v[220:223], v[0:3]
	v_mfma_f32_16x16x32_bf16 v[64:67], v[196:199], v[220:223], v[64:67]
	v_mfma_f32_16x16x32_bf16 v[72:75], v[176:179], v[228:231], v[72:75]
	v_mfma_f32_16x16x32_bf16 v[76:79], v[196:199], v[228:231], v[76:79]
	s_barrier
	s_add_i32 s24, 0, 0x18000
	v_add_u32_e32 v143, s24, v142
	s_add_i32 s25, 0, 0x1c000
	ds_read_b128 v[148:151], v143
	ds_read_b128 v[152:155], v143 offset:1024
	ds_read_b128 v[164:167], v143 offset:2048
	ds_read_b128 v[168:171], v143 offset:3072
	v_add_u32_e32 v143, s25, v142
	ds_read_b128 v[172:175], v143
	ds_read_b128 v[176:179], v143 offset:1024
	ds_read_b128 v[192:195], v143 offset:2048
	ds_read_b128 v[196:199], v143 offset:3072
	s_mov_b32 m0, s51
	v_lshl_add_u64 v[238:239], v[144:145], 0, s[20:21]
	ds_read_b128 v[200:203], v112 offset:32768
	ds_read_b128 v[204:207], v112 offset:33792
	ds_read_b128 v[208:211], v112 offset:34816
	ds_read_b128 v[212:215], v112 offset:35840
	ds_read_b128 v[216:219], v112 offset:36864
	ds_read_b128 v[220:223], v112 offset:37888
	ds_read_b128 v[224:227], v112 offset:38912
	ds_read_b128 v[228:231], v112 offset:39936
	global_load_lds_dwordx4 v[238:239], off
	v_lshl_add_u64 v[238:239], v[232:233], 0, s[20:21]
	s_mov_b32 m0, s96
	s_nop 0
	global_load_lds_dwordx4 v[238:239], off
	s_waitcnt vmcnt(8)
	s_waitcnt lgkmcnt(0)
	s_barrier
	s_waitcnt lgkmcnt(0)
	v_mfma_f32_16x16x32_bf16 v[126:129], v[148:151], v[200:203], v[126:129]
	v_mfma_f32_16x16x32_bf16 v[122:125], v[164:167], v[200:203], v[122:125]
	v_mfma_f32_16x16x32_bf16 v[118:121], v[148:151], v[208:211], v[118:121]
	v_mfma_f32_16x16x32_bf16 v[114:117], v[164:167], v[208:211], v[114:117]
	v_mfma_f32_16x16x32_bf16 v[108:111], v[148:151], v[216:219], v[108:111]
	v_mfma_f32_16x16x32_bf16 v[104:107], v[164:167], v[216:219], v[104:107]
	v_mfma_f32_16x16x32_bf16 v[100:103], v[148:151], v[224:227], v[100:103]
	v_mfma_f32_16x16x32_bf16 v[96:99], v[164:167], v[224:227], v[96:99]
	v_mfma_f32_16x16x32_bf16 v[126:129], v[152:155], v[204:207], v[126:129]
	v_mfma_f32_16x16x32_bf16 v[122:125], v[168:171], v[204:207], v[122:125]
	v_mfma_f32_16x16x32_bf16 v[118:121], v[152:155], v[212:215], v[118:121]
	v_mfma_f32_16x16x32_bf16 v[114:117], v[168:171], v[212:215], v[114:117]
	v_mfma_f32_16x16x32_bf16 v[108:111], v[152:155], v[220:223], v[108:111]
	v_mfma_f32_16x16x32_bf16 v[104:107], v[168:171], v[220:223], v[104:107]
	v_mfma_f32_16x16x32_bf16 v[100:103], v[152:155], v[228:231], v[100:103]
	v_mfma_f32_16x16x32_bf16 v[96:99], v[168:171], v[228:231], v[96:99]
	v_mfma_f32_16x16x32_bf16 v[92:95], v[172:175], v[200:203], v[92:95]
	v_mfma_f32_16x16x32_bf16 v[88:91], v[192:195], v[200:203], v[88:91]
	v_mfma_f32_16x16x32_bf16 v[84:87], v[172:175], v[208:211], v[84:87]
	v_mfma_f32_16x16x32_bf16 v[80:83], v[192:195], v[208:211], v[80:83]
	v_mfma_f32_16x16x32_bf16 v[68:71], v[172:175], v[216:219], v[68:71]
	v_mfma_f32_16x16x32_bf16 v[60:63], v[192:195], v[216:219], v[60:63]
	v_mfma_f32_16x16x32_bf16 v[56:59], v[172:175], v[224:227], v[56:59]
	v_mfma_f32_16x16x32_bf16 v[52:55], v[192:195], v[224:227], v[52:55]
	v_mfma_f32_16x16x32_bf16 v[92:95], v[176:179], v[204:207], v[92:95]
	v_mfma_f32_16x16x32_bf16 v[88:91], v[196:199], v[204:207], v[88:91]
	v_mfma_f32_16x16x32_bf16 v[84:87], v[176:179], v[212:215], v[84:87]
	v_mfma_f32_16x16x32_bf16 v[80:83], v[196:199], v[212:215], v[80:83]
	v_mfma_f32_16x16x32_bf16 v[68:71], v[176:179], v[220:223], v[68:71]
	v_mfma_f32_16x16x32_bf16 v[60:63], v[196:199], v[220:223], v[60:63]
	v_mfma_f32_16x16x32_bf16 v[56:59], v[176:179], v[228:231], v[56:59]
	v_mfma_f32_16x16x32_bf16 v[52:55], v[196:199], v[228:231], v[52:55]
	s_barrier
	s_add_i32 s24, s24, s48
	v_lshl_add_u64 v[238:239], v[234:235], 0, s[22:23]
	s_mov_b32 m0, s24
	ds_read_b128 v[200:203], v112 offset:49152
	ds_read_b128 v[204:207], v112 offset:50176
	ds_read_b128 v[208:211], v112 offset:51200
	ds_read_b128 v[212:215], v112 offset:52224
	ds_read_b128 v[216:219], v112 offset:53248
	ds_read_b128 v[220:223], v112 offset:54272
	ds_read_b128 v[224:227], v112 offset:55296
	ds_read_b128 v[228:231], v112 offset:56320
	global_load_lds_dwordx4 v[238:239], off
	v_lshl_add_u64 v[238:239], v[236:237], 0, s[22:23]
	s_add_i32 m0, s24, 0x2000
	s_add_i32 s24, s25, s48
	global_load_lds_dwordx4 v[238:239], off
	v_lshl_add_u64 v[234:235], v[234:235], 0, s[28:29]
	s_mov_b32 m0, s24
	v_lshl_add_u64 v[144:145], v[144:145], 0, s[44:45]
	global_load_lds_dwordx4 v[234:235], off
	v_lshl_add_u64 v[234:235], v[236:237], 0, s[28:29]
	s_add_i32 m0, s24, 0x2000
	s_nop 0
	global_load_lds_dwordx4 v[234:235], off
	s_mov_b32 m0, s54
	s_nop 0
	global_load_lds_dwordx4 v[144:145], off
	v_lshl_add_u64 v[144:145], v[232:233], 0, s[44:45]
	s_mov_b32 m0, s55
	s_nop 0
	global_load_lds_dwordx4 v[144:145], off
	s_waitcnt vmcnt(8)
	s_waitcnt lgkmcnt(0)
	s_barrier
	s_waitcnt lgkmcnt(0)
	v_mfma_f32_16x16x32_bf16 v[48:51], v[148:151], v[200:203], v[48:51]
	v_mfma_f32_16x16x32_bf16 v[44:47], v[164:167], v[200:203], v[44:47]
	v_mfma_f32_16x16x32_bf16 v[40:43], v[148:151], v[208:211], v[40:43]
	v_mfma_f32_16x16x32_bf16 v[36:39], v[164:167], v[208:211], v[36:39]
	v_mfma_f32_16x16x32_bf16 v[32:35], v[148:151], v[216:219], v[32:35]
	v_mfma_f32_16x16x32_bf16 v[28:31], v[164:167], v[216:219], v[28:31]
	v_mfma_f32_16x16x32_bf16 v[24:27], v[148:151], v[224:227], v[24:27]
	v_mfma_f32_16x16x32_bf16 v[20:23], v[164:167], v[224:227], v[20:23]
	v_mfma_f32_16x16x32_bf16 v[48:51], v[152:155], v[204:207], v[48:51]
	v_mfma_f32_16x16x32_bf16 v[44:47], v[168:171], v[204:207], v[44:47]
	v_mfma_f32_16x16x32_bf16 v[40:43], v[152:155], v[212:215], v[40:43]
	v_mfma_f32_16x16x32_bf16 v[36:39], v[168:171], v[212:215], v[36:39]
	v_mfma_f32_16x16x32_bf16 v[32:35], v[152:155], v[220:223], v[32:35]
	v_mfma_f32_16x16x32_bf16 v[28:31], v[168:171], v[220:223], v[28:31]
	v_mfma_f32_16x16x32_bf16 v[24:27], v[152:155], v[228:231], v[24:27]
	v_mfma_f32_16x16x32_bf16 v[20:23], v[168:171], v[228:231], v[20:23]
	v_mfma_f32_16x16x32_bf16 v[16:19], v[172:175], v[200:203], v[16:19]
	v_mfma_f32_16x16x32_bf16 v[12:15], v[192:195], v[200:203], v[12:15]
	v_mfma_f32_16x16x32_bf16 v[8:11], v[172:175], v[208:211], v[8:11]
	v_mfma_f32_16x16x32_bf16 v[4:7], v[192:195], v[208:211], v[4:7]
	v_mfma_f32_16x16x32_bf16 v[0:3], v[172:175], v[216:219], v[0:3]
	v_mfma_f32_16x16x32_bf16 v[64:67], v[192:195], v[216:219], v[64:67]
	v_mfma_f32_16x16x32_bf16 v[72:75], v[172:175], v[224:227], v[72:75]
	v_mfma_f32_16x16x32_bf16 v[76:79], v[192:195], v[224:227], v[76:79]
	v_mfma_f32_16x16x32_bf16 v[16:19], v[176:179], v[204:207], v[16:19]
	v_mfma_f32_16x16x32_bf16 v[12:15], v[196:199], v[204:207], v[12:15]
	v_mfma_f32_16x16x32_bf16 v[8:11], v[176:179], v[212:215], v[8:11]
	v_mfma_f32_16x16x32_bf16 v[4:7], v[196:199], v[212:215], v[4:7]
	v_mfma_f32_16x16x32_bf16 v[0:3], v[176:179], v[220:223], v[0:3]
	v_mfma_f32_16x16x32_bf16 v[64:67], v[196:199], v[220:223], v[64:67]
	v_mfma_f32_16x16x32_bf16 v[72:75], v[176:179], v[228:231], v[72:75]
	v_mfma_f32_16x16x32_bf16 v[76:79], v[196:199], v[228:231], v[76:79]
	s_barrier
	v_lshl_add_u64 v[134:135], v[134:135], 0, s[34:35]
	v_lshl_add_u64 v[136:137], v[136:137], 0, s[34:35]
	v_lshl_add_u64 v[138:139], v[138:139], 0, s[34:35]
	s_cmp_ge_u32 s6, s8
	v_lshl_add_u64 v[140:141], v[140:141], 0, s[34:35]
	s_cbranch_scc0 .LBB0_1824
	v_add_u32_e32 v228, 0, v142
	v_add_u32_e32 v148, 0x10000, v228
	v_add_u32_e32 v172, 0x14000, v228
	ds_read_b128 v[134:137], v148
	ds_read_b128 v[138:141], v148 offset:1024
	ds_read_b128 v[142:145], v148 offset:2048
	ds_read_b128 v[148:151], v148 offset:3072
	ds_read_b128 v[152:155], v172
	ds_read_b128 v[164:167], v172 offset:1024
	ds_read_b128 v[168:171], v172 offset:2048
	ds_read_b128 v[172:175], v172 offset:3072
	s_add_i32 s10, s10, -1
	s_mov_b32 m0, s9
	s_lshl_b64 s[8:9], s[10:11], 7
	s_add_u32 s2, s2, s8
	s_addc_u32 s3, s3, s9
	v_lshl_add_u64 v[130:131], s[2:3], 0, v[130:131]
	ds_read_b128 v[176:179], v112
	ds_read_b128 v[192:195], v112 offset:1024
	ds_read_b128 v[196:199], v112 offset:2048
	ds_read_b128 v[200:203], v112 offset:3072
	ds_read_b128 v[204:207], v112 offset:4096
	ds_read_b128 v[208:211], v112 offset:5120
	ds_read_b128 v[212:215], v112 offset:6144
	ds_read_b128 v[216:219], v112 offset:7168
	global_load_lds_dwordx4 v[130:131], off
	v_lshl_add_u64 v[130:131], s[2:3], 0, v[132:133]
	s_mov_b32 m0, s7
	s_nop 0
	global_load_lds_dwordx4 v[130:131], off
	s_waitcnt vmcnt(8)
	s_waitcnt lgkmcnt(0)
	s_barrier
	s_waitcnt lgkmcnt(0)
	v_mfma_f32_16x16x32_bf16 v[126:129], v[134:137], v[176:179], v[126:129]
	v_mfma_f32_16x16x32_bf16 v[122:125], v[142:145], v[176:179], v[122:125]
	v_mfma_f32_16x16x32_bf16 v[118:121], v[134:137], v[196:199], v[118:121]
	v_mfma_f32_16x16x32_bf16 v[114:117], v[142:145], v[196:199], v[114:117]
	v_mfma_f32_16x16x32_bf16 v[100:103], v[134:137], v[212:215], v[100:103]
	v_mfma_f32_16x16x32_bf16 v[96:99], v[142:145], v[212:215], v[96:99]
	v_mfma_f32_16x16x32_bf16 v[126:129], v[138:141], v[192:195], v[126:129]
	v_mfma_f32_16x16x32_bf16 v[122:125], v[148:151], v[192:195], v[122:125]
	v_mfma_f32_16x16x32_bf16 v[118:121], v[138:141], v[200:203], v[118:121]
	v_mfma_f32_16x16x32_bf16 v[114:117], v[148:151], v[200:203], v[114:117]
	v_mfma_f32_16x16x32_bf16 v[108:111], v[134:137], v[204:207], v[108:111]
	v_mfma_f32_16x16x32_bf16 v[104:107], v[142:145], v[204:207], v[104:107]
	v_mfma_f32_16x16x32_bf16 v[100:103], v[138:141], v[216:219], v[100:103]
	v_mfma_f32_16x16x32_bf16 v[96:99], v[148:151], v[216:219], v[96:99]
	v_mfma_f32_16x16x32_bf16 v[130:133], v[138:141], v[208:211], v[108:111]
	v_mfma_f32_16x16x32_bf16 v[220:223], v[148:151], v[208:211], v[104:107]
	v_mfma_f32_16x16x32_bf16 v[84:87], v[152:155], v[196:199], v[84:87]
	v_mfma_f32_16x16x32_bf16 v[80:83], v[168:171], v[196:199], v[80:83]
	v_mfma_f32_16x16x32_bf16 v[68:71], v[152:155], v[204:207], v[68:71]
	v_mfma_f32_16x16x32_bf16 v[60:63], v[168:171], v[204:207], v[60:63]
	v_mfma_f32_16x16x32_bf16 v[56:59], v[152:155], v[212:215], v[56:59]
	v_mfma_f32_16x16x32_bf16 v[52:55], v[168:171], v[212:215], v[52:55]
	v_mfma_f32_16x16x32_bf16 v[92:95], v[152:155], v[176:179], v[92:95]
	v_mfma_f32_16x16x32_bf16 v[88:91], v[168:171], v[176:179], v[88:91]
	v_mfma_f32_16x16x32_bf16 v[84:87], v[164:167], v[200:203], v[84:87]
	v_mfma_f32_16x16x32_bf16 v[80:83], v[172:175], v[200:203], v[80:83]
	v_mfma_f32_16x16x32_bf16 v[68:71], v[164:167], v[208:211], v[68:71]
	v_mfma_f32_16x16x32_bf16 v[60:63], v[172:175], v[208:211], v[60:63]
	v_mfma_f32_16x16x32_bf16 v[56:59], v[164:167], v[216:219], v[56:59]
	v_mfma_f32_16x16x32_bf16 v[52:55], v[172:175], v[216:219], v[52:55]
	v_mfma_f32_16x16x32_bf16 v[224:227], v[164:167], v[192:195], v[92:95]
	v_mfma_f32_16x16x32_bf16 v[176:179], v[172:175], v[192:195], v[88:91]
	s_barrier
	s_nop 0
	ds_read_b128 v[88:91], v112 offset:16384
	ds_read_b128 v[92:95], v112 offset:17408
	ds_read_b128 v[104:107], v112 offset:18432
	ds_read_b128 v[108:111], v112 offset:19456
	ds_read_b128 v[192:195], v112 offset:20480
	ds_read_b128 v[196:199], v112 offset:21504
	ds_read_b128 v[200:203], v112 offset:22528
	ds_read_b128 v[204:207], v112 offset:23552
	s_waitcnt vmcnt(2)
	s_waitcnt lgkmcnt(0)
	s_barrier
	s_waitcnt lgkmcnt(0)
	v_mfma_f32_16x16x32_bf16 v[48:51], v[134:137], v[88:91], v[48:51]
	v_mfma_f32_16x16x32_bf16 v[44:47], v[142:145], v[88:91], v[44:47]
	v_mfma_f32_16x16x32_bf16 v[40:43], v[134:137], v[104:107], v[40:43]
	v_mfma_f32_16x16x32_bf16 v[36:39], v[142:145], v[104:107], v[36:39]
	v_mfma_f32_16x16x32_bf16 v[32:35], v[134:137], v[192:195], v[32:35]
	v_mfma_f32_16x16x32_bf16 v[20:23], v[142:145], v[200:203], v[20:23]
	v_mfma_f32_16x16x32_bf16 v[48:51], v[138:141], v[92:95], v[48:51]
	v_mfma_f32_16x16x32_bf16 v[44:47], v[148:151], v[92:95], v[44:47]
	v_mfma_f32_16x16x32_bf16 v[40:43], v[138:141], v[108:111], v[40:43]
	v_mfma_f32_16x16x32_bf16 v[36:39], v[148:151], v[108:111], v[36:39]
	v_mfma_f32_16x16x32_bf16 v[32:35], v[138:141], v[196:199], v[32:35]
	v_mfma_f32_16x16x32_bf16 v[28:31], v[142:145], v[192:195], v[28:31]
	v_mfma_f32_16x16x32_bf16 v[24:27], v[134:137], v[200:203], v[24:27]
	v_mfma_f32_16x16x32_bf16 v[20:23], v[148:151], v[204:207], v[20:23]
	v_mfma_f32_16x16x32_bf16 v[208:211], v[148:151], v[196:199], v[28:31]
	v_mfma_f32_16x16x32_bf16 v[134:137], v[138:141], v[204:207], v[24:27]
	v_mfma_f32_16x16x32_bf16 v[8:11], v[152:155], v[104:107], v[8:11]
	v_mfma_f32_16x16x32_bf16 v[142:145], v[164:167], v[108:111], v[8:11]
	v_mfma_f32_16x16x32_bf16 v[8:11], v[168:171], v[192:195], v[64:67]
	v_mfma_f32_16x16x32_bf16 v[16:19], v[152:155], v[88:91], v[16:19]
	v_mfma_f32_16x16x32_bf16 v[4:7], v[168:171], v[104:107], v[4:7]
	v_mfma_f32_16x16x32_bf16 v[0:3], v[152:155], v[192:195], v[0:3]
	v_mfma_f32_16x16x32_bf16 v[148:151], v[172:175], v[196:199], v[8:11]
	v_mfma_f32_16x16x32_bf16 v[8:11], v[152:155], v[200:203], v[72:75]
	v_mfma_f32_16x16x32_bf16 v[16:19], v[164:167], v[92:95], v[16:19]
	v_mfma_f32_16x16x32_bf16 v[12:15], v[168:171], v[88:91], v[12:15]
	v_mfma_f32_16x16x32_bf16 v[4:7], v[172:175], v[108:111], v[4:7]
	v_mfma_f32_16x16x32_bf16 v[0:3], v[164:167], v[196:199], v[0:3]
	v_mfma_f32_16x16x32_bf16 v[152:155], v[164:167], v[204:207], v[8:11]
	v_mfma_f32_16x16x32_bf16 v[8:11], v[168:171], v[200:203], v[76:79]
	v_mfma_f32_16x16x32_bf16 v[138:141], v[172:175], v[92:95], v[12:15]
	v_mfma_f32_16x16x32_bf16 v[164:167], v[172:175], v[204:207], v[8:11]
	s_barrier
	v_add_u32_e32 v24, 0x18000, v228
	s_nop 2
	ds_read_b128 v[8:11], v24
	ds_read_b128 v[12:15], v24 offset:1024
	ds_read_b128 v[168:171], v24 offset:2048
	ds_read_b128 v[172:175], v24 offset:3072
	v_add_u32_e32 v24, 0x1c000, v228
	ds_read_b128 v[192:195], v24
	ds_read_b128 v[196:199], v24 offset:1024
	ds_read_b128 v[200:203], v24 offset:2048
	ds_read_b128 v[204:207], v24 offset:3072
	ds_read_b128 v[24:27], v112 offset:32768
	ds_read_b128 v[28:31], v112 offset:33792
	ds_read_b128 v[64:67], v112 offset:34816
	ds_read_b128 v[212:215], v112 offset:35840
	ds_read_b128 v[216:219], v112 offset:36864
	ds_read_b128 v[228:231], v112 offset:37888
	ds_read_b128 v[232:235], v112 offset:38912
	ds_read_b128 v[236:239], v112 offset:39936
	s_waitcnt vmcnt(0)
	s_waitcnt lgkmcnt(0)
	s_barrier
	s_waitcnt lgkmcnt(0)
	v_mfma_f32_16x16x32_bf16 v[72:75], v[8:11], v[24:27], v[126:129]
	v_mfma_f32_16x16x32_bf16 v[126:129], v[12:15], v[28:31], v[72:75]
	v_mfma_f32_16x16x32_bf16 v[72:75], v[168:171], v[24:27], v[122:125]
	v_mfma_f32_16x16x32_bf16 v[122:125], v[172:175], v[28:31], v[72:75]
	v_mfma_f32_16x16x32_bf16 v[72:75], v[8:11], v[64:67], v[118:121]
	v_mfma_f32_16x16x32_bf16 v[108:111], v[12:15], v[212:215], v[72:75]
	v_mfma_f32_16x16x32_bf16 v[72:75], v[168:171], v[64:67], v[114:117]
	v_mfma_f32_16x16x32_bf16 v[104:107], v[172:175], v[212:215], v[72:75]
	v_mfma_f32_16x16x32_bf16 v[72:75], v[8:11], v[216:219], v[130:133]
	v_mfma_f32_16x16x32_bf16 v[92:95], v[12:15], v[228:231], v[72:75]
	v_mfma_f32_16x16x32_bf16 v[72:75], v[168:171], v[216:219], v[220:223]
	v_mfma_f32_16x16x32_bf16 v[88:91], v[172:175], v[228:231], v[72:75]
	v_mfma_f32_16x16x32_bf16 v[72:75], v[8:11], v[232:235], v[100:103]
	v_mfma_f32_16x16x32_bf16 v[76:79], v[12:15], v[236:239], v[72:75]
	v_mfma_f32_16x16x32_bf16 v[72:75], v[168:171], v[232:235], v[96:99]
	v_mfma_f32_16x16x32_bf16 v[72:75], v[172:175], v[236:239], v[72:75]
	v_mfma_f32_16x16x32_bf16 v[96:99], v[192:195], v[24:27], v[224:227]
	v_mfma_f32_16x16x32_bf16 v[24:27], v[200:203], v[24:27], v[176:179]
	v_mfma_f32_16x16x32_bf16 v[114:117], v[204:207], v[28:31], v[24:27]
	v_mfma_f32_16x16x32_bf16 v[24:27], v[192:195], v[64:67], v[84:87]
	v_mfma_f32_16x16x32_bf16 v[100:103], v[196:199], v[212:215], v[24:27]
	v_mfma_f32_16x16x32_bf16 v[24:27], v[200:203], v[64:67], v[80:83]
	v_mfma_f32_16x16x32_bf16 v[118:121], v[196:199], v[28:31], v[96:99]
	v_mfma_f32_16x16x32_bf16 v[96:99], v[204:207], v[212:215], v[24:27]
	v_mfma_f32_16x16x32_bf16 v[24:27], v[192:195], v[216:219], v[68:71]
	v_mfma_f32_16x16x32_bf16 v[84:87], v[196:199], v[228:231], v[24:27]
	v_mfma_f32_16x16x32_bf16 v[24:27], v[200:203], v[216:219], v[60:63]
	v_mfma_f32_16x16x32_bf16 v[80:83], v[204:207], v[228:231], v[24:27]
	v_mfma_f32_16x16x32_bf16 v[24:27], v[192:195], v[232:235], v[56:59]
	v_mfma_f32_16x16x32_bf16 v[68:71], v[196:199], v[236:239], v[24:27]
	v_mfma_f32_16x16x32_bf16 v[24:27], v[200:203], v[232:235], v[52:55]
	v_mfma_f32_16x16x32_bf16 v[64:67], v[204:207], v[236:239], v[24:27]
	s_barrier
	ds_read_b128 v[130:133], v112 offset:49152
	ds_read_b128 v[176:179], v112 offset:50176
	ds_read_b128 v[212:215], v112 offset:51200
	ds_read_b128 v[216:219], v112 offset:52224
	ds_read_b128 v[220:223], v112 offset:53248
	ds_read_b128 v[224:227], v112 offset:54272
	ds_read_b128 v[228:231], v112 offset:55296
	ds_read_b128 v[232:235], v112 offset:56320
	s_waitcnt lgkmcnt(0)
	s_barrier
	s_waitcnt lgkmcnt(0)
	v_mfma_f32_16x16x32_bf16 v[24:27], v[8:11], v[130:133], v[48:51]
	v_mfma_f32_16x16x32_bf16 v[60:63], v[12:15], v[176:179], v[24:27]
	v_mfma_f32_16x16x32_bf16 v[24:27], v[168:171], v[130:133], v[44:47]
	v_mfma_f32_16x16x32_bf16 v[56:59], v[172:175], v[176:179], v[24:27]
	v_mfma_f32_16x16x32_bf16 v[24:27], v[8:11], v[212:215], v[40:43]
	v_mfma_f32_16x16x32_bf16 v[44:47], v[12:15], v[216:219], v[24:27]
	v_mfma_f32_16x16x32_bf16 v[24:27], v[168:171], v[212:215], v[36:39]
	v_mfma_f32_16x16x32_bf16 v[40:43], v[172:175], v[216:219], v[24:27]
	v_mfma_f32_16x16x32_bf16 v[24:27], v[8:11], v[220:223], v[32:35]
	v_mfma_f32_16x16x32_bf16 v[8:11], v[8:11], v[228:231], v[134:137]
	v_mfma_f32_16x16x32_bf16 v[28:31], v[12:15], v[224:227], v[24:27]
	v_mfma_f32_16x16x32_bf16 v[24:27], v[168:171], v[220:223], v[208:211]
	v_mfma_f32_16x16x32_bf16 v[12:15], v[12:15], v[232:235], v[8:11]
	v_mfma_f32_16x16x32_bf16 v[8:11], v[168:171], v[228:231], v[20:23]
	v_mfma_f32_16x16x32_bf16 v[24:27], v[172:175], v[224:227], v[24:27]
	v_mfma_f32_16x16x32_bf16 v[8:11], v[172:175], v[232:235], v[8:11]
	v_mfma_f32_16x16x32_bf16 v[16:19], v[192:195], v[130:133], v[16:19]
	v_mfma_f32_16x16x32_bf16 v[52:55], v[196:199], v[176:179], v[16:19]
	v_mfma_f32_16x16x32_bf16 v[16:19], v[200:203], v[130:133], v[138:141]
	v_mfma_f32_16x16x32_bf16 v[0:3], v[192:195], v[220:223], v[0:3]
	v_mfma_f32_16x16x32_bf16 v[48:51], v[204:207], v[176:179], v[16:19]
	v_mfma_f32_16x16x32_bf16 v[16:19], v[192:195], v[212:215], v[142:145]
	v_mfma_f32_16x16x32_bf16 v[20:23], v[196:199], v[224:227], v[0:3]
	v_mfma_f32_16x16x32_bf16 v[0:3], v[200:203], v[220:223], v[148:151]
	v_mfma_f32_16x16x32_bf16 v[36:39], v[196:199], v[216:219], v[16:19]
	v_mfma_f32_16x16x32_bf16 v[4:7], v[200:203], v[212:215], v[4:7]
	v_mfma_f32_16x16x32_bf16 v[16:19], v[204:207], v[224:227], v[0:3]
	v_mfma_f32_16x16x32_bf16 v[0:3], v[192:195], v[228:231], v[152:155]
	v_mfma_f32_16x16x32_bf16 v[32:35], v[204:207], v[216:219], v[4:7]
	v_mfma_f32_16x16x32_bf16 v[4:7], v[196:199], v[232:235], v[0:3]
	v_mfma_f32_16x16x32_bf16 v[0:3], v[200:203], v[228:231], v[164:167]
	v_mfma_f32_16x16x32_bf16 v[0:3], v[204:207], v[232:235], v[0:3]
	s_barrier
	s_waitcnt vmcnt(0)
	s_cmpk_lt_u32 s47, 0x100
	s_cbranch_scc0 .LBB0_1827
	s_barrier

.LBB0_2065:
	s_setprio 0
	s_getreg_b32 s2, hwreg(HW_REG_XCC_ID, 0, 4)
	s_waitcnt vmcnt(0)
	s_waitcnt vmcnt(0)
	s_barrier
	s_mov_b64 s[0:1], exec
	v_readlane_b32 s4, v253, 14
	v_readlane_b32 s5, v253, 15
	s_and_b64 s[4:5], s[0:1], s[4:5]
	s_mov_b64 exec, s[4:5]
	s_cbranch_execnz .LBB0_2066
	s_getpc_b64 s[98:99]
